# stack_e + setprio 1/0 moved across the barriers bounding each K-loop MFMA segment
# speedup vs baseline: 1.0085x; 1.0085x over previous
;     __host__ __device__ bool next(int i, Unit& u) const { const int t = i / 3, b = i - 3 * t; Unit v; if (!StaticOrder::next(t, v)) return false; u.pm = v.pm; u.pn = 8 * b + v.pn; return true; }
; #define PG8_STAGE(bufoff, gbase, voff) do { const int so_ = (int)(unsigned)((const char*)(gbase) - base_##voff); _Pragma("unroll") for (int _i = 0; _i < 2; ++_i) \
;         __builtin_amdgcn_raw_ptr_buffer_load_lds(rs_##voff, (PG8_LAS unsigned*)(lds + (bufoff) + ldsw + _i * 8192), 16, (int)(voff)[_i], so_, 0, 0); } while (0)
; #define PG8_LDA(dst, b, h) do { _Pragma("unroll") for (int m = 0; m < 4; ++m) _Pragma("unroll") for (int k = 0; k < 2; ++k) dst[m][k] = *(const PG8_LAS bf16x8*)(lds + PG8_SA(b, h) + aoff + m * 2048 + k * 1024); } while (0)
; #define PG8_WAIT_V(n) asm volatile("s_waitcnt vmcnt(" #n ")" ::: "memory")
; #define PG8_WAIT_L(n) asm volatile("s_waitcnt lgkmcnt(" #n ")" ::: "memory")
; #define PG8_BAR __builtin_amdgcn_s_barrier()
; template <class Epi, class Sched, bool ALIGN_EPI = false, bool SP2 = false>
; __device__ __forceinline__ void gemm_phase(PG8_LAS unsigned char* lds, const Gemm g, const Sched& S, const Epi& E, int tid_in) {
;     ...
;         const bool has_next = S.next(ui + 1, nxt);
;         const char* nA = has_next ? (const char*)g.A + (size_t)nxt.pm * tstepA + (g.grp ? (size_t)(nxt.pn / g.grp) * g.agrp : (size_t)0) : cA; const char* nB = has_next ? (const char*)g.Bt + (size_t)nxt.pn * tstepB : cB;
;         for (int t = 0; t < nt; t += 2) {
;             const bool last = (t == nt - 2);
;             const char* a1 = cA + (size_t)(t + 1) * kstep;
;             const char* a2 = last ? nA : cA + (size_t)(t + 2) * kstep; const char* b2 = last ? nB : cB + (size_t)(t + 2) * kstep;
;             const char* a3 = a2 + kstep; const char* b3 = b2 + kstep;
;             if (last && has_next) S.a_ready(nxt);
;             if constexpr (SP2) {
;             PG8_LDB(B0, 0, 0); PG8_LDB(B1, 0, 1); PG8_SCHED; PG8_LDA(At, 0, 0); PG8_STAGE(PG8_SA(1, 1), a1 + hstepA, voffA);
;             PG8_WAIT_V(8); PG8_WAIT_L(0); PG8_BAR; PG8_MMA(0, 0, At, B0); PG8_MMA(0, 1, At, B1); PG8_BAR; PG8_SCHED;
;             PG8_LDA(At, 0, 1); PG8_STAGE(PG8_SB(0, 0), b2, voffB); PG8_STAGE(PG8_SB(0, 1), b2 + hstepB, voffB); PG8_STAGE(PG8_SA(0, 0), a2, voffA);
;             PG8_WAIT_V(8); PG8_WAIT_L(0); PG8_BAR; PG8_MMA(1, 0, At, B0); PG8_MMA(1, 1, At, B1); PG8_BAR; PG8_SCHED;
.LBB0_311:
	s_ashr_i32 s23, s22, 31
	s_lshl_b64 s[10:11], s[22:23], 20
	s_add_u32 s24, s4, s10
	s_addc_u32 s25, s26, s11
	s_and_b64 s[10:11], s[34:35], exec
	s_cselect_b32 s19, s24, s12
	s_ashr_i32 s15, s14, 31
	s_lshl_b64 s[10:11], s[14:15], 20
	s_add_u32 s10, s40, s10
	s_addc_u32 s11, s60, s11
	s_and_b64 s[20:21], s[34:35], exec
	s_cselect_b32 s15, s10, s16
	s_add_u32 s20, s16, 0x100
	v_mov_b32_e32 v2, 0
	s_addc_u32 s21, s17, 0
	s_mov_b32 s23, -2
	v_add_u32_e32 v0, 0x10000, v237
	ds_read_b128 v[130:133], v0
	ds_read_b128 v[134:137], v0 offset:1024
	ds_read_b128 v[138:141], v0 offset:2048
	ds_read_b128 v[142:145], v0 offset:3072
	v_add_u32_e32 v0, 0x14000, v237
	ds_read_b128 v[146:149], v0
	ds_read_b128 v[150:153], v0 offset:1024
	ds_read_b128 v[154:157], v0 offset:2048
	ds_read_b128 v[158:161], v0 offset:3072
	s_add_u32 s16, s12, 0x100
	s_addc_u32 s17, s13, 0
	s_sub_i32 s12, s12, s4
	s_add_i32 s12, s12, 0x80080
	s_sub_i32 s36, s12, 0x80000
	s_cmp_eq_u32 s23, 28
	s_cselect_b32 s13, s19, s16
	s_mov_b32 m0, s69
	ds_read_b128 v[162:165], v238
	ds_read_b128 v[166:169], v238 offset:1024
	ds_read_b128 v[170:173], v238 offset:2048
	ds_read_b128 v[174:177], v238 offset:3072
	ds_read_b128 v[178:181], v238 offset:4096
	ds_read_b128 v[182:185], v238 offset:5120
	ds_read_b128 v[186:189], v238 offset:6144
	ds_read_b128 v[190:193], v238 offset:7168
	s_mov_b32 m0, s78
	s_nop 0
	buffer_load_dwordx4 v211, s[4:7], s36 offen lds
	s_mov_b32 m0, s69
	s_nop 0
	buffer_load_dwordx4 v195, s[4:7], s12 offen lds
	s_mov_b32 m0, s67
	s_nop 0
	buffer_load_dwordx4 v211, s[4:7], s12 offen lds
	s_waitcnt vmcnt(8)
	s_waitcnt lgkmcnt(0)
	s_setprio 1
	s_barrier
	v_mfma_f32_16x16x32_bf16 v[126:129], v[130:133], v[162:165], 0
	v_mfma_f32_16x16x32_bf16 v[122:125], v[138:141], v[162:165], 0
	v_mfma_f32_16x16x32_bf16 v[106:109], v[138:141], v[170:173], 0
	v_mfma_f32_16x16x32_bf16 v[110:113], v[130:133], v[170:173], 0
	v_mfma_f32_16x16x32_bf16 v[94:97], v[130:133], v[178:181], 0
	v_mfma_f32_16x16x32_bf16 v[90:93], v[138:141], v[178:181], 0
	v_mfma_f32_16x16x32_bf16 v[74:77], v[138:141], v[186:189], 0
	v_mfma_f32_16x16x32_bf16 v[78:81], v[130:133], v[186:189], 0
	v_mfma_f32_16x16x32_bf16 v[126:129], v[134:137], v[166:169], v[126:129]
	v_mfma_f32_16x16x32_bf16 v[122:125], v[142:145], v[166:169], v[122:125]
	v_mfma_f32_16x16x32_bf16 v[106:109], v[142:145], v[174:177], v[106:109]
	v_mfma_f32_16x16x32_bf16 v[110:113], v[134:137], v[174:177], v[110:113]
	v_mfma_f32_16x16x32_bf16 v[94:97], v[134:137], v[182:185], v[94:97]
	v_mfma_f32_16x16x32_bf16 v[90:93], v[142:145], v[182:185], v[90:93]
	v_mfma_f32_16x16x32_bf16 v[74:77], v[142:145], v[190:193], v[74:77]
	v_mfma_f32_16x16x32_bf16 v[78:81], v[134:137], v[190:193], v[78:81]
	v_mfma_f32_16x16x32_bf16 v[118:121], v[146:149], v[162:165], 0
	v_mfma_f32_16x16x32_bf16 v[114:117], v[154:157], v[162:165], 0
	v_mfma_f32_16x16x32_bf16 v[98:101], v[154:157], v[170:173], 0
	v_mfma_f32_16x16x32_bf16 v[102:105], v[146:149], v[170:173], 0
	v_mfma_f32_16x16x32_bf16 v[86:89], v[146:149], v[178:181], 0
	v_mfma_f32_16x16x32_bf16 v[82:85], v[154:157], v[178:181], 0
	v_mfma_f32_16x16x32_bf16 v[66:69], v[154:157], v[186:189], 0
	v_mfma_f32_16x16x32_bf16 v[70:73], v[146:149], v[186:189], 0
	v_mfma_f32_16x16x32_bf16 v[118:121], v[150:153], v[166:169], v[118:121]
	v_mfma_f32_16x16x32_bf16 v[114:117], v[158:161], v[166:169], v[114:117]
	v_mfma_f32_16x16x32_bf16 v[98:101], v[158:161], v[174:177], v[98:101]
	v_mfma_f32_16x16x32_bf16 v[102:105], v[150:153], v[174:177], v[102:105]
	v_mfma_f32_16x16x32_bf16 v[86:89], v[150:153], v[182:185], v[86:89]
	v_mfma_f32_16x16x32_bf16 v[82:85], v[158:161], v[182:185], v[82:85]
	v_mfma_f32_16x16x32_bf16 v[66:69], v[158:161], v[190:193], v[66:69]
	v_mfma_f32_16x16x32_bf16 v[70:73], v[150:153], v[190:193], v[70:73]
	s_barrier
	s_setprio 0
	s_cselect_b32 s12, s15, s20
	s_mov_b32 m0, s61
	s_mov_b32 s42, s6
	s_mov_b32 s43, s7
	s_sub_i32 s12, s12, s40
	ds_read_b128 v[162:165], v238 offset:16384
	ds_read_b128 v[166:169], v238 offset:17408
	ds_read_b128 v[170:173], v238 offset:18432
	ds_read_b128 v[174:177], v238 offset:19456
	ds_read_b128 v[178:181], v238 offset:20480
	ds_read_b128 v[182:185], v238 offset:21504
	ds_read_b128 v[186:189], v238 offset:22528
	ds_read_b128 v[190:193], v238 offset:23552
	buffer_load_dwordx4 v207, s[40:43], s12 offen lds
	s_mov_b32 m0, s62
	s_add_i32 s36, s12, 0x80000
	buffer_load_dwordx4 v224, s[40:43], s12 offen lds
	s_mov_b32 m0, s63
	s_sub_i32 s13, s13, s4
	buffer_load_dwordx4 v207, s[40:43], s36 offen lds
	s_mov_b32 m0, s71
	s_nop 0
	buffer_load_dwordx4 v224, s[40:43], s36 offen lds
	s_mov_b32 m0, s53
	s_nop 0
	buffer_load_dwordx4 v195, s[4:7], s13 offen lds
	s_waitcnt vmcnt(7)
	s_waitcnt lgkmcnt(0)
	s_setprio 1
	s_barrier
; #define PG8_STAGE(bufoff, gbase, voff) do { const int so_ = (int)(unsigned)((const char*)(gbase) - base_##voff); _Pragma("unroll") for (int _i = 0; _i < 2; ++_i) \
;         __builtin_amdgcn_raw_ptr_buffer_load_lds(rs_##voff, (PG8_LAS unsigned*)(lds + (bufoff) + ldsw + _i * 8192), 16, (int)(voff)[_i], so_, 0, 0); } while (0)
; #define PG8_LDA(dst, b, h) do { _Pragma("unroll") for (int m = 0; m < 4; ++m) _Pragma("unroll") for (int k = 0; k < 2; ++k) dst[m][k] = *(const PG8_LAS bf16x8*)(lds + PG8_SA(b, h) + aoff + m * 2048 + k * 1024); } while (0)
; #define PG8_LDB(dst, b, h) do { _Pragma("unroll") for (int n = 0; n < 2; ++n) _Pragma("unroll") for (int k = 0; k < 2; ++k) dst[n][k] = *(const PG8_LAS bf16x8*)(lds + PG8_SB(b, h) + boff + n * 2048 + k * 1024); } while (0)
; #define PG8_MMA(ai, bj, At, Bt) do { __builtin_amdgcn_s_setprio(1); _Pragma("unroll") for (int m = 0; m < 4; ++m) _Pragma("unroll") for (int n = 0; n < 2; ++n) _Pragma("unroll") for (int k = 0; k < 2; ++k) \
;         acc[ai][bj][m][n] = __builtin_amdgcn_mfma_f32_16x16x32_bf16(Bt[n][k], At[m][k], acc[ai][bj][m][n], 0, 0, 0); __builtin_amdgcn_s_setprio(0); } while (0)
; #define PG8_WAIT_V(n) asm volatile("s_waitcnt vmcnt(" #n ")" ::: "memory")
; #define PG8_WAIT_L(n) asm volatile("s_waitcnt lgkmcnt(" #n ")" ::: "memory")
; #define PG8_BAR __builtin_amdgcn_s_barrier()
; #define PG8_SCHED __builtin_amdgcn_sched_barrier(0)
; template <class Epi, class Sched, bool ALIGN_EPI = false, bool SP2 = false>
; __device__ __forceinline__ void gemm_phase(PG8_LAS unsigned char* lds, const Gemm g, const Sched& S, const Epi& E, int tid_in) {
;     ...
;             PG8_WAIT_V(8); PG8_WAIT_L(0); PG8_BAR; PG8_MMA(1, 0, At, B0); PG8_MMA(1, 1, At, B1); PG8_BAR; PG8_SCHED;
;             PG8_LDB(B0, 1, 0); PG8_LDB(B1, 1, 1); PG8_SCHED; PG8_LDA(At, 1, 0); PG8_STAGE(PG8_SA(0, 1), a2 + hstepA, voffA);
;             PG8_WAIT_V(8); PG8_WAIT_L(0); PG8_BAR; PG8_MMA(0, 0, At, B0); PG8_MMA(0, 1, At, B1); PG8_BAR; PG8_SCHED;
	v_mfma_f32_16x16x32_bf16 v[62:65], v[130:133], v[162:165], 0
	v_mfma_f32_16x16x32_bf16 v[58:61], v[138:141], v[162:165], 0
	v_mfma_f32_16x16x32_bf16 v[42:45], v[138:141], v[170:173], 0
	v_mfma_f32_16x16x32_bf16 v[46:49], v[130:133], v[170:173], 0
	v_mfma_f32_16x16x32_bf16 v[30:33], v[130:133], v[178:181], 0
	v_mfma_f32_16x16x32_bf16 v[26:29], v[138:141], v[178:181], 0
	v_mfma_f32_16x16x32_bf16 v[10:13], v[138:141], v[186:189], 0
	v_mfma_f32_16x16x32_bf16 v[14:17], v[130:133], v[186:189], 0
	v_mfma_f32_16x16x32_bf16 v[62:65], v[134:137], v[166:169], v[62:65]
	v_mfma_f32_16x16x32_bf16 v[58:61], v[142:145], v[166:169], v[58:61]
	v_mfma_f32_16x16x32_bf16 v[42:45], v[142:145], v[174:177], v[42:45]
	v_mfma_f32_16x16x32_bf16 v[46:49], v[134:137], v[174:177], v[46:49]
	v_mfma_f32_16x16x32_bf16 v[30:33], v[134:137], v[182:185], v[30:33]
	v_mfma_f32_16x16x32_bf16 v[26:29], v[142:145], v[182:185], v[26:29]
	v_mfma_f32_16x16x32_bf16 v[10:13], v[142:145], v[190:193], v[10:13]
	v_mfma_f32_16x16x32_bf16 v[14:17], v[134:137], v[190:193], v[14:17]
	v_mfma_f32_16x16x32_bf16 v[54:57], v[146:149], v[162:165], 0
	v_mfma_f32_16x16x32_bf16 v[50:53], v[154:157], v[162:165], 0
	v_mfma_f32_16x16x32_bf16 v[34:37], v[154:157], v[170:173], 0
	v_mfma_f32_16x16x32_bf16 v[38:41], v[146:149], v[170:173], 0
	v_mfma_f32_16x16x32_bf16 v[22:25], v[146:149], v[178:181], 0
	v_mfma_f32_16x16x32_bf16 v[18:21], v[154:157], v[178:181], 0
	v_mfma_f32_16x16x32_bf16 v[2:5], v[154:157], v[186:189], 0
	v_mfma_f32_16x16x32_bf16 v[6:9], v[146:149], v[186:189], 0
	v_mfma_f32_16x16x32_bf16 v[54:57], v[150:153], v[166:169], v[54:57]
	v_mfma_f32_16x16x32_bf16 v[50:53], v[158:161], v[166:169], v[50:53]
	v_mfma_f32_16x16x32_bf16 v[34:37], v[158:161], v[174:177], v[34:37]
	v_mfma_f32_16x16x32_bf16 v[38:41], v[150:153], v[174:177], v[38:41]
	v_mfma_f32_16x16x32_bf16 v[22:25], v[150:153], v[182:185], v[22:25]
	v_mfma_f32_16x16x32_bf16 v[18:21], v[158:161], v[182:185], v[18:21]
	v_mfma_f32_16x16x32_bf16 v[2:5], v[158:161], v[190:193], v[2:5]
	v_mfma_f32_16x16x32_bf16 v[6:9], v[150:153], v[190:193], v[6:9]
	s_barrier
	s_setprio 0
	v_add_u32_e32 v0, 0x18000, v237
	ds_read_b128 v[130:133], v0
	ds_read_b128 v[134:137], v0 offset:1024
	ds_read_b128 v[138:141], v0 offset:2048
	ds_read_b128 v[142:145], v0 offset:3072
	v_add_u32_e32 v0, 0x1c000, v237
	ds_read_b128 v[146:149], v0
	ds_read_b128 v[150:153], v0 offset:1024
	ds_read_b128 v[154:157], v0 offset:2048
	ds_read_b128 v[158:161], v0 offset:3072
	s_add_i32 s36, s13, 0x80000
	s_mov_b32 m0, s73
	ds_read_b128 v[162:165], v238 offset:32768
	ds_read_b128 v[166:169], v238 offset:33792
	ds_read_b128 v[170:173], v238 offset:34816
	ds_read_b128 v[174:177], v238 offset:35840
	ds_read_b128 v[178:181], v238 offset:36864
	ds_read_b128 v[182:185], v238 offset:37888
	ds_read_b128 v[186:189], v238 offset:38912
	ds_read_b128 v[190:193], v238 offset:39936
	s_mov_b32 m0, s72
	s_nop 0
	buffer_load_dwordx4 v211, s[4:7], s13 offen lds
	s_mov_b32 m0, s73
	s_nop 0
	buffer_load_dwordx4 v195, s[4:7], s36 offen lds
	s_mov_b32 m0, s74
	s_nop 0
	buffer_load_dwordx4 v211, s[4:7], s36 offen lds
	s_waitcnt vmcnt(8)
	s_waitcnt lgkmcnt(0)
	s_setprio 1
	s_barrier
	v_mfma_f32_16x16x32_bf16 v[126:129], v[130:133], v[162:165], v[126:129]
	v_mfma_f32_16x16x32_bf16 v[122:125], v[138:141], v[162:165], v[122:125]
	v_mfma_f32_16x16x32_bf16 v[106:109], v[138:141], v[170:173], v[106:109]
	v_mfma_f32_16x16x32_bf16 v[110:113], v[130:133], v[170:173], v[110:113]
	v_mfma_f32_16x16x32_bf16 v[94:97], v[130:133], v[178:181], v[94:97]
	v_mfma_f32_16x16x32_bf16 v[90:93], v[138:141], v[178:181], v[90:93]
	v_mfma_f32_16x16x32_bf16 v[74:77], v[138:141], v[186:189], v[74:77]
	v_mfma_f32_16x16x32_bf16 v[78:81], v[130:133], v[186:189], v[78:81]
	v_mfma_f32_16x16x32_bf16 v[126:129], v[134:137], v[166:169], v[126:129]
	v_mfma_f32_16x16x32_bf16 v[122:125], v[142:145], v[166:169], v[122:125]
	v_mfma_f32_16x16x32_bf16 v[106:109], v[142:145], v[174:177], v[106:109]
	v_mfma_f32_16x16x32_bf16 v[110:113], v[134:137], v[174:177], v[110:113]
	v_mfma_f32_16x16x32_bf16 v[94:97], v[134:137], v[182:185], v[94:97]
	v_mfma_f32_16x16x32_bf16 v[90:93], v[142:145], v[182:185], v[90:93]
	v_mfma_f32_16x16x32_bf16 v[74:77], v[142:145], v[190:193], v[74:77]
	v_mfma_f32_16x16x32_bf16 v[78:81], v[134:137], v[190:193], v[78:81]
	v_mfma_f32_16x16x32_bf16 v[118:121], v[146:149], v[162:165], v[118:121]
	v_mfma_f32_16x16x32_bf16 v[114:117], v[154:157], v[162:165], v[114:117]
	v_mfma_f32_16x16x32_bf16 v[98:101], v[154:157], v[170:173], v[98:101]
	v_mfma_f32_16x16x32_bf16 v[102:105], v[146:149], v[170:173], v[102:105]
	v_mfma_f32_16x16x32_bf16 v[86:89], v[146:149], v[178:181], v[86:89]
	v_mfma_f32_16x16x32_bf16 v[82:85], v[154:157], v[178:181], v[82:85]
	v_mfma_f32_16x16x32_bf16 v[66:69], v[154:157], v[186:189], v[66:69]
	v_mfma_f32_16x16x32_bf16 v[70:73], v[146:149], v[186:189], v[70:73]
	v_mfma_f32_16x16x32_bf16 v[118:121], v[150:153], v[166:169], v[118:121]
	v_mfma_f32_16x16x32_bf16 v[114:117], v[158:161], v[166:169], v[114:117]
	v_mfma_f32_16x16x32_bf16 v[98:101], v[158:161], v[174:177], v[98:101]
	v_mfma_f32_16x16x32_bf16 v[102:105], v[150:153], v[174:177], v[102:105]
	v_mfma_f32_16x16x32_bf16 v[86:89], v[150:153], v[182:185], v[86:89]
	v_mfma_f32_16x16x32_bf16 v[82:85], v[158:161], v[182:185], v[82:85]
	v_mfma_f32_16x16x32_bf16 v[66:69], v[158:161], v[190:193], v[66:69]
	v_mfma_f32_16x16x32_bf16 v[70:73], v[150:153], v[190:193], v[70:73]
	s_barrier
; #define PG8_STAGE(bufoff, gbase, voff) do { const int so_ = (int)(unsigned)((const char*)(gbase) - base_##voff); _Pragma("unroll") for (int _i = 0; _i < 2; ++_i) \
;         __builtin_amdgcn_raw_ptr_buffer_load_lds(rs_##voff, (PG8_LAS unsigned*)(lds + (bufoff) + ldsw + _i * 8192), 16, (int)(voff)[_i], so_, 0, 0); } while (0)
; #define PG8_LDA(dst, b, h) do { _Pragma("unroll") for (int m = 0; m < 4; ++m) _Pragma("unroll") for (int k = 0; k < 2; ++k) dst[m][k] = *(const PG8_LAS bf16x8*)(lds + PG8_SA(b, h) + aoff + m * 2048 + k * 1024); } while (0)
; #define PG8_LDB(dst, b, h) do { _Pragma("unroll") for (int n = 0; n < 2; ++n) _Pragma("unroll") for (int k = 0; k < 2; ++k) dst[n][k] = *(const PG8_LAS bf16x8*)(lds + PG8_SB(b, h) + boff + n * 2048 + k * 1024); } while (0)
; #define PG8_MMA(ai, bj, At, Bt) do { __builtin_amdgcn_s_setprio(1); _Pragma("unroll") for (int m = 0; m < 4; ++m) _Pragma("unroll") for (int n = 0; n < 2; ++n) _Pragma("unroll") for (int k = 0; k < 2; ++k) \
;         acc[ai][bj][m][n] = __builtin_amdgcn_mfma_f32_16x16x32_bf16(Bt[n][k], At[m][k], acc[ai][bj][m][n], 0, 0, 0); __builtin_amdgcn_s_setprio(0); } while (0)
; template <class Epi, class Sched, bool ALIGN_EPI = false, bool SP2 = false>
; __device__ __forceinline__ void gemm_phase(PG8_LAS unsigned char* lds, const Gemm g, const Sched& S, const Epi& E, int tid_in) {
;     ...
;             PG8_LDB(B0, 0, 0); PG8_LDB(B1, 0, 1); PG8_SCHED; PG8_LDA(At, 0, 0); PG8_STAGE(PG8_SA(1, 1), a1 + hstepA, voffA);
;             PG8_WAIT_V(8); PG8_WAIT_L(0); PG8_BAR; PG8_MMA(0, 0, At, B0); PG8_MMA(0, 1, At, B1); PG8_BAR; PG8_SCHED;
;             PG8_LDA(At, 0, 1); PG8_STAGE(PG8_SB(0, 0), b2, voffB); PG8_STAGE(PG8_SB(0, 1), b2 + hstepB, voffB); PG8_STAGE(PG8_SA(0, 0), a2, voffA);
;             PG8_WAIT_V(8); PG8_WAIT_L(0); PG8_BAR; PG8_MMA(1, 0, At, B0); PG8_MMA(1, 1, At, B1); PG8_BAR; PG8_SCHED;
;             PG8_LDB(B0, 1, 0); PG8_LDB(B1, 1, 1); PG8_SCHED; PG8_LDA(At, 1, 0); PG8_STAGE(PG8_SA(0, 1), a2 + hstepA, voffA);
;             PG8_WAIT_V(8); PG8_WAIT_L(0); PG8_BAR; PG8_MMA(0, 0, At, B0); PG8_MMA(0, 1, At, B1); PG8_BAR; PG8_SCHED;
;             PG8_LDA(At, 1, 1); PG8_STAGE(PG8_SB(1, 0), b3, voffB); PG8_STAGE(PG8_SB(1, 1), b3 + hstepB, voffB); PG8_STAGE(PG8_SA(1, 0), a3, voffA);
;             PG8_WAIT_V(8); PG8_WAIT_L(0); PG8_BAR; PG8_MMA(1, 0, At, B0); PG8_MMA(1, 1, At, B1); PG8_BAR; PG8_SCHED;
	s_setprio 0
	s_mov_b32 m0, s75
	s_add_i32 s36, s12, 0x80
	ds_read_b128 v[162:165], v238 offset:49152
	ds_read_b128 v[166:169], v238 offset:50176
	ds_read_b128 v[170:173], v238 offset:51200
	ds_read_b128 v[174:177], v238 offset:52224
	ds_read_b128 v[178:181], v238 offset:53248
	ds_read_b128 v[182:185], v238 offset:54272
	ds_read_b128 v[186:189], v238 offset:55296
	ds_read_b128 v[190:193], v238 offset:56320
	buffer_load_dwordx4 v207, s[40:43], s36 offen lds
	s_mov_b32 m0, s76
	s_add_i32 s12, s12, 0x80080
	buffer_load_dwordx4 v224, s[40:43], s36 offen lds
	s_mov_b32 m0, s79
	s_addk_i32 s13, 0x80
	buffer_load_dwordx4 v207, s[40:43], s12 offen lds
	s_mov_b32 m0, s68
	s_nop 0
	buffer_load_dwordx4 v224, s[40:43], s12 offen lds
	s_mov_b32 m0, s77
	s_nop 0
	buffer_load_dwordx4 v195, s[4:7], s13 offen lds
	s_waitcnt vmcnt(7)
	s_waitcnt lgkmcnt(0)
	s_setprio 1
	s_barrier
	v_mfma_f32_16x16x32_bf16 v[62:65], v[130:133], v[162:165], v[62:65]
	v_mfma_f32_16x16x32_bf16 v[58:61], v[138:141], v[162:165], v[58:61]
	v_mfma_f32_16x16x32_bf16 v[42:45], v[138:141], v[170:173], v[42:45]
	v_mfma_f32_16x16x32_bf16 v[46:49], v[130:133], v[170:173], v[46:49]
	v_mfma_f32_16x16x32_bf16 v[30:33], v[130:133], v[178:181], v[30:33]
	v_mfma_f32_16x16x32_bf16 v[26:29], v[138:141], v[178:181], v[26:29]
	v_mfma_f32_16x16x32_bf16 v[10:13], v[138:141], v[186:189], v[10:13]
	v_mfma_f32_16x16x32_bf16 v[14:17], v[130:133], v[186:189], v[14:17]
	v_mfma_f32_16x16x32_bf16 v[62:65], v[134:137], v[166:169], v[62:65]
	v_mfma_f32_16x16x32_bf16 v[58:61], v[142:145], v[166:169], v[58:61]
	v_mfma_f32_16x16x32_bf16 v[42:45], v[142:145], v[174:177], v[42:45]
	v_mfma_f32_16x16x32_bf16 v[46:49], v[134:137], v[174:177], v[46:49]
	v_mfma_f32_16x16x32_bf16 v[30:33], v[134:137], v[182:185], v[30:33]
	v_mfma_f32_16x16x32_bf16 v[26:29], v[142:145], v[182:185], v[26:29]
	v_mfma_f32_16x16x32_bf16 v[10:13], v[142:145], v[190:193], v[10:13]
	v_mfma_f32_16x16x32_bf16 v[14:17], v[134:137], v[190:193], v[14:17]
	v_mfma_f32_16x16x32_bf16 v[54:57], v[146:149], v[162:165], v[54:57]
	v_mfma_f32_16x16x32_bf16 v[50:53], v[154:157], v[162:165], v[50:53]
	v_mfma_f32_16x16x32_bf16 v[34:37], v[154:157], v[170:173], v[34:37]
	v_mfma_f32_16x16x32_bf16 v[38:41], v[146:149], v[170:173], v[38:41]
	v_mfma_f32_16x16x32_bf16 v[22:25], v[146:149], v[178:181], v[22:25]
	v_mfma_f32_16x16x32_bf16 v[18:21], v[154:157], v[178:181], v[18:21]
	v_mfma_f32_16x16x32_bf16 v[2:5], v[154:157], v[186:189], v[2:5]
	v_mfma_f32_16x16x32_bf16 v[6:9], v[146:149], v[186:189], v[6:9]
	v_mfma_f32_16x16x32_bf16 v[54:57], v[150:153], v[166:169], v[54:57]
	v_mfma_f32_16x16x32_bf16 v[50:53], v[158:161], v[166:169], v[50:53]
	v_mfma_f32_16x16x32_bf16 v[34:37], v[158:161], v[174:177], v[34:37]
	v_mfma_f32_16x16x32_bf16 v[38:41], v[150:153], v[174:177], v[38:41]
	v_mfma_f32_16x16x32_bf16 v[22:25], v[150:153], v[182:185], v[22:25]
	v_mfma_f32_16x16x32_bf16 v[18:21], v[158:161], v[182:185], v[18:21]
	v_mfma_f32_16x16x32_bf16 v[2:5], v[158:161], v[190:193], v[2:5]
	v_mfma_f32_16x16x32_bf16 v[6:9], v[150:153], v[190:193], v[6:9]
	s_barrier
	s_setprio 0
	s_add_i32 s23, s23, 2
	s_add_u32 s20, s20, 0x100
	s_addc_u32 s21, s21, 0
	s_cmp_gt_u32 s23, 29
	s_mov_b64 s[12:13], s[16:17]
.LBB0_312:
	v_add_u32_e32 v0, 0x10000, v237
	ds_read_b128 v[130:133], v0
	ds_read_b128 v[134:137], v0 offset:1024
	ds_read_b128 v[138:141], v0 offset:2048
	ds_read_b128 v[142:145], v0 offset:3072
	v_add_u32_e32 v0, 0x14000, v237
	ds_read_b128 v[146:149], v0
	ds_read_b128 v[150:153], v0 offset:1024
	ds_read_b128 v[154:157], v0 offset:2048
	ds_read_b128 v[158:161], v0 offset:3072
	s_add_u32 s16, s12, 0x100
	s_addc_u32 s17, s13, 0
	s_sub_i32 s12, s12, s4
	s_add_i32 s12, s12, 0x80080
	s_sub_i32 s36, s12, 0x80000
	s_cmp_eq_u32 s23, 28
	s_cselect_b32 s13, s19, s16
	s_mov_b32 m0, s69
	ds_read_b128 v[162:165], v238
	ds_read_b128 v[166:169], v238 offset:1024
	ds_read_b128 v[170:173], v238 offset:2048
	ds_read_b128 v[174:177], v238 offset:3072
	ds_read_b128 v[178:181], v238 offset:4096
	ds_read_b128 v[182:185], v238 offset:5120
	ds_read_b128 v[186:189], v238 offset:6144
	ds_read_b128 v[190:193], v238 offset:7168
	s_mov_b32 m0, s78
	s_nop 0
	buffer_load_dwordx4 v211, s[4:7], s36 offen lds
	s_mov_b32 m0, s69
	s_nop 0
	buffer_load_dwordx4 v195, s[4:7], s12 offen lds
	s_mov_b32 m0, s67
	s_nop 0
	buffer_load_dwordx4 v211, s[4:7], s12 offen lds
	s_waitcnt vmcnt(8)
	s_waitcnt lgkmcnt(0)
	s_setprio 1
	s_barrier
	v_mfma_f32_16x16x32_bf16 v[126:129], v[130:133], v[162:165], v[126:129]
	v_mfma_f32_16x16x32_bf16 v[122:125], v[138:141], v[162:165], v[122:125]
	v_mfma_f32_16x16x32_bf16 v[106:109], v[138:141], v[170:173], v[106:109]
	v_mfma_f32_16x16x32_bf16 v[110:113], v[130:133], v[170:173], v[110:113]
	v_mfma_f32_16x16x32_bf16 v[94:97], v[130:133], v[178:181], v[94:97]
	v_mfma_f32_16x16x32_bf16 v[90:93], v[138:141], v[178:181], v[90:93]
	v_mfma_f32_16x16x32_bf16 v[74:77], v[138:141], v[186:189], v[74:77]
	v_mfma_f32_16x16x32_bf16 v[78:81], v[130:133], v[186:189], v[78:81]
	v_mfma_f32_16x16x32_bf16 v[126:129], v[134:137], v[166:169], v[126:129]
	v_mfma_f32_16x16x32_bf16 v[122:125], v[142:145], v[166:169], v[122:125]
	v_mfma_f32_16x16x32_bf16 v[106:109], v[142:145], v[174:177], v[106:109]
	v_mfma_f32_16x16x32_bf16 v[110:113], v[134:137], v[174:177], v[110:113]
	v_mfma_f32_16x16x32_bf16 v[94:97], v[134:137], v[182:185], v[94:97]
	v_mfma_f32_16x16x32_bf16 v[90:93], v[142:145], v[182:185], v[90:93]
	v_mfma_f32_16x16x32_bf16 v[74:77], v[142:145], v[190:193], v[74:77]
	v_mfma_f32_16x16x32_bf16 v[78:81], v[134:137], v[190:193], v[78:81]
	v_mfma_f32_16x16x32_bf16 v[118:121], v[146:149], v[162:165], v[118:121]
	v_mfma_f32_16x16x32_bf16 v[114:117], v[154:157], v[162:165], v[114:117]
	v_mfma_f32_16x16x32_bf16 v[98:101], v[154:157], v[170:173], v[98:101]
	v_mfma_f32_16x16x32_bf16 v[102:105], v[146:149], v[170:173], v[102:105]
	v_mfma_f32_16x16x32_bf16 v[86:89], v[146:149], v[178:181], v[86:89]
	v_mfma_f32_16x16x32_bf16 v[82:85], v[154:157], v[178:181], v[82:85]
	v_mfma_f32_16x16x32_bf16 v[66:69], v[154:157], v[186:189], v[66:69]
	v_mfma_f32_16x16x32_bf16 v[70:73], v[146:149], v[186:189], v[70:73]
	v_mfma_f32_16x16x32_bf16 v[118:121], v[150:153], v[166:169], v[118:121]
	v_mfma_f32_16x16x32_bf16 v[114:117], v[158:161], v[166:169], v[114:117]
	v_mfma_f32_16x16x32_bf16 v[98:101], v[158:161], v[174:177], v[98:101]
	v_mfma_f32_16x16x32_bf16 v[102:105], v[150:153], v[174:177], v[102:105]
	v_mfma_f32_16x16x32_bf16 v[86:89], v[150:153], v[182:185], v[86:89]
	v_mfma_f32_16x16x32_bf16 v[82:85], v[158:161], v[182:185], v[82:85]
	v_mfma_f32_16x16x32_bf16 v[66:69], v[158:161], v[190:193], v[66:69]
	v_mfma_f32_16x16x32_bf16 v[70:73], v[150:153], v[190:193], v[70:73]
	s_barrier
; #define PG8_STAGE(bufoff, gbase, voff) do { const int so_ = (int)(unsigned)((const char*)(gbase) - base_##voff); _Pragma("unroll") for (int _i = 0; _i < 2; ++_i) \
;         __builtin_amdgcn_raw_ptr_buffer_load_lds(rs_##voff, (PG8_LAS unsigned*)(lds + (bufoff) + ldsw + _i * 8192), 16, (int)(voff)[_i], so_, 0, 0); } while (0)
; #define PG8_LDA(dst, b, h) do { _Pragma("unroll") for (int m = 0; m < 4; ++m) _Pragma("unroll") for (int k = 0; k < 2; ++k) dst[m][k] = *(const PG8_LAS bf16x8*)(lds + PG8_SA(b, h) + aoff + m * 2048 + k * 1024); } while (0)
; #define PG8_LDB(dst, b, h) do { _Pragma("unroll") for (int n = 0; n < 2; ++n) _Pragma("unroll") for (int k = 0; k < 2; ++k) dst[n][k] = *(const PG8_LAS bf16x8*)(lds + PG8_SB(b, h) + boff + n * 2048 + k * 1024); } while (0)
; #define PG8_MMA(ai, bj, At, Bt) do { __builtin_amdgcn_s_setprio(1); _Pragma("unroll") for (int m = 0; m < 4; ++m) _Pragma("unroll") for (int n = 0; n < 2; ++n) _Pragma("unroll") for (int k = 0; k < 2; ++k) \
;         acc[ai][bj][m][n] = __builtin_amdgcn_mfma_f32_16x16x32_bf16(Bt[n][k], At[m][k], acc[ai][bj][m][n], 0, 0, 0); __builtin_amdgcn_s_setprio(0); } while (0)
; #define PG8_WAIT_V(n) asm volatile("s_waitcnt vmcnt(" #n ")" ::: "memory")
; #define PG8_WAIT_L(n) asm volatile("s_waitcnt lgkmcnt(" #n ")" ::: "memory")
; #define PG8_BAR __builtin_amdgcn_s_barrier()
; #define PG8_SCHED __builtin_amdgcn_sched_barrier(0)
; template <class Epi, class Sched, bool ALIGN_EPI = false, bool SP2 = false>
; __device__ __forceinline__ void gemm_phase(PG8_LAS unsigned char* lds, const Gemm g, const Sched& S, const Epi& E, int tid_in) {
;     ...
;             PG8_WAIT_V(8); PG8_WAIT_L(0); PG8_BAR; PG8_MMA(0, 0, At, B0); PG8_MMA(0, 1, At, B1); PG8_BAR; PG8_SCHED;
;             PG8_LDA(At, 0, 1); PG8_STAGE(PG8_SB(0, 0), b2, voffB); PG8_STAGE(PG8_SB(0, 1), b2 + hstepB, voffB); PG8_STAGE(PG8_SA(0, 0), a2, voffA);
;             PG8_WAIT_V(8); PG8_WAIT_L(0); PG8_BAR; PG8_MMA(1, 0, At, B0); PG8_MMA(1, 1, At, B1); PG8_BAR; PG8_SCHED;
;             PG8_LDB(B0, 1, 0); PG8_LDB(B1, 1, 1); PG8_SCHED; PG8_LDA(At, 1, 0); PG8_STAGE(PG8_SA(0, 1), a2 + hstepA, voffA);
;             PG8_WAIT_V(8); PG8_WAIT_L(0); PG8_BAR; PG8_MMA(0, 0, At, B0); PG8_MMA(0, 1, At, B1); PG8_BAR; PG8_SCHED;
	s_setprio 0
	s_cselect_b32 s12, s15, s20
	s_mov_b32 m0, s61
	s_mov_b32 s42, s6
	s_mov_b32 s43, s7
	s_sub_i32 s12, s12, s40
	ds_read_b128 v[162:165], v238 offset:16384
	ds_read_b128 v[166:169], v238 offset:17408
	ds_read_b128 v[170:173], v238 offset:18432
	ds_read_b128 v[174:177], v238 offset:19456
	ds_read_b128 v[178:181], v238 offset:20480
	ds_read_b128 v[182:185], v238 offset:21504
	ds_read_b128 v[186:189], v238 offset:22528
	ds_read_b128 v[190:193], v238 offset:23552
	buffer_load_dwordx4 v207, s[40:43], s12 offen lds
	s_mov_b32 m0, s62
	s_add_i32 s36, s12, 0x80000
	buffer_load_dwordx4 v224, s[40:43], s12 offen lds
	s_mov_b32 m0, s63
	s_sub_i32 s13, s13, s4
	buffer_load_dwordx4 v207, s[40:43], s36 offen lds
	s_mov_b32 m0, s71
	s_nop 0
	buffer_load_dwordx4 v224, s[40:43], s36 offen lds
	s_mov_b32 m0, s53
	s_nop 0
	buffer_load_dwordx4 v195, s[4:7], s13 offen lds
	s_waitcnt vmcnt(7)
	s_waitcnt lgkmcnt(0)
	s_setprio 1
	s_barrier
	v_mfma_f32_16x16x32_bf16 v[62:65], v[130:133], v[162:165], v[62:65]
	v_mfma_f32_16x16x32_bf16 v[58:61], v[138:141], v[162:165], v[58:61]
	v_mfma_f32_16x16x32_bf16 v[42:45], v[138:141], v[170:173], v[42:45]
	v_mfma_f32_16x16x32_bf16 v[46:49], v[130:133], v[170:173], v[46:49]
	v_mfma_f32_16x16x32_bf16 v[30:33], v[130:133], v[178:181], v[30:33]
	v_mfma_f32_16x16x32_bf16 v[26:29], v[138:141], v[178:181], v[26:29]
	v_mfma_f32_16x16x32_bf16 v[10:13], v[138:141], v[186:189], v[10:13]
	v_mfma_f32_16x16x32_bf16 v[14:17], v[130:133], v[186:189], v[14:17]
	v_mfma_f32_16x16x32_bf16 v[62:65], v[134:137], v[166:169], v[62:65]
	v_mfma_f32_16x16x32_bf16 v[58:61], v[142:145], v[166:169], v[58:61]
	v_mfma_f32_16x16x32_bf16 v[42:45], v[142:145], v[174:177], v[42:45]
	v_mfma_f32_16x16x32_bf16 v[46:49], v[134:137], v[174:177], v[46:49]
	v_mfma_f32_16x16x32_bf16 v[30:33], v[134:137], v[182:185], v[30:33]
	v_mfma_f32_16x16x32_bf16 v[26:29], v[142:145], v[182:185], v[26:29]
	v_mfma_f32_16x16x32_bf16 v[10:13], v[142:145], v[190:193], v[10:13]
	v_mfma_f32_16x16x32_bf16 v[14:17], v[134:137], v[190:193], v[14:17]
	v_mfma_f32_16x16x32_bf16 v[54:57], v[146:149], v[162:165], v[54:57]
	v_mfma_f32_16x16x32_bf16 v[50:53], v[154:157], v[162:165], v[50:53]
	v_mfma_f32_16x16x32_bf16 v[34:37], v[154:157], v[170:173], v[34:37]
	v_mfma_f32_16x16x32_bf16 v[38:41], v[146:149], v[170:173], v[38:41]
	v_mfma_f32_16x16x32_bf16 v[22:25], v[146:149], v[178:181], v[22:25]
	v_mfma_f32_16x16x32_bf16 v[18:21], v[154:157], v[178:181], v[18:21]
	v_mfma_f32_16x16x32_bf16 v[2:5], v[154:157], v[186:189], v[2:5]
	v_mfma_f32_16x16x32_bf16 v[6:9], v[146:149], v[186:189], v[6:9]
	v_mfma_f32_16x16x32_bf16 v[54:57], v[150:153], v[166:169], v[54:57]
	v_mfma_f32_16x16x32_bf16 v[50:53], v[158:161], v[166:169], v[50:53]
	v_mfma_f32_16x16x32_bf16 v[34:37], v[158:161], v[174:177], v[34:37]
	v_mfma_f32_16x16x32_bf16 v[38:41], v[150:153], v[174:177], v[38:41]
	v_mfma_f32_16x16x32_bf16 v[22:25], v[150:153], v[182:185], v[22:25]
	v_mfma_f32_16x16x32_bf16 v[18:21], v[158:161], v[182:185], v[18:21]
	v_mfma_f32_16x16x32_bf16 v[2:5], v[158:161], v[190:193], v[2:5]
	v_mfma_f32_16x16x32_bf16 v[6:9], v[150:153], v[190:193], v[6:9]
	s_barrier
	s_setprio 0
	v_add_u32_e32 v0, 0x18000, v237
	ds_read_b128 v[130:133], v0
	ds_read_b128 v[134:137], v0 offset:1024
	ds_read_b128 v[138:141], v0 offset:2048
	ds_read_b128 v[142:145], v0 offset:3072
	v_add_u32_e32 v0, 0x1c000, v237
	ds_read_b128 v[146:149], v0
	ds_read_b128 v[150:153], v0 offset:1024
	ds_read_b128 v[154:157], v0 offset:2048
	ds_read_b128 v[158:161], v0 offset:3072
	s_add_i32 s36, s13, 0x80000
	s_mov_b32 m0, s73
	ds_read_b128 v[162:165], v238 offset:32768
	ds_read_b128 v[166:169], v238 offset:33792
	ds_read_b128 v[170:173], v238 offset:34816
	ds_read_b128 v[174:177], v238 offset:35840
	ds_read_b128 v[178:181], v238 offset:36864
	ds_read_b128 v[182:185], v238 offset:37888
	ds_read_b128 v[186:189], v238 offset:38912
	ds_read_b128 v[190:193], v238 offset:39936
	s_mov_b32 m0, s72
	s_nop 0
	buffer_load_dwordx4 v211, s[4:7], s13 offen lds
	s_mov_b32 m0, s73
	s_nop 0
	buffer_load_dwordx4 v195, s[4:7], s36 offen lds
	s_mov_b32 m0, s74
	s_nop 0
	buffer_load_dwordx4 v211, s[4:7], s36 offen lds
	s_waitcnt vmcnt(8)
	s_waitcnt lgkmcnt(0)
	s_setprio 1
	s_barrier
; #define PG8_STAGE(bufoff, gbase, voff) do { const int so_ = (int)(unsigned)((const char*)(gbase) - base_##voff); _Pragma("unroll") for (int _i = 0; _i < 2; ++_i) \
;         __builtin_amdgcn_raw_ptr_buffer_load_lds(rs_##voff, (PG8_LAS unsigned*)(lds + (bufoff) + ldsw + _i * 8192), 16, (int)(voff)[_i], so_, 0, 0); } while (0)
; #define PG8_WAIT_V(n) asm volatile("s_waitcnt vmcnt(" #n ")" ::: "memory")
; template <class Epi, class Sched, bool ALIGN_EPI = false, bool SP2 = false>
; __device__ __forceinline__ void gemm_phase(PG8_LAS unsigned char* lds, const Gemm g, const Sched& S, const Epi& E, int tid_in) {
;     ...
;             PG8_WAIT_V(8); PG8_WAIT_L(0); PG8_BAR; PG8_MMA(0, 0, At, B0); PG8_MMA(0, 1, At, B1); PG8_BAR; PG8_SCHED;
;             PG8_LDA(At, 1, 1); PG8_STAGE(PG8_SB(1, 0), b3, voffB); PG8_STAGE(PG8_SB(1, 1), b3 + hstepB, voffB); PG8_STAGE(PG8_SA(1, 0), a3, voffA);
;             PG8_WAIT_V(8); PG8_WAIT_L(0); PG8_BAR; PG8_MMA(1, 0, At, B0); PG8_MMA(1, 1, At, B1); PG8_BAR; PG8_SCHED;
;             } else {
;             PG8_LDB(B0, 0, 0); PG8_SCHED; PG8_LDA(At, 0, 0); PG8_STAGE(PG8_SA(1, 1), a1 + hstepA, voffA);
;             PG8_WAIT_L(8); PG8_BAR; PG8_WAIT_L(0); PG8_MMA(0, 0, At, B0); PG8_BAR; PG8_SCHED;
;             PG8_LDB(B1, 0, 1); PG8_STAGE(PG8_SB(0, 0), b2, voffB);
;             PG8_BAR; PG8_WAIT_L(0); PG8_MMA(0, 1, At, B1); PG8_BAR;
;             PG8_LDA(At, 0, 1); PG8_STAGE(PG8_SA(0, 0), a2, voffA);
;             PG8_BAR; PG8_WAIT_L(0); PG8_MMA(1, 0, At, B0); PG8_BAR; PG8_SCHED;
;             PG8_STAGE(PG8_SB(0, 1), b2 + hstepB, voffB);
;             PG8_WAIT_V(6); PG8_BAR; PG8_MMA(1, 1, At, B1); PG8_BAR;
;             PG8_LDB(B0, 1, 0); PG8_SCHED; PG8_LDA(At, 1, 0); PG8_STAGE(PG8_SA(0, 1), a2 + hstepA, voffA);
;             PG8_WAIT_L(8); PG8_BAR; PG8_WAIT_L(0); PG8_MMA(0, 0, At, B0); PG8_BAR; PG8_SCHED;
;             PG8_LDB(B1, 1, 1); PG8_STAGE(PG8_SB(1, 0), b3, voffB);
;             PG8_BAR; PG8_WAIT_L(0); PG8_MMA(0, 1, At, B1); PG8_BAR;
;             PG8_LDA(At, 1, 1); PG8_STAGE(PG8_SA(1, 0), a3, voffA);
;             PG8_BAR; PG8_WAIT_L(0); PG8_MMA(1, 0, At, B0); PG8_BAR; PG8_SCHED;
;             PG8_STAGE(PG8_SB(1, 1), b3 + hstepB, voffB);
;             PG8_WAIT_V(6); PG8_BAR; PG8_MMA(1, 1, At, B1); PG8_BAR;
;             }
;         }
;         if constexpr (ALIGN_EPI) { if (wr == 0) PG8_BAR; }
	v_mfma_f32_16x16x32_bf16 v[126:129], v[130:133], v[162:165], v[126:129]
	v_mfma_f32_16x16x32_bf16 v[122:125], v[138:141], v[162:165], v[122:125]
	v_mfma_f32_16x16x32_bf16 v[106:109], v[138:141], v[170:173], v[106:109]
	v_mfma_f32_16x16x32_bf16 v[110:113], v[130:133], v[170:173], v[110:113]
	v_mfma_f32_16x16x32_bf16 v[94:97], v[130:133], v[178:181], v[94:97]
	v_mfma_f32_16x16x32_bf16 v[90:93], v[138:141], v[178:181], v[90:93]
	v_mfma_f32_16x16x32_bf16 v[74:77], v[138:141], v[186:189], v[74:77]
	v_mfma_f32_16x16x32_bf16 v[78:81], v[130:133], v[186:189], v[78:81]
	v_mfma_f32_16x16x32_bf16 v[126:129], v[134:137], v[166:169], v[126:129]
	v_mfma_f32_16x16x32_bf16 v[122:125], v[142:145], v[166:169], v[122:125]
	v_mfma_f32_16x16x32_bf16 v[106:109], v[142:145], v[174:177], v[106:109]
	v_mfma_f32_16x16x32_bf16 v[110:113], v[134:137], v[174:177], v[110:113]
	v_mfma_f32_16x16x32_bf16 v[94:97], v[134:137], v[182:185], v[94:97]
	v_mfma_f32_16x16x32_bf16 v[90:93], v[142:145], v[182:185], v[90:93]
	v_mfma_f32_16x16x32_bf16 v[74:77], v[142:145], v[190:193], v[74:77]
	v_mfma_f32_16x16x32_bf16 v[78:81], v[134:137], v[190:193], v[78:81]
	v_mfma_f32_16x16x32_bf16 v[118:121], v[146:149], v[162:165], v[118:121]
	v_mfma_f32_16x16x32_bf16 v[114:117], v[154:157], v[162:165], v[114:117]
	v_mfma_f32_16x16x32_bf16 v[98:101], v[154:157], v[170:173], v[98:101]
	v_mfma_f32_16x16x32_bf16 v[102:105], v[146:149], v[170:173], v[102:105]
	v_mfma_f32_16x16x32_bf16 v[86:89], v[146:149], v[178:181], v[86:89]
	v_mfma_f32_16x16x32_bf16 v[82:85], v[154:157], v[178:181], v[82:85]
	v_mfma_f32_16x16x32_bf16 v[66:69], v[154:157], v[186:189], v[66:69]
	v_mfma_f32_16x16x32_bf16 v[70:73], v[146:149], v[186:189], v[70:73]
	v_mfma_f32_16x16x32_bf16 v[118:121], v[150:153], v[166:169], v[118:121]
	v_mfma_f32_16x16x32_bf16 v[114:117], v[158:161], v[166:169], v[114:117]
	v_mfma_f32_16x16x32_bf16 v[98:101], v[158:161], v[174:177], v[98:101]
	v_mfma_f32_16x16x32_bf16 v[102:105], v[150:153], v[174:177], v[102:105]
	v_mfma_f32_16x16x32_bf16 v[86:89], v[150:153], v[182:185], v[86:89]
	v_mfma_f32_16x16x32_bf16 v[82:85], v[158:161], v[182:185], v[82:85]
	v_mfma_f32_16x16x32_bf16 v[66:69], v[158:161], v[190:193], v[66:69]
	v_mfma_f32_16x16x32_bf16 v[70:73], v[150:153], v[190:193], v[70:73]
	s_barrier
	s_setprio 0
	s_mov_b32 m0, s75
	s_add_i32 s36, s12, 0x80
	ds_read_b128 v[162:165], v238 offset:49152
	ds_read_b128 v[166:169], v238 offset:50176
	ds_read_b128 v[170:173], v238 offset:51200
	ds_read_b128 v[174:177], v238 offset:52224
	ds_read_b128 v[178:181], v238 offset:53248
	ds_read_b128 v[182:185], v238 offset:54272
	ds_read_b128 v[186:189], v238 offset:55296
	ds_read_b128 v[190:193], v238 offset:56320
	buffer_load_dwordx4 v207, s[40:43], s36 offen lds
	s_mov_b32 m0, s76
	s_add_i32 s12, s12, 0x80080
	buffer_load_dwordx4 v224, s[40:43], s36 offen lds
	s_mov_b32 m0, s79
	s_addk_i32 s13, 0x80
	buffer_load_dwordx4 v207, s[40:43], s12 offen lds
	s_mov_b32 m0, s68
	s_nop 0
	buffer_load_dwordx4 v224, s[40:43], s12 offen lds
	s_mov_b32 m0, s77
	s_nop 0
	buffer_load_dwordx4 v195, s[4:7], s13 offen lds
	s_waitcnt vmcnt(7)
	s_waitcnt lgkmcnt(0)
	s_setprio 1
	s_barrier
	v_mfma_f32_16x16x32_bf16 v[62:65], v[130:133], v[162:165], v[62:65]
	v_mfma_f32_16x16x32_bf16 v[58:61], v[138:141], v[162:165], v[58:61]
	v_mfma_f32_16x16x32_bf16 v[42:45], v[138:141], v[170:173], v[42:45]
	v_mfma_f32_16x16x32_bf16 v[46:49], v[130:133], v[170:173], v[46:49]
	v_mfma_f32_16x16x32_bf16 v[30:33], v[130:133], v[178:181], v[30:33]
	v_mfma_f32_16x16x32_bf16 v[26:29], v[138:141], v[178:181], v[26:29]
	v_mfma_f32_16x16x32_bf16 v[10:13], v[138:141], v[186:189], v[10:13]
	v_mfma_f32_16x16x32_bf16 v[14:17], v[130:133], v[186:189], v[14:17]
	v_mfma_f32_16x16x32_bf16 v[62:65], v[134:137], v[166:169], v[62:65]
	v_mfma_f32_16x16x32_bf16 v[58:61], v[142:145], v[166:169], v[58:61]
	v_mfma_f32_16x16x32_bf16 v[42:45], v[142:145], v[174:177], v[42:45]
	v_mfma_f32_16x16x32_bf16 v[46:49], v[134:137], v[174:177], v[46:49]
	v_mfma_f32_16x16x32_bf16 v[30:33], v[134:137], v[182:185], v[30:33]
	v_mfma_f32_16x16x32_bf16 v[26:29], v[142:145], v[182:185], v[26:29]
	v_mfma_f32_16x16x32_bf16 v[10:13], v[142:145], v[190:193], v[10:13]
	v_mfma_f32_16x16x32_bf16 v[14:17], v[134:137], v[190:193], v[14:17]
	v_mfma_f32_16x16x32_bf16 v[54:57], v[146:149], v[162:165], v[54:57]
	v_mfma_f32_16x16x32_bf16 v[50:53], v[154:157], v[162:165], v[50:53]
	v_mfma_f32_16x16x32_bf16 v[34:37], v[154:157], v[170:173], v[34:37]
	v_mfma_f32_16x16x32_bf16 v[38:41], v[146:149], v[170:173], v[38:41]
	v_mfma_f32_16x16x32_bf16 v[22:25], v[146:149], v[178:181], v[22:25]
	v_mfma_f32_16x16x32_bf16 v[18:21], v[154:157], v[178:181], v[18:21]
	v_mfma_f32_16x16x32_bf16 v[2:5], v[154:157], v[186:189], v[2:5]
	v_mfma_f32_16x16x32_bf16 v[6:9], v[146:149], v[186:189], v[6:9]
	v_mfma_f32_16x16x32_bf16 v[54:57], v[150:153], v[166:169], v[54:57]
	v_mfma_f32_16x16x32_bf16 v[50:53], v[158:161], v[166:169], v[50:53]
	v_mfma_f32_16x16x32_bf16 v[34:37], v[158:161], v[174:177], v[34:37]
	v_mfma_f32_16x16x32_bf16 v[38:41], v[150:153], v[174:177], v[38:41]
	v_mfma_f32_16x16x32_bf16 v[22:25], v[150:153], v[182:185], v[22:25]
	v_mfma_f32_16x16x32_bf16 v[18:21], v[158:161], v[182:185], v[18:21]
	v_mfma_f32_16x16x32_bf16 v[2:5], v[158:161], v[190:193], v[2:5]
	v_mfma_f32_16x16x32_bf16 v[6:9], v[150:153], v[190:193], v[6:9]
	s_barrier
	s_setprio 0
	s_add_i32 s23, s23, 2
	s_add_u32 s20, s20, 0x100
	s_addc_u32 s21, s21, 0
	s_cmp_gt_u32 s23, 29
	s_mov_b64 s[12:13], s[16:17]
	s_cbranch_scc0 .LBB0_312
	s_and_b64 vcc, exec, s[48:49]
	s_cbranch_vccz .LBB0_315
	s_barrier

; #define PG8_STAGE(bufoff, gbase, voff) do { const int so_ = (int)(unsigned)((const char*)(gbase) - base_##voff); _Pragma("unroll") for (int _i = 0; _i < 2; ++_i) \
;         __builtin_amdgcn_raw_ptr_buffer_load_lds(rs_##voff, (PG8_LAS unsigned*)(lds + (bufoff) + ldsw + _i * 8192), 16, (int)(voff)[_i], so_, 0, 0); } while (0)
; #define PG8_LDA(dst, b, h) do { _Pragma("unroll") for (int m = 0; m < 4; ++m) _Pragma("unroll") for (int k = 0; k < 2; ++k) dst[m][k] = *(const PG8_LAS bf16x8*)(lds + PG8_SA(b, h) + aoff + m * 2048 + k * 1024); } while (0)
; #define PG8_LDB(dst, b, h) do { _Pragma("unroll") for (int n = 0; n < 2; ++n) _Pragma("unroll") for (int k = 0; k < 2; ++k) dst[n][k] = *(const PG8_LAS bf16x8*)(lds + PG8_SB(b, h) + boff + n * 2048 + k * 1024); } while (0)
; #define PG8_MMA(ai, bj, At, Bt) do { __builtin_amdgcn_s_setprio(1); _Pragma("unroll") for (int m = 0; m < 4; ++m) _Pragma("unroll") for (int n = 0; n < 2; ++n) _Pragma("unroll") for (int k = 0; k < 2; ++k) \
;         acc[ai][bj][m][n] = __builtin_amdgcn_mfma_f32_16x16x32_bf16(Bt[n][k], At[m][k], acc[ai][bj][m][n], 0, 0, 0); __builtin_amdgcn_s_setprio(0); } while (0)
; #define PG8_WAIT_V(n) asm volatile("s_waitcnt vmcnt(" #n ")" ::: "memory")
; #define PG8_WAIT_L(n) asm volatile("s_waitcnt lgkmcnt(" #n ")" ::: "memory")
; #define PG8_BAR __builtin_amdgcn_s_barrier()
; #define PG8_SCHED __builtin_amdgcn_sched_barrier(0)
; template <class Epi, class Sched, bool ALIGN_EPI = false, bool SP2 = false>
; __device__ __forceinline__ void gemm_phase(PG8_LAS unsigned char* lds, const Gemm g, const Sched& S, const Epi& E, int tid_in) {
;     ...
;             PG8_LDB(B0, 0, 0); PG8_LDB(B1, 0, 1); PG8_SCHED; PG8_LDA(At, 0, 0); PG8_STAGE(PG8_SA(1, 1), a1 + hstepA, voffA);
;             PG8_WAIT_V(8); PG8_WAIT_L(0); PG8_BAR; PG8_MMA(0, 0, At, B0); PG8_MMA(0, 1, At, B1); PG8_BAR; PG8_SCHED;
;             PG8_LDA(At, 0, 1); PG8_STAGE(PG8_SB(0, 0), b2, voffB); PG8_STAGE(PG8_SB(0, 1), b2 + hstepB, voffB); PG8_STAGE(PG8_SA(0, 0), a2, voffA);
;             PG8_WAIT_V(8); PG8_WAIT_L(0); PG8_BAR; PG8_MMA(1, 0, At, B0); PG8_MMA(1, 1, At, B1); PG8_BAR; PG8_SCHED;
.LBB0_1037:
	v_add_u32_e32 v0, 0x10000, v236
	ds_read_b128 v[132:135], v0
	ds_read_b128 v[136:139], v0 offset:1024
	ds_read_b128 v[140:143], v0 offset:2048
	ds_read_b128 v[144:147], v0 offset:3072
	v_add_u32_e32 v0, 0x14000, v236
	ds_read_b128 v[148:151], v0
	ds_read_b128 v[152:155], v0 offset:1024
	ds_read_b128 v[156:159], v0 offset:2048
	ds_read_b128 v[160:163], v0 offset:3072
	s_add_u32 s16, s12, 0x100
	s_addc_u32 s17, s13, 0
	s_sub_i32 s12, s12, s4
	s_add_i32 s12, s12, 0xc0080
	s_sub_i32 s39, s12, 0xc0000
	s_cmp_eq_u32 s38, 12
	s_cselect_b32 s13, s24, s16
	s_mov_b32 m0, s76
	ds_read_b128 v[164:167], v237
	ds_read_b128 v[168:171], v237 offset:1024
	ds_read_b128 v[172:175], v237 offset:2048
	ds_read_b128 v[176:179], v237 offset:3072
	ds_read_b128 v[180:183], v237 offset:4096
	ds_read_b128 v[184:187], v237 offset:5120
	ds_read_b128 v[188:191], v237 offset:6144
	ds_read_b128 v[192:195], v237 offset:7168
	s_mov_b32 m0, s73
	s_nop 0
	buffer_load_dwordx4 v222, s[4:7], s39 offen lds
	s_mov_b32 m0, s76
	s_nop 0
	buffer_load_dwordx4 v220, s[4:7], s12 offen lds
	s_mov_b32 m0, s77
	s_nop 0
	buffer_load_dwordx4 v222, s[4:7], s12 offen lds
	s_waitcnt vmcnt(8)
	s_waitcnt lgkmcnt(0)
	s_setprio 1
	s_barrier
	v_mfma_f32_16x16x32_bf16 v[128:131], v[132:135], v[164:167], v[128:131]
	v_mfma_f32_16x16x32_bf16 v[124:127], v[140:143], v[164:167], v[124:127]
	v_mfma_f32_16x16x32_bf16 v[116:119], v[140:143], v[172:175], v[116:119]
	v_mfma_f32_16x16x32_bf16 v[120:123], v[132:135], v[172:175], v[120:123]
	v_mfma_f32_16x16x32_bf16 v[112:115], v[132:135], v[180:183], v[112:115]
	v_mfma_f32_16x16x32_bf16 v[108:111], v[140:143], v[180:183], v[108:111]
	v_mfma_f32_16x16x32_bf16 v[100:103], v[140:143], v[188:191], v[100:103]
	v_mfma_f32_16x16x32_bf16 v[104:107], v[132:135], v[188:191], v[104:107]
	v_mfma_f32_16x16x32_bf16 v[128:131], v[136:139], v[168:171], v[128:131]
	v_mfma_f32_16x16x32_bf16 v[124:127], v[144:147], v[168:171], v[124:127]
	v_mfma_f32_16x16x32_bf16 v[116:119], v[144:147], v[176:179], v[116:119]
	v_mfma_f32_16x16x32_bf16 v[120:123], v[136:139], v[176:179], v[120:123]
	v_mfma_f32_16x16x32_bf16 v[112:115], v[136:139], v[184:187], v[112:115]
	v_mfma_f32_16x16x32_bf16 v[108:111], v[144:147], v[184:187], v[108:111]
	v_mfma_f32_16x16x32_bf16 v[100:103], v[144:147], v[192:195], v[100:103]
	v_mfma_f32_16x16x32_bf16 v[104:107], v[136:139], v[192:195], v[104:107]
	v_mfma_f32_16x16x32_bf16 v[96:99], v[148:151], v[164:167], v[96:99]
	v_mfma_f32_16x16x32_bf16 v[92:95], v[156:159], v[164:167], v[92:95]
	v_mfma_f32_16x16x32_bf16 v[84:87], v[156:159], v[172:175], v[84:87]
	v_mfma_f32_16x16x32_bf16 v[88:91], v[148:151], v[172:175], v[88:91]
	v_mfma_f32_16x16x32_bf16 v[80:83], v[148:151], v[180:183], v[80:83]
	v_mfma_f32_16x16x32_bf16 v[76:79], v[156:159], v[180:183], v[76:79]
	v_mfma_f32_16x16x32_bf16 v[68:71], v[156:159], v[188:191], v[68:71]
	v_mfma_f32_16x16x32_bf16 v[72:75], v[148:151], v[188:191], v[72:75]
	v_mfma_f32_16x16x32_bf16 v[96:99], v[152:155], v[168:171], v[96:99]
	v_mfma_f32_16x16x32_bf16 v[92:95], v[160:163], v[168:171], v[92:95]
	v_mfma_f32_16x16x32_bf16 v[84:87], v[160:163], v[176:179], v[84:87]
	v_mfma_f32_16x16x32_bf16 v[88:91], v[152:155], v[176:179], v[88:91]
	v_mfma_f32_16x16x32_bf16 v[80:83], v[152:155], v[184:187], v[80:83]
	v_mfma_f32_16x16x32_bf16 v[76:79], v[160:163], v[184:187], v[76:79]
	v_mfma_f32_16x16x32_bf16 v[68:71], v[160:163], v[192:195], v[68:71]
	v_mfma_f32_16x16x32_bf16 v[72:75], v[152:155], v[192:195], v[72:75]
	s_barrier
	s_setprio 0
	s_cselect_b32 s12, s18, s19
	s_mov_b32 m0, s26
	s_mov_b32 s46, s6
	s_mov_b32 s47, s7
	s_sub_i32 s12, s12, s44
	ds_read_b128 v[164:167], v237 offset:16384
	ds_read_b128 v[168:171], v237 offset:17408
	ds_read_b128 v[172:175], v237 offset:18432
	ds_read_b128 v[176:179], v237 offset:19456
	ds_read_b128 v[180:183], v237 offset:20480
	ds_read_b128 v[184:187], v237 offset:21504
	ds_read_b128 v[188:191], v237 offset:22528
	ds_read_b128 v[192:195], v237 offset:23552
	buffer_load_dwordx4 v221, s[44:47], s12 offen lds
	s_mov_b32 m0, s53
	s_add_i32 s39, s12, 0x40000
	buffer_load_dwordx4 v223, s[44:47], s12 offen lds
	s_mov_b32 m0, s60
	s_sub_i32 s13, s13, s4
	buffer_load_dwordx4 v221, s[44:47], s39 offen lds
	s_mov_b32 m0, s61
	s_nop 0
	buffer_load_dwordx4 v223, s[44:47], s39 offen lds
	s_mov_b32 m0, s21
	s_nop 0
	buffer_load_dwordx4 v220, s[4:7], s13 offen lds
	s_waitcnt vmcnt(7)
	s_waitcnt lgkmcnt(0)
	s_setprio 1
	s_barrier
	v_mfma_f32_16x16x32_bf16 v[64:67], v[132:135], v[164:167], v[64:67]
	v_mfma_f32_16x16x32_bf16 v[60:63], v[140:143], v[164:167], v[60:63]
	v_mfma_f32_16x16x32_bf16 v[52:55], v[140:143], v[172:175], v[52:55]
	v_mfma_f32_16x16x32_bf16 v[56:59], v[132:135], v[172:175], v[56:59]
	v_mfma_f32_16x16x32_bf16 v[48:51], v[132:135], v[180:183], v[48:51]
	v_mfma_f32_16x16x32_bf16 v[44:47], v[140:143], v[180:183], v[44:47]
	v_mfma_f32_16x16x32_bf16 v[36:39], v[140:143], v[188:191], v[36:39]
	v_mfma_f32_16x16x32_bf16 v[40:43], v[132:135], v[188:191], v[40:43]
	v_mfma_f32_16x16x32_bf16 v[64:67], v[136:139], v[168:171], v[64:67]
	v_mfma_f32_16x16x32_bf16 v[60:63], v[144:147], v[168:171], v[60:63]
	v_mfma_f32_16x16x32_bf16 v[52:55], v[144:147], v[176:179], v[52:55]
	v_mfma_f32_16x16x32_bf16 v[56:59], v[136:139], v[176:179], v[56:59]
	v_mfma_f32_16x16x32_bf16 v[48:51], v[136:139], v[184:187], v[48:51]
	v_mfma_f32_16x16x32_bf16 v[44:47], v[144:147], v[184:187], v[44:47]
	v_mfma_f32_16x16x32_bf16 v[36:39], v[144:147], v[192:195], v[36:39]
	v_mfma_f32_16x16x32_bf16 v[40:43], v[136:139], v[192:195], v[40:43]
	v_mfma_f32_16x16x32_bf16 v[32:35], v[148:151], v[164:167], v[32:35]
	v_mfma_f32_16x16x32_bf16 v[28:31], v[156:159], v[164:167], v[28:31]
	v_mfma_f32_16x16x32_bf16 v[20:23], v[156:159], v[172:175], v[20:23]
	v_mfma_f32_16x16x32_bf16 v[24:27], v[148:151], v[172:175], v[24:27]
	v_mfma_f32_16x16x32_bf16 v[16:19], v[148:151], v[180:183], v[16:19]
	v_mfma_f32_16x16x32_bf16 v[12:15], v[156:159], v[180:183], v[12:15]
	v_mfma_f32_16x16x32_bf16 v[2:5], v[156:159], v[188:191], v[4:7]
	v_mfma_f32_16x16x32_bf16 v[8:11], v[148:151], v[188:191], v[8:11]
	v_mfma_f32_16x16x32_bf16 v[32:35], v[152:155], v[168:171], v[32:35]
	v_mfma_f32_16x16x32_bf16 v[28:31], v[160:163], v[168:171], v[28:31]
	v_mfma_f32_16x16x32_bf16 v[20:23], v[160:163], v[176:179], v[20:23]
	v_mfma_f32_16x16x32_bf16 v[24:27], v[152:155], v[176:179], v[24:27]
	v_mfma_f32_16x16x32_bf16 v[16:19], v[152:155], v[184:187], v[16:19]
	v_mfma_f32_16x16x32_bf16 v[12:15], v[160:163], v[184:187], v[12:15]
	v_mfma_f32_16x16x32_bf16 v[2:5], v[160:163], v[192:195], v[2:5]
	v_mfma_f32_16x16x32_bf16 v[8:11], v[152:155], v[192:195], v[8:11]
	s_barrier
; #define PG8_LDA(dst, b, h) do { _Pragma("unroll") for (int m = 0; m < 4; ++m) _Pragma("unroll") for (int k = 0; k < 2; ++k) dst[m][k] = *(const PG8_LAS bf16x8*)(lds + PG8_SA(b, h) + aoff + m * 2048 + k * 1024); } while (0)
; #define PG8_WAIT_V(n) asm volatile("s_waitcnt vmcnt(" #n ")" ::: "memory")
; template <class Epi, class Sched, bool ALIGN_EPI = false, bool SP2 = false>
; __device__ __forceinline__ void gemm_phase(PG8_LAS unsigned char* lds, const Gemm g, const Sched& S, const Epi& E, int tid_in) {
;     ...
;             PG8_LDB(B0, 1, 0); PG8_LDB(B1, 1, 1); PG8_SCHED; PG8_LDA(At, 1, 0); PG8_STAGE(PG8_SA(0, 1), a2 + hstepA, voffA);
;             PG8_WAIT_V(8); PG8_WAIT_L(0); PG8_BAR; PG8_MMA(0, 0, At, B0); PG8_MMA(0, 1, At, B1); PG8_BAR; PG8_SCHED;
;             PG8_LDA(At, 1, 1); PG8_STAGE(PG8_SB(1, 0), b3, voffB); PG8_STAGE(PG8_SB(1, 1), b3 + hstepB, voffB); PG8_STAGE(PG8_SA(1, 0), a3, voffA);
;             PG8_WAIT_V(8); PG8_WAIT_L(0); PG8_BAR; PG8_MMA(1, 0, At, B0); PG8_MMA(1, 1, At, B1); PG8_BAR; PG8_SCHED;
;             } else {
;             PG8_LDB(B0, 0, 0); PG8_SCHED; PG8_LDA(At, 0, 0); PG8_STAGE(PG8_SA(1, 1), a1 + hstepA, voffA);
;             PG8_WAIT_L(8); PG8_BAR; PG8_WAIT_L(0); PG8_MMA(0, 0, At, B0); PG8_BAR; PG8_SCHED;
;             PG8_LDB(B1, 0, 1); PG8_STAGE(PG8_SB(0, 0), b2, voffB);
;             PG8_BAR; PG8_WAIT_L(0); PG8_MMA(0, 1, At, B1); PG8_BAR;
;             PG8_LDA(At, 0, 1); PG8_STAGE(PG8_SA(0, 0), a2, voffA);
;             PG8_BAR; PG8_WAIT_L(0); PG8_MMA(1, 0, At, B0); PG8_BAR; PG8_SCHED;
;             PG8_STAGE(PG8_SB(0, 1), b2 + hstepB, voffB);
;             PG8_WAIT_V(6); PG8_BAR; PG8_MMA(1, 1, At, B1); PG8_BAR;
;             PG8_LDB(B0, 1, 0); PG8_SCHED; PG8_LDA(At, 1, 0); PG8_STAGE(PG8_SA(0, 1), a2 + hstepA, voffA);
;             PG8_WAIT_L(8); PG8_BAR; PG8_WAIT_L(0); PG8_MMA(0, 0, At, B0); PG8_BAR; PG8_SCHED;
;             PG8_LDB(B1, 1, 1); PG8_STAGE(PG8_SB(1, 0), b3, voffB);
;             PG8_BAR; PG8_WAIT_L(0); PG8_MMA(0, 1, At, B1); PG8_BAR;
;             PG8_LDA(At, 1, 1); PG8_STAGE(PG8_SA(1, 0), a3, voffA);
;             PG8_BAR; PG8_WAIT_L(0); PG8_MMA(1, 0, At, B0); PG8_BAR; PG8_SCHED;
;             PG8_STAGE(PG8_SB(1, 1), b3 + hstepB, voffB);
;             PG8_WAIT_V(6); PG8_BAR; PG8_MMA(1, 1, At, B1); PG8_BAR;
;             }
;         }
;         if constexpr (ALIGN_EPI) { if (wr == 0) PG8_BAR; }
	s_setprio 0
	v_add_u32_e32 v0, 0x18000, v236
	ds_read_b128 v[132:135], v0
	ds_read_b128 v[136:139], v0 offset:1024
	ds_read_b128 v[140:143], v0 offset:2048
	ds_read_b128 v[144:147], v0 offset:3072
	v_add_u32_e32 v0, 0x1c000, v236
	ds_read_b128 v[148:151], v0
	ds_read_b128 v[152:155], v0 offset:1024
	ds_read_b128 v[156:159], v0 offset:2048
	ds_read_b128 v[160:163], v0 offset:3072
	s_add_i32 s39, s13, 0xc0000
	s_mov_b32 m0, s63
	ds_read_b128 v[164:167], v237 offset:32768
	ds_read_b128 v[168:171], v237 offset:33792
	ds_read_b128 v[172:175], v237 offset:34816
	ds_read_b128 v[176:179], v237 offset:35840
	ds_read_b128 v[180:183], v237 offset:36864
	ds_read_b128 v[184:187], v237 offset:37888
	ds_read_b128 v[188:191], v237 offset:38912
	ds_read_b128 v[192:195], v237 offset:39936
	s_mov_b32 m0, s62
	s_nop 0
	buffer_load_dwordx4 v222, s[4:7], s13 offen lds
	s_mov_b32 m0, s63
	s_nop 0
	buffer_load_dwordx4 v220, s[4:7], s39 offen lds
	s_mov_b32 m0, s66
	s_nop 0
	buffer_load_dwordx4 v222, s[4:7], s39 offen lds
	s_waitcnt vmcnt(8)
	s_waitcnt lgkmcnt(0)
	s_setprio 1
	s_barrier
	v_mfma_f32_16x16x32_bf16 v[128:131], v[132:135], v[164:167], v[128:131]
	v_mfma_f32_16x16x32_bf16 v[124:127], v[140:143], v[164:167], v[124:127]
	v_mfma_f32_16x16x32_bf16 v[116:119], v[140:143], v[172:175], v[116:119]
	v_mfma_f32_16x16x32_bf16 v[120:123], v[132:135], v[172:175], v[120:123]
	v_mfma_f32_16x16x32_bf16 v[112:115], v[132:135], v[180:183], v[112:115]
	v_mfma_f32_16x16x32_bf16 v[108:111], v[140:143], v[180:183], v[108:111]
	v_mfma_f32_16x16x32_bf16 v[100:103], v[140:143], v[188:191], v[100:103]
	v_mfma_f32_16x16x32_bf16 v[104:107], v[132:135], v[188:191], v[104:107]
	v_mfma_f32_16x16x32_bf16 v[128:131], v[136:139], v[168:171], v[128:131]
	v_mfma_f32_16x16x32_bf16 v[124:127], v[144:147], v[168:171], v[124:127]
	v_mfma_f32_16x16x32_bf16 v[116:119], v[144:147], v[176:179], v[116:119]
	v_mfma_f32_16x16x32_bf16 v[120:123], v[136:139], v[176:179], v[120:123]
	v_mfma_f32_16x16x32_bf16 v[112:115], v[136:139], v[184:187], v[112:115]
	v_mfma_f32_16x16x32_bf16 v[108:111], v[144:147], v[184:187], v[108:111]
	v_mfma_f32_16x16x32_bf16 v[100:103], v[144:147], v[192:195], v[100:103]
	v_mfma_f32_16x16x32_bf16 v[104:107], v[136:139], v[192:195], v[104:107]
	v_mfma_f32_16x16x32_bf16 v[96:99], v[148:151], v[164:167], v[96:99]
	v_mfma_f32_16x16x32_bf16 v[92:95], v[156:159], v[164:167], v[92:95]
	v_mfma_f32_16x16x32_bf16 v[84:87], v[156:159], v[172:175], v[84:87]
	v_mfma_f32_16x16x32_bf16 v[88:91], v[148:151], v[172:175], v[88:91]
	v_mfma_f32_16x16x32_bf16 v[80:83], v[148:151], v[180:183], v[80:83]
	v_mfma_f32_16x16x32_bf16 v[76:79], v[156:159], v[180:183], v[76:79]
	v_mfma_f32_16x16x32_bf16 v[68:71], v[156:159], v[188:191], v[68:71]
	v_mfma_f32_16x16x32_bf16 v[72:75], v[148:151], v[188:191], v[72:75]
	v_mfma_f32_16x16x32_bf16 v[96:99], v[152:155], v[168:171], v[96:99]
	v_mfma_f32_16x16x32_bf16 v[92:95], v[160:163], v[168:171], v[92:95]
	v_mfma_f32_16x16x32_bf16 v[84:87], v[160:163], v[176:179], v[84:87]
	v_mfma_f32_16x16x32_bf16 v[88:91], v[152:155], v[176:179], v[88:91]
	v_mfma_f32_16x16x32_bf16 v[80:83], v[152:155], v[184:187], v[80:83]
	v_mfma_f32_16x16x32_bf16 v[76:79], v[160:163], v[184:187], v[76:79]
	v_mfma_f32_16x16x32_bf16 v[68:71], v[160:163], v[192:195], v[68:71]
	v_mfma_f32_16x16x32_bf16 v[72:75], v[152:155], v[192:195], v[72:75]
	s_barrier
	s_setprio 0
	s_mov_b32 m0, s69
	s_add_i32 s39, s12, 0x80
	ds_read_b128 v[164:167], v237 offset:49152
	ds_read_b128 v[168:171], v237 offset:50176
	ds_read_b128 v[172:175], v237 offset:51200
	ds_read_b128 v[176:179], v237 offset:52224
	ds_read_b128 v[180:183], v237 offset:53248
	ds_read_b128 v[184:187], v237 offset:54272
	ds_read_b128 v[188:191], v237 offset:55296
	ds_read_b128 v[192:195], v237 offset:56320
	buffer_load_dwordx4 v221, s[44:47], s39 offen lds
	s_mov_b32 m0, s71
	s_add_i32 s12, s12, 0x40080
	buffer_load_dwordx4 v223, s[44:47], s39 offen lds
	s_mov_b32 m0, s74
	s_addk_i32 s13, 0x80
	buffer_load_dwordx4 v221, s[44:47], s12 offen lds
	s_mov_b32 m0, s75
	s_nop 0
	buffer_load_dwordx4 v223, s[44:47], s12 offen lds
	s_mov_b32 m0, s72
	s_nop 0
	buffer_load_dwordx4 v220, s[4:7], s13 offen lds
	s_waitcnt vmcnt(7)
	s_waitcnt lgkmcnt(0)
	s_setprio 1
	s_barrier
	v_mfma_f32_16x16x32_bf16 v[64:67], v[132:135], v[164:167], v[64:67]
	v_mfma_f32_16x16x32_bf16 v[60:63], v[140:143], v[164:167], v[60:63]
	v_mfma_f32_16x16x32_bf16 v[52:55], v[140:143], v[172:175], v[52:55]
	v_mfma_f32_16x16x32_bf16 v[56:59], v[132:135], v[172:175], v[56:59]
	v_mfma_f32_16x16x32_bf16 v[48:51], v[132:135], v[180:183], v[48:51]
	v_mfma_f32_16x16x32_bf16 v[44:47], v[140:143], v[180:183], v[44:47]
	v_mfma_f32_16x16x32_bf16 v[36:39], v[140:143], v[188:191], v[36:39]
	v_mfma_f32_16x16x32_bf16 v[40:43], v[132:135], v[188:191], v[40:43]
	v_mfma_f32_16x16x32_bf16 v[64:67], v[136:139], v[168:171], v[64:67]
	v_mfma_f32_16x16x32_bf16 v[60:63], v[144:147], v[168:171], v[60:63]
	v_mfma_f32_16x16x32_bf16 v[52:55], v[144:147], v[176:179], v[52:55]
	v_mfma_f32_16x16x32_bf16 v[56:59], v[136:139], v[176:179], v[56:59]
	v_mfma_f32_16x16x32_bf16 v[48:51], v[136:139], v[184:187], v[48:51]
	v_mfma_f32_16x16x32_bf16 v[44:47], v[144:147], v[184:187], v[44:47]
	v_mfma_f32_16x16x32_bf16 v[36:39], v[144:147], v[192:195], v[36:39]
	v_mfma_f32_16x16x32_bf16 v[40:43], v[136:139], v[192:195], v[40:43]
	v_mfma_f32_16x16x32_bf16 v[32:35], v[148:151], v[164:167], v[32:35]
	v_mfma_f32_16x16x32_bf16 v[28:31], v[156:159], v[164:167], v[28:31]
	v_mfma_f32_16x16x32_bf16 v[20:23], v[156:159], v[172:175], v[20:23]
	v_mfma_f32_16x16x32_bf16 v[24:27], v[148:151], v[172:175], v[24:27]
	v_mfma_f32_16x16x32_bf16 v[16:19], v[148:151], v[180:183], v[16:19]
	v_mfma_f32_16x16x32_bf16 v[12:15], v[156:159], v[180:183], v[12:15]
	v_mfma_f32_16x16x32_bf16 v[2:5], v[156:159], v[188:191], v[2:5]
	v_mfma_f32_16x16x32_bf16 v[6:9], v[148:151], v[188:191], v[8:11]
	v_mfma_f32_16x16x32_bf16 v[32:35], v[152:155], v[168:171], v[32:35]
	v_mfma_f32_16x16x32_bf16 v[28:31], v[160:163], v[168:171], v[28:31]
	v_mfma_f32_16x16x32_bf16 v[20:23], v[160:163], v[176:179], v[20:23]
	v_mfma_f32_16x16x32_bf16 v[24:27], v[152:155], v[176:179], v[24:27]
	v_mfma_f32_16x16x32_bf16 v[16:19], v[152:155], v[184:187], v[16:19]
	v_mfma_f32_16x16x32_bf16 v[12:15], v[160:163], v[184:187], v[12:15]
	v_mfma_f32_16x16x32_bf16 v[4:7], v[160:163], v[192:195], v[2:5]
	v_mfma_f32_16x16x32_bf16 v[8:11], v[152:155], v[192:195], v[6:9]
	s_barrier
	s_setprio 0
	s_add_i32 s38, s38, 2
	s_add_u32 s19, s19, 0x100
	s_addc_u32 s23, s23, 0
	s_cmp_gt_u32 s38, 13
	s_mov_b64 s[12:13], s[16:17]
	s_cbranch_scc0 .LBB0_1037
	s_and_b64 vcc, exec, s[14:15]
	s_cbranch_vccz .LBB0_1040
	s_barrier

; #define PG8_STAGE(bufoff, gbase, voff) do { const int so_ = (int)(unsigned)((const char*)(gbase) - base_##voff); _Pragma("unroll") for (int _i = 0; _i < 2; ++_i) \
;         __builtin_amdgcn_raw_ptr_buffer_load_lds(rs_##voff, (PG8_LAS unsigned*)(lds + (bufoff) + ldsw + _i * 8192), 16, (int)(voff)[_i], so_, 0, 0); } while (0)
; #define PG8_LDA(dst, b, h) do { _Pragma("unroll") for (int m = 0; m < 4; ++m) _Pragma("unroll") for (int k = 0; k < 2; ++k) dst[m][k] = *(const PG8_LAS bf16x8*)(lds + PG8_SA(b, h) + aoff + m * 2048 + k * 1024); } while (0)
; #define PG8_LDB(dst, b, h) do { _Pragma("unroll") for (int n = 0; n < 2; ++n) _Pragma("unroll") for (int k = 0; k < 2; ++k) dst[n][k] = *(const PG8_LAS bf16x8*)(lds + PG8_SB(b, h) + boff + n * 2048 + k * 1024); } while (0)
; #define PG8_MMA(ai, bj, At, Bt) do { __builtin_amdgcn_s_setprio(1); _Pragma("unroll") for (int m = 0; m < 4; ++m) _Pragma("unroll") for (int n = 0; n < 2; ++n) _Pragma("unroll") for (int k = 0; k < 2; ++k) \
;         acc[ai][bj][m][n] = __builtin_amdgcn_mfma_f32_16x16x32_bf16(Bt[n][k], At[m][k], acc[ai][bj][m][n], 0, 0, 0); __builtin_amdgcn_s_setprio(0); } while (0)
; #define PG8_WAIT_V(n) asm volatile("s_waitcnt vmcnt(" #n ")" ::: "memory")
; #define PG8_WAIT_L(n) asm volatile("s_waitcnt lgkmcnt(" #n ")" ::: "memory")
; #define PG8_BAR __builtin_amdgcn_s_barrier()
; #define PG8_SCHED __builtin_amdgcn_sched_barrier(0)
; template <class Epi, class Sched, bool ALIGN_EPI = false, bool SP2 = false>
; __device__ __forceinline__ void gemm_phase(PG8_LAS unsigned char* lds, const Gemm g, const Sched& S, const Epi& E, int tid_in) {
;     ...
;             PG8_LDB(B0, 0, 0); PG8_LDB(B1, 0, 1); PG8_SCHED; PG8_LDA(At, 0, 0); PG8_STAGE(PG8_SA(1, 1), a1 + hstepA, voffA);
;             PG8_WAIT_V(8); PG8_WAIT_L(0); PG8_BAR; PG8_MMA(0, 0, At, B0); PG8_MMA(0, 1, At, B1); PG8_BAR; PG8_SCHED;
;             PG8_LDA(At, 0, 1); PG8_STAGE(PG8_SB(0, 0), b2, voffB); PG8_STAGE(PG8_SB(0, 1), b2 + hstepB, voffB); PG8_STAGE(PG8_SA(0, 0), a2, voffA);
;             PG8_WAIT_V(8); PG8_WAIT_L(0); PG8_BAR; PG8_MMA(1, 0, At, B0); PG8_MMA(1, 1, At, B1); PG8_BAR; PG8_SCHED;
.LBB0_1265:
	v_add_u32_e32 v133, 0x10000, v131
	ds_read_b128 v[134:137], v133
	ds_read_b128 v[138:141], v133 offset:1024
	ds_read_b128 v[142:145], v133 offset:2048
	ds_read_b128 v[146:149], v133 offset:3072
	v_add_u32_e32 v133, 0x14000, v131
	ds_read_b128 v[150:153], v133
	ds_read_b128 v[154:157], v133 offset:1024
	ds_read_b128 v[158:161], v133 offset:2048
	ds_read_b128 v[166:169], v133 offset:3072
	s_add_i32 s42, s18, s44
	s_add_i32 s21, s14, s44
	s_add_i32 s79, s12, s44
	s_addk_i32 s42, 0xff80
	s_sub_i32 vcc_lo, s42, 0x80000
	s_cmp_eq_u32 s19, 28
	s_cselect_b32 s21, s15, s21
	s_mov_b32 m0, s75
	ds_read_b128 v[170:173], v132
	ds_read_b128 v[174:177], v132 offset:1024
	ds_read_b128 v[178:181], v132 offset:2048
	ds_read_b128 v[182:185], v132 offset:3072
	ds_read_b128 v[186:189], v132 offset:4096
	ds_read_b128 v[190:193], v132 offset:5120
	ds_read_b128 v[200:203], v132 offset:6144
	ds_read_b128 v[206:209], v132 offset:7168
	s_mov_b32 m0, s72
	s_nop 0
	buffer_load_dwordx4 v130, s[4:7], vcc_lo offen lds
	s_mov_b32 m0, s75
	s_nop 0
	buffer_load_dwordx4 v0, s[4:7], s42 offen lds
	s_mov_b32 m0, s76
	s_nop 0
	buffer_load_dwordx4 v130, s[4:7], s42 offen lds
	s_waitcnt vmcnt(8)
	s_waitcnt lgkmcnt(0)
	s_setprio 1
	s_barrier
	v_mfma_f32_16x16x32_bf16 v[34:37], v[134:137], v[170:173], v[34:37]
	v_mfma_f32_16x16x32_bf16 v[18:21], v[142:145], v[170:173], v[18:21]
	v_mfma_f32_16x16x32_bf16 v[78:81], v[142:145], v[178:181], v[78:81]
	v_mfma_f32_16x16x32_bf16 v[86:89], v[134:137], v[178:181], v[86:89]
	v_mfma_f32_16x16x32_bf16 v[106:109], v[134:137], v[186:189], v[106:109]
	v_mfma_f32_16x16x32_bf16 v[102:105], v[142:145], v[186:189], v[102:105]
	v_mfma_f32_16x16x32_bf16 v[122:125], v[142:145], v[200:203], v[122:125]
	v_mfma_f32_16x16x32_bf16 v[126:129], v[134:137], v[200:203], v[126:129]
	v_mfma_f32_16x16x32_bf16 v[34:37], v[138:141], v[174:177], v[34:37]
	v_mfma_f32_16x16x32_bf16 v[18:21], v[146:149], v[174:177], v[18:21]
	v_mfma_f32_16x16x32_bf16 v[78:81], v[146:149], v[182:185], v[78:81]
	v_mfma_f32_16x16x32_bf16 v[86:89], v[138:141], v[182:185], v[86:89]
	v_mfma_f32_16x16x32_bf16 v[106:109], v[138:141], v[190:193], v[106:109]
	v_mfma_f32_16x16x32_bf16 v[102:105], v[146:149], v[190:193], v[102:105]
	v_mfma_f32_16x16x32_bf16 v[122:125], v[146:149], v[206:209], v[122:125]
	v_mfma_f32_16x16x32_bf16 v[126:129], v[138:141], v[206:209], v[126:129]
	v_mfma_f32_16x16x32_bf16 v[14:17], v[150:153], v[170:173], v[14:17]
	v_mfma_f32_16x16x32_bf16 v[38:41], v[158:161], v[170:173], v[38:41]
	v_mfma_f32_16x16x32_bf16 v[90:93], v[158:161], v[178:181], v[90:93]
	v_mfma_f32_16x16x32_bf16 v[74:77], v[150:153], v[178:181], v[74:77]
	v_mfma_f32_16x16x32_bf16 v[98:101], v[150:153], v[186:189], v[98:101]
	v_mfma_f32_16x16x32_bf16 v[110:113], v[158:161], v[186:189], v[110:113]
	v_mfma_f32_16x16x32_bf16 v[114:117], v[158:161], v[200:203], v[114:117]
	v_mfma_f32_16x16x32_bf16 v[118:121], v[150:153], v[200:203], v[118:121]
	v_mfma_f32_16x16x32_bf16 v[14:17], v[154:157], v[174:177], v[14:17]
	v_mfma_f32_16x16x32_bf16 v[38:41], v[166:169], v[174:177], v[38:41]
	v_mfma_f32_16x16x32_bf16 v[90:93], v[166:169], v[182:185], v[90:93]
	v_mfma_f32_16x16x32_bf16 v[74:77], v[154:157], v[182:185], v[74:77]
	v_mfma_f32_16x16x32_bf16 v[98:101], v[154:157], v[190:193], v[98:101]
	v_mfma_f32_16x16x32_bf16 v[110:113], v[166:169], v[190:193], v[110:113]
	v_mfma_f32_16x16x32_bf16 v[114:117], v[166:169], v[206:209], v[114:117]
	v_mfma_f32_16x16x32_bf16 v[118:121], v[154:157], v[206:209], v[118:121]
	s_barrier
	s_setprio 0
	s_cselect_b32 s79, s17, s79
	s_mov_b32 m0, s49
	s_mov_b32 s42, s6
	s_mov_b32 s43, s7
	s_sub_i32 s79, s79, s40
	ds_read_b128 v[170:173], v132 offset:16384
	ds_read_b128 v[174:177], v132 offset:17408
	ds_read_b128 v[178:181], v132 offset:18432
	ds_read_b128 v[182:185], v132 offset:19456
	ds_read_b128 v[186:189], v132 offset:20480
	ds_read_b128 v[190:193], v132 offset:21504
	ds_read_b128 v[200:203], v132 offset:22528
	ds_read_b128 v[206:209], v132 offset:23552
	buffer_load_dwordx4 v0, s[40:43], s79 offen lds
	s_mov_b32 m0, s60
	s_add_i32 vcc_lo, s79, 0x80000
	buffer_load_dwordx4 v130, s[40:43], s79 offen lds
	s_mov_b32 m0, s61
	s_sub_i32 s21, s21, s4
	buffer_load_dwordx4 v0, s[40:43], vcc_lo offen lds
	s_mov_b32 m0, s62
	s_nop 0
	buffer_load_dwordx4 v130, s[40:43], vcc_lo offen lds
	s_mov_b32 m0, s35
	s_nop 0
	buffer_load_dwordx4 v0, s[4:7], s21 offen lds
	s_waitcnt vmcnt(7)
	s_waitcnt lgkmcnt(0)
	s_setprio 1
	s_barrier
	v_mfma_f32_16x16x32_bf16 v[50:53], v[134:137], v[170:173], v[50:53]
	v_mfma_f32_16x16x32_bf16 v[30:33], v[142:145], v[170:173], v[30:33]
	v_mfma_f32_16x16x32_bf16 v[58:61], v[142:145], v[178:181], v[58:61]
	v_mfma_f32_16x16x32_bf16 v[62:65], v[134:137], v[178:181], v[62:65]
	v_mfma_f32_16x16x32_bf16 v[94:97], v[134:137], v[186:189], v[94:97]
	v_mfma_f32_16x16x32_bf16 v[82:85], v[142:145], v[186:189], v[82:85]
	v_mfma_f32_16x16x32_bf16 v[26:29], v[142:145], v[200:203], v[26:29]
	v_mfma_f32_16x16x32_bf16 v[46:49], v[134:137], v[200:203], v[46:49]
	v_mfma_f32_16x16x32_bf16 v[50:53], v[138:141], v[174:177], v[50:53]
	v_mfma_f32_16x16x32_bf16 v[30:33], v[146:149], v[174:177], v[30:33]
	v_mfma_f32_16x16x32_bf16 v[58:61], v[146:149], v[182:185], v[58:61]
	v_mfma_f32_16x16x32_bf16 v[62:65], v[138:141], v[182:185], v[62:65]
	v_mfma_f32_16x16x32_bf16 v[94:97], v[138:141], v[190:193], v[94:97]
	v_mfma_f32_16x16x32_bf16 v[82:85], v[146:149], v[190:193], v[82:85]
	v_mfma_f32_16x16x32_bf16 v[26:29], v[146:149], v[206:209], v[26:29]
	v_mfma_f32_16x16x32_bf16 v[46:49], v[138:141], v[206:209], v[46:49]
	v_mfma_f32_16x16x32_bf16 v[22:25], v[150:153], v[170:173], v[22:25]
	v_mfma_f32_16x16x32_bf16 v[10:13], v[158:161], v[170:173], v[10:13]
	v_mfma_f32_16x16x32_bf16 v[66:69], v[158:161], v[178:181], v[66:69]
	v_mfma_f32_16x16x32_bf16 v[54:57], v[150:153], v[178:181], v[54:57]
	v_mfma_f32_16x16x32_bf16 v[70:73], v[150:153], v[186:189], v[70:73]
	v_mfma_f32_16x16x32_bf16 v[42:45], v[158:161], v[186:189], v[42:45]
	v_mfma_f32_16x16x32_bf16 v[2:5], v[158:161], v[200:203], v[2:5]
	v_mfma_f32_16x16x32_bf16 v[6:9], v[150:153], v[200:203], v[6:9]
	v_mfma_f32_16x16x32_bf16 v[22:25], v[154:157], v[174:177], v[22:25]
	v_mfma_f32_16x16x32_bf16 v[10:13], v[166:169], v[174:177], v[10:13]
	v_mfma_f32_16x16x32_bf16 v[66:69], v[166:169], v[182:185], v[66:69]
	v_mfma_f32_16x16x32_bf16 v[54:57], v[154:157], v[182:185], v[54:57]
	v_mfma_f32_16x16x32_bf16 v[70:73], v[154:157], v[190:193], v[70:73]
	v_mfma_f32_16x16x32_bf16 v[42:45], v[166:169], v[190:193], v[42:45]
	v_mfma_f32_16x16x32_bf16 v[2:5], v[166:169], v[206:209], v[2:5]
	v_mfma_f32_16x16x32_bf16 v[6:9], v[154:157], v[206:209], v[6:9]
	s_barrier
; #define PG8_STAGE(bufoff, gbase, voff) do { const int so_ = (int)(unsigned)((const char*)(gbase) - base_##voff); _Pragma("unroll") for (int _i = 0; _i < 2; ++_i) \
;         __builtin_amdgcn_raw_ptr_buffer_load_lds(rs_##voff, (PG8_LAS unsigned*)(lds + (bufoff) + ldsw + _i * 8192), 16, (int)(voff)[_i], so_, 0, 0); } while (0)
; #define PG8_LDA(dst, b, h) do { _Pragma("unroll") for (int m = 0; m < 4; ++m) _Pragma("unroll") for (int k = 0; k < 2; ++k) dst[m][k] = *(const PG8_LAS bf16x8*)(lds + PG8_SA(b, h) + aoff + m * 2048 + k * 1024); } while (0)
; #define PG8_LDB(dst, b, h) do { _Pragma("unroll") for (int n = 0; n < 2; ++n) _Pragma("unroll") for (int k = 0; k < 2; ++k) dst[n][k] = *(const PG8_LAS bf16x8*)(lds + PG8_SB(b, h) + boff + n * 2048 + k * 1024); } while (0)
; #define PG8_MMA(ai, bj, At, Bt) do { __builtin_amdgcn_s_setprio(1); _Pragma("unroll") for (int m = 0; m < 4; ++m) _Pragma("unroll") for (int n = 0; n < 2; ++n) _Pragma("unroll") for (int k = 0; k < 2; ++k) \
;         acc[ai][bj][m][n] = __builtin_amdgcn_mfma_f32_16x16x32_bf16(Bt[n][k], At[m][k], acc[ai][bj][m][n], 0, 0, 0); __builtin_amdgcn_s_setprio(0); } while (0)
; #define PG8_WAIT_V(n) asm volatile("s_waitcnt vmcnt(" #n ")" ::: "memory")
; #define PG8_WAIT_L(n) asm volatile("s_waitcnt lgkmcnt(" #n ")" ::: "memory")
; #define PG8_BAR __builtin_amdgcn_s_barrier()
; #define PG8_SCHED __builtin_amdgcn_sched_barrier(0)
; template <class Epi, class Sched, bool ALIGN_EPI = false, bool SP2 = false>
; __device__ __forceinline__ void gemm_phase(PG8_LAS unsigned char* lds, const Gemm g, const Sched& S, const Epi& E, int tid_in) {
;     ...
;             PG8_WAIT_V(8); PG8_WAIT_L(0); PG8_BAR; PG8_MMA(1, 0, At, B0); PG8_MMA(1, 1, At, B1); PG8_BAR; PG8_SCHED;
;             PG8_LDB(B0, 1, 0); PG8_LDB(B1, 1, 1); PG8_SCHED; PG8_LDA(At, 1, 0); PG8_STAGE(PG8_SA(0, 1), a2 + hstepA, voffA);
;             PG8_WAIT_V(8); PG8_WAIT_L(0); PG8_BAR; PG8_MMA(0, 0, At, B0); PG8_MMA(0, 1, At, B1); PG8_BAR; PG8_SCHED;
;             PG8_LDA(At, 1, 1); PG8_STAGE(PG8_SB(1, 0), b3, voffB); PG8_STAGE(PG8_SB(1, 1), b3 + hstepB, voffB); PG8_STAGE(PG8_SA(1, 0), a3, voffA);
	s_setprio 0
	v_add_u32_e32 v133, 0x18000, v131
	ds_read_b128 v[134:137], v133
	ds_read_b128 v[138:141], v133 offset:1024
	ds_read_b128 v[142:145], v133 offset:2048
	ds_read_b128 v[146:149], v133 offset:3072
	v_add_u32_e32 v133, 0x1c000, v131
	ds_read_b128 v[150:153], v133
	ds_read_b128 v[154:157], v133 offset:1024
	ds_read_b128 v[158:161], v133 offset:2048
	ds_read_b128 v[166:169], v133 offset:3072
	s_add_i32 vcc_lo, s21, 0x80000
	s_mov_b32 m0, s66
	ds_read_b128 v[170:173], v132 offset:32768
	ds_read_b128 v[174:177], v132 offset:33792
	ds_read_b128 v[178:181], v132 offset:34816
	ds_read_b128 v[182:185], v132 offset:35840
	ds_read_b128 v[186:189], v132 offset:36864
	ds_read_b128 v[190:193], v132 offset:37888
	ds_read_b128 v[200:203], v132 offset:38912
	ds_read_b128 v[206:209], v132 offset:39936
	s_mov_b32 m0, s63
	s_nop 0
	buffer_load_dwordx4 v130, s[4:7], s21 offen lds
	s_mov_b32 m0, s66
	s_nop 0
	buffer_load_dwordx4 v0, s[4:7], vcc_lo offen lds
	s_mov_b32 m0, s67
	s_nop 0
	buffer_load_dwordx4 v130, s[4:7], vcc_lo offen lds
	s_waitcnt vmcnt(8)
	s_waitcnt lgkmcnt(0)
	s_setprio 1
	s_barrier
	v_mfma_f32_16x16x32_bf16 v[34:37], v[134:137], v[170:173], v[34:37]
	v_mfma_f32_16x16x32_bf16 v[18:21], v[142:145], v[170:173], v[18:21]
	v_mfma_f32_16x16x32_bf16 v[78:81], v[142:145], v[178:181], v[78:81]
	v_mfma_f32_16x16x32_bf16 v[86:89], v[134:137], v[178:181], v[86:89]
	v_mfma_f32_16x16x32_bf16 v[106:109], v[134:137], v[186:189], v[106:109]
	v_mfma_f32_16x16x32_bf16 v[102:105], v[142:145], v[186:189], v[102:105]
	v_mfma_f32_16x16x32_bf16 v[122:125], v[142:145], v[200:203], v[122:125]
	v_mfma_f32_16x16x32_bf16 v[126:129], v[134:137], v[200:203], v[126:129]
	v_mfma_f32_16x16x32_bf16 v[34:37], v[138:141], v[174:177], v[34:37]
	v_mfma_f32_16x16x32_bf16 v[18:21], v[146:149], v[174:177], v[18:21]
	v_mfma_f32_16x16x32_bf16 v[78:81], v[146:149], v[182:185], v[78:81]
	v_mfma_f32_16x16x32_bf16 v[86:89], v[138:141], v[182:185], v[86:89]
	v_mfma_f32_16x16x32_bf16 v[106:109], v[138:141], v[190:193], v[106:109]
	v_mfma_f32_16x16x32_bf16 v[102:105], v[146:149], v[190:193], v[102:105]
	v_mfma_f32_16x16x32_bf16 v[122:125], v[146:149], v[206:209], v[122:125]
	v_mfma_f32_16x16x32_bf16 v[126:129], v[138:141], v[206:209], v[126:129]
	v_mfma_f32_16x16x32_bf16 v[14:17], v[150:153], v[170:173], v[14:17]
	v_mfma_f32_16x16x32_bf16 v[38:41], v[158:161], v[170:173], v[38:41]
	v_mfma_f32_16x16x32_bf16 v[90:93], v[158:161], v[178:181], v[90:93]
	v_mfma_f32_16x16x32_bf16 v[74:77], v[150:153], v[178:181], v[74:77]
	v_mfma_f32_16x16x32_bf16 v[98:101], v[150:153], v[186:189], v[98:101]
	v_mfma_f32_16x16x32_bf16 v[110:113], v[158:161], v[186:189], v[110:113]
	v_mfma_f32_16x16x32_bf16 v[114:117], v[158:161], v[200:203], v[114:117]
	v_mfma_f32_16x16x32_bf16 v[118:121], v[150:153], v[200:203], v[118:121]
	v_mfma_f32_16x16x32_bf16 v[14:17], v[154:157], v[174:177], v[14:17]
	v_mfma_f32_16x16x32_bf16 v[38:41], v[166:169], v[174:177], v[38:41]
	v_mfma_f32_16x16x32_bf16 v[90:93], v[166:169], v[182:185], v[90:93]
	v_mfma_f32_16x16x32_bf16 v[74:77], v[154:157], v[182:185], v[74:77]
	v_mfma_f32_16x16x32_bf16 v[98:101], v[154:157], v[190:193], v[98:101]
	v_mfma_f32_16x16x32_bf16 v[110:113], v[166:169], v[190:193], v[110:113]
	v_mfma_f32_16x16x32_bf16 v[114:117], v[166:169], v[206:209], v[114:117]
	v_mfma_f32_16x16x32_bf16 v[118:121], v[154:157], v[206:209], v[118:121]
	s_barrier
	s_setprio 0
	s_mov_b32 m0, s68
	s_add_i32 vcc_lo, s79, 0x80
	ds_read_b128 v[170:173], v132 offset:49152
	ds_read_b128 v[174:177], v132 offset:50176
	ds_read_b128 v[178:181], v132 offset:51200
	ds_read_b128 v[182:185], v132 offset:52224
	ds_read_b128 v[186:189], v132 offset:53248
	ds_read_b128 v[190:193], v132 offset:54272
	ds_read_b128 v[200:203], v132 offset:55296
	ds_read_b128 v[206:209], v132 offset:56320
	buffer_load_dwordx4 v0, s[40:43], vcc_lo offen lds
	s_mov_b32 m0, s69
	s_add_i32 s79, s79, 0x80080
	buffer_load_dwordx4 v130, s[40:43], vcc_lo offen lds
	s_mov_b32 m0, s73
	s_addk_i32 s21, 0x80
	buffer_load_dwordx4 v0, s[40:43], s79 offen lds
	s_mov_b32 m0, s74
	s_nop 0
	buffer_load_dwordx4 v130, s[40:43], s79 offen lds
	s_mov_b32 m0, s71
	s_nop 0
	buffer_load_dwordx4 v0, s[4:7], s21 offen lds
	s_waitcnt vmcnt(7)
	s_waitcnt lgkmcnt(0)
	s_setprio 1
	s_barrier
;     static __device__ __forceinline__ bool last_of_chain(const Unit& u) { return (u.pn >> 3) == 2; }
; template <class Epi, class Sched, bool ALIGN_EPI = false, bool SP2 = false>
; __device__ __forceinline__ void gemm_phase(PG8_LAS unsigned char* lds, const Gemm g, const Sched& S, const Epi& E, int tid_in) {
;     ...
;             PG8_WAIT_V(8); PG8_WAIT_L(0); PG8_BAR; PG8_MMA(1, 0, At, B0); PG8_MMA(1, 1, At, B1); PG8_BAR; PG8_SCHED;
;             } else {
;             PG8_LDB(B0, 0, 0); PG8_SCHED; PG8_LDA(At, 0, 0); PG8_STAGE(PG8_SA(1, 1), a1 + hstepA, voffA);
;             PG8_WAIT_L(8); PG8_BAR; PG8_WAIT_L(0); PG8_MMA(0, 0, At, B0); PG8_BAR; PG8_SCHED;
;             PG8_LDB(B1, 0, 1); PG8_STAGE(PG8_SB(0, 0), b2, voffB);
;             PG8_BAR; PG8_WAIT_L(0); PG8_MMA(0, 1, At, B1); PG8_BAR;
;             PG8_LDA(At, 0, 1); PG8_STAGE(PG8_SA(0, 0), a2, voffA);
;             PG8_BAR; PG8_WAIT_L(0); PG8_MMA(1, 0, At, B0); PG8_BAR; PG8_SCHED;
;             PG8_STAGE(PG8_SB(0, 1), b2 + hstepB, voffB);
;             PG8_WAIT_V(6); PG8_BAR; PG8_MMA(1, 1, At, B1); PG8_BAR;
;             PG8_LDB(B0, 1, 0); PG8_SCHED; PG8_LDA(At, 1, 0); PG8_STAGE(PG8_SA(0, 1), a2 + hstepA, voffA);
;             PG8_WAIT_L(8); PG8_BAR; PG8_WAIT_L(0); PG8_MMA(0, 0, At, B0); PG8_BAR; PG8_SCHED;
;             PG8_LDB(B1, 1, 1); PG8_STAGE(PG8_SB(1, 0), b3, voffB);
;             PG8_BAR; PG8_WAIT_L(0); PG8_MMA(0, 1, At, B1); PG8_BAR;
;             PG8_LDA(At, 1, 1); PG8_STAGE(PG8_SA(1, 0), a3, voffA);
;             PG8_BAR; PG8_WAIT_L(0); PG8_MMA(1, 0, At, B0); PG8_BAR; PG8_SCHED;
;             PG8_STAGE(PG8_SB(1, 1), b3 + hstepB, voffB);
;             PG8_WAIT_V(6); PG8_BAR; PG8_MMA(1, 1, At, B1); PG8_BAR;
;             }
;         }
;         if constexpr (ALIGN_EPI) { if (wr == 0) PG8_BAR; }
;         if constexpr (!Epi::AFTER_DRAIN) { E(acc, cur, wr, wc, fr, fq); S.done(cur); }
;         if (!has_next) break;
;         bool zero_acc = true; if constexpr (Epi::CHAIN) zero_acc = Epi::last_of_chain(cur);
;         if (zero_acc) {
; #pragma unroll
;         for (int a = 0; a < 2; ++a)
; #pragma unroll
;             for (int b = 0; b < 2; ++b)
; #pragma unroll
;                 for (int m = 0; m < 4; ++m)
; #pragma unroll
;                     for (int n = 0; n < 2; ++n) acc[a][b][m][n] = (f32x4){0.f, 0.f, 0.f, 0.f};
;         }
;         cur = nxt; cA = nA; cB = nB; ++ui;
	v_mfma_f32_16x16x32_bf16 v[50:53], v[134:137], v[170:173], v[50:53]
	v_mfma_f32_16x16x32_bf16 v[30:33], v[142:145], v[170:173], v[30:33]
	v_mfma_f32_16x16x32_bf16 v[58:61], v[142:145], v[178:181], v[58:61]
	v_mfma_f32_16x16x32_bf16 v[62:65], v[134:137], v[178:181], v[62:65]
	v_mfma_f32_16x16x32_bf16 v[94:97], v[134:137], v[186:189], v[94:97]
	v_mfma_f32_16x16x32_bf16 v[82:85], v[142:145], v[186:189], v[82:85]
	v_mfma_f32_16x16x32_bf16 v[26:29], v[142:145], v[200:203], v[26:29]
	v_mfma_f32_16x16x32_bf16 v[46:49], v[134:137], v[200:203], v[46:49]
	v_mfma_f32_16x16x32_bf16 v[50:53], v[138:141], v[174:177], v[50:53]
	v_mfma_f32_16x16x32_bf16 v[30:33], v[146:149], v[174:177], v[30:33]
	v_mfma_f32_16x16x32_bf16 v[58:61], v[146:149], v[182:185], v[58:61]
	v_mfma_f32_16x16x32_bf16 v[62:65], v[138:141], v[182:185], v[62:65]
	v_mfma_f32_16x16x32_bf16 v[94:97], v[138:141], v[190:193], v[94:97]
	v_mfma_f32_16x16x32_bf16 v[82:85], v[146:149], v[190:193], v[82:85]
	v_mfma_f32_16x16x32_bf16 v[26:29], v[146:149], v[206:209], v[26:29]
	v_mfma_f32_16x16x32_bf16 v[46:49], v[138:141], v[206:209], v[46:49]
	v_mfma_f32_16x16x32_bf16 v[22:25], v[150:153], v[170:173], v[22:25]
	v_mfma_f32_16x16x32_bf16 v[10:13], v[158:161], v[170:173], v[10:13]
	v_mfma_f32_16x16x32_bf16 v[66:69], v[158:161], v[178:181], v[66:69]
	v_mfma_f32_16x16x32_bf16 v[54:57], v[150:153], v[178:181], v[54:57]
	v_mfma_f32_16x16x32_bf16 v[70:73], v[150:153], v[186:189], v[70:73]
	v_mfma_f32_16x16x32_bf16 v[42:45], v[158:161], v[186:189], v[42:45]
	v_mfma_f32_16x16x32_bf16 v[2:5], v[158:161], v[200:203], v[2:5]
	v_mfma_f32_16x16x32_bf16 v[6:9], v[150:153], v[200:203], v[6:9]
	v_mfma_f32_16x16x32_bf16 v[22:25], v[154:157], v[174:177], v[22:25]
	v_mfma_f32_16x16x32_bf16 v[10:13], v[166:169], v[174:177], v[10:13]
	v_mfma_f32_16x16x32_bf16 v[66:69], v[166:169], v[182:185], v[66:69]
	v_mfma_f32_16x16x32_bf16 v[54:57], v[154:157], v[182:185], v[54:57]
	v_mfma_f32_16x16x32_bf16 v[70:73], v[154:157], v[190:193], v[70:73]
	v_mfma_f32_16x16x32_bf16 v[42:45], v[166:169], v[190:193], v[42:45]
	v_mfma_f32_16x16x32_bf16 v[2:5], v[166:169], v[206:209], v[2:5]
	v_mfma_f32_16x16x32_bf16 v[6:9], v[154:157], v[206:209], v[6:9]
	s_barrier
	s_setprio 0
	s_add_i32 s19, s19, 2
	s_add_u32 s44, s44, 0x100
	s_addc_u32 s45, s45, 0
	s_cmp_gt_u32 s19, 29
	s_cbranch_scc0 .LBB0_1265
	s_andn2_b64 vcc, exec, s[38:39]
	s_cbranch_vccnz .LBB0_1257
	v_mov_b32_e32 v2, 0
	s_mov_b64 s[12:13], s[24:25]
	s_mov_b32 s10, s16
	s_mov_b32 s48, s20
	s_mov_b64 s[14:15], s[22:23]
	s_mov_b32 s13, s78
	v_mov_b32_e32 v3, v2
	v_mov_b32_e32 v4, v2
	v_mov_b32_e32 v5, v2
	v_mov_b32_e32 v6, v2
	v_mov_b32_e32 v7, v2
	v_mov_b32_e32 v8, v2
	v_mov_b32_e32 v9, v2
	v_mov_b32_e32 v42, v2
	v_mov_b32_e32 v43, v2
	v_mov_b32_e32 v44, v2
	v_mov_b32_e32 v45, v2
	v_mov_b32_e32 v70, v2
	v_mov_b32_e32 v71, v2
	v_mov_b32_e32 v72, v2
	v_mov_b32_e32 v73, v2
	v_mov_b32_e32 v66, v2
	v_mov_b32_e32 v67, v2
	v_mov_b32_e32 v68, v2
	v_mov_b32_e32 v69, v2
	v_mov_b32_e32 v54, v2
	v_mov_b32_e32 v55, v2
	v_mov_b32_e32 v56, v2
	v_mov_b32_e32 v57, v2
	v_mov_b32_e32 v10, v2
	v_mov_b32_e32 v11, v2
	v_mov_b32_e32 v12, v2
	v_mov_b32_e32 v13, v2
	v_mov_b32_e32 v22, v2
	v_mov_b32_e32 v23, v2
	v_mov_b32_e32 v24, v2
	v_mov_b32_e32 v25, v2
	v_mov_b32_e32 v26, v2
	v_mov_b32_e32 v27, v2
	v_mov_b32_e32 v28, v2
	v_mov_b32_e32 v29, v2
	v_mov_b32_e32 v46, v2
	v_mov_b32_e32 v47, v2
	v_mov_b32_e32 v48, v2
	v_mov_b32_e32 v49, v2
	v_mov_b32_e32 v82, v2
	v_mov_b32_e32 v83, v2
	v_mov_b32_e32 v84, v2
	v_mov_b32_e32 v85, v2
	v_mov_b32_e32 v94, v2
	v_mov_b32_e32 v95, v2
	v_mov_b32_e32 v96, v2
	v_mov_b32_e32 v97, v2
	v_mov_b32_e32 v58, v2
	v_mov_b32_e32 v59, v2
	v_mov_b32_e32 v60, v2
	v_mov_b32_e32 v61, v2
	v_mov_b32_e32 v62, v2
	v_mov_b32_e32 v63, v2
	v_mov_b32_e32 v64, v2
	v_mov_b32_e32 v65, v2
	v_mov_b32_e32 v30, v2
	v_mov_b32_e32 v31, v2
	v_mov_b32_e32 v32, v2
	v_mov_b32_e32 v33, v2
	v_mov_b32_e32 v50, v2
	v_mov_b32_e32 v51, v2
	v_mov_b32_e32 v52, v2
	v_mov_b32_e32 v53, v2
	v_mov_b32_e32 v114, v2
	v_mov_b32_e32 v115, v2
	v_mov_b32_e32 v116, v2
	v_mov_b32_e32 v117, v2
	v_mov_b32_e32 v118, v2
	v_mov_b32_e32 v119, v2
	v_mov_b32_e32 v120, v2
	v_mov_b32_e32 v121, v2
	v_mov_b32_e32 v110, v2
	v_mov_b32_e32 v111, v2
	v_mov_b32_e32 v112, v2
	v_mov_b32_e32 v113, v2
	v_mov_b32_e32 v98, v2
	v_mov_b32_e32 v99, v2
	v_mov_b32_e32 v100, v2
	v_mov_b32_e32 v101, v2
	v_mov_b32_e32 v90, v2
	v_mov_b32_e32 v91, v2
	v_mov_b32_e32 v92, v2
	v_mov_b32_e32 v93, v2
	v_mov_b32_e32 v74, v2
	v_mov_b32_e32 v75, v2
	v_mov_b32_e32 v76, v2
	v_mov_b32_e32 v77, v2
	v_mov_b32_e32 v38, v2
	v_mov_b32_e32 v39, v2
	v_mov_b32_e32 v40, v2
	v_mov_b32_e32 v41, v2
	v_mov_b32_e32 v14, v2
	v_mov_b32_e32 v15, v2
	v_mov_b32_e32 v16, v2
	v_mov_b32_e32 v17, v2
	v_mov_b32_e32 v122, v2
	v_mov_b32_e32 v123, v2
	v_mov_b32_e32 v124, v2
	v_mov_b32_e32 v125, v2
	v_mov_b32_e32 v126, v2
	v_mov_b32_e32 v127, v2
	v_mov_b32_e32 v128, v2
	v_mov_b32_e32 v129, v2
	v_mov_b32_e32 v102, v2
	v_mov_b32_e32 v103, v2
	v_mov_b32_e32 v104, v2
	v_mov_b32_e32 v105, v2
	v_mov_b32_e32 v106, v2
	v_mov_b32_e32 v107, v2
	v_mov_b32_e32 v108, v2
	v_mov_b32_e32 v109, v2
	v_mov_b32_e32 v78, v2
	v_mov_b32_e32 v79, v2
	v_mov_b32_e32 v80, v2
	v_mov_b32_e32 v81, v2
	v_mov_b32_e32 v86, v2
	v_mov_b32_e32 v87, v2
	v_mov_b32_e32 v88, v2
	v_mov_b32_e32 v89, v2
	v_mov_b32_e32 v18, v2
	v_mov_b32_e32 v19, v2
	v_mov_b32_e32 v20, v2
	v_mov_b32_e32 v21, v2
	v_mov_b32_e32 v34, v2
	v_mov_b32_e32 v35, v2
	v_mov_b32_e32 v36, v2
	v_mov_b32_e32 v37, v2
	s_branch .LBB0_1257

;     __host__ __device__ bool next(int i, Unit& u) const { const int t = i / 3, b = i - 3 * t; Unit v; if (!StaticOrder::next(t, v)) return false; u.pm = v.pm; u.pn = 8 * b + v.pn; return true; }
; #define PG8_STAGE(bufoff, gbase, voff) do { const int so_ = (int)(unsigned)((const char*)(gbase) - base_##voff); _Pragma("unroll") for (int _i = 0; _i < 2; ++_i) \
;         __builtin_amdgcn_raw_ptr_buffer_load_lds(rs_##voff, (PG8_LAS unsigned*)(lds + (bufoff) + ldsw + _i * 8192), 16, (int)(voff)[_i], so_, 0, 0); } while (0)
; #define PG8_LDA(dst, b, h) do { _Pragma("unroll") for (int m = 0; m < 4; ++m) _Pragma("unroll") for (int k = 0; k < 2; ++k) dst[m][k] = *(const PG8_LAS bf16x8*)(lds + PG8_SA(b, h) + aoff + m * 2048 + k * 1024); } while (0)
; #define PG8_WAIT_V(n) asm volatile("s_waitcnt vmcnt(" #n ")" ::: "memory")
; #define PG8_WAIT_L(n) asm volatile("s_waitcnt lgkmcnt(" #n ")" ::: "memory")
; #define PG8_BAR __builtin_amdgcn_s_barrier()
; template <class Epi, class Sched, bool ALIGN_EPI = false, bool SP2 = false>
; __device__ __forceinline__ void gemm_phase(PG8_LAS unsigned char* lds, const Gemm g, const Sched& S, const Epi& E, int tid_in) {
;     ...
;         const bool has_next = S.next(ui + 1, nxt);
;         const char* nA = has_next ? (const char*)g.A + (size_t)nxt.pm * tstepA + (g.grp ? (size_t)(nxt.pn / g.grp) * g.agrp : (size_t)0) : cA; const char* nB = has_next ? (const char*)g.Bt + (size_t)nxt.pn * tstepB : cB;
;         for (int t = 0; t < nt; t += 2) {
;             const bool last = (t == nt - 2);
;             const char* a1 = cA + (size_t)(t + 1) * kstep;
;             const char* a2 = last ? nA : cA + (size_t)(t + 2) * kstep; const char* b2 = last ? nB : cB + (size_t)(t + 2) * kstep;
;             const char* a3 = a2 + kstep; const char* b3 = b2 + kstep;
;             if (last && has_next) S.a_ready(nxt);
;             if constexpr (SP2) {
;             PG8_LDB(B0, 0, 0); PG8_LDB(B1, 0, 1); PG8_SCHED; PG8_LDA(At, 0, 0); PG8_STAGE(PG8_SA(1, 1), a1 + hstepA, voffA);
;             PG8_WAIT_V(8); PG8_WAIT_L(0); PG8_BAR; PG8_MMA(0, 0, At, B0); PG8_MMA(0, 1, At, B1); PG8_BAR; PG8_SCHED;
;             PG8_LDA(At, 0, 1); PG8_STAGE(PG8_SB(0, 0), b2, voffB); PG8_STAGE(PG8_SB(0, 1), b2 + hstepB, voffB); PG8_STAGE(PG8_SA(0, 0), a2, voffA);
;             PG8_WAIT_V(8); PG8_WAIT_L(0); PG8_BAR; PG8_MMA(1, 0, At, B0); PG8_MMA(1, 1, At, B1); PG8_BAR; PG8_SCHED;
.LBB0_1513:
	s_ashr_i32 s21, s20, 31
	s_lshl_b64 s[18:19], s[20:21], 20
	s_add_u32 s22, s4, s18
	s_addc_u32 s23, s9, s19
	s_and_b64 s[18:19], s[36:37], exec
	s_cselect_b32 s18, s22, s16
	s_ashr_i32 s15, s14, 31
	s_lshl_b64 s[24:25], s[14:15], 20
	s_add_u32 s24, s40, s24
	s_addc_u32 s25, s26, s25
	s_and_b64 s[42:43], s[36:37], exec
	s_cselect_b32 s15, s24, s38
	s_add_u32 s19, s38, 0x100
	v_mov_b32_e32 v2, 0
	s_addc_u32 s21, s39, 0
	s_mov_b32 s73, -2
	v_add_u32_e32 v141, 0x10000, v139
	ds_read_b128 v[130:133], v141
	ds_read_b128 v[142:145], v141 offset:1024
	ds_read_b128 v[146:149], v141 offset:2048
	ds_read_b128 v[150:153], v141 offset:3072
	v_add_u32_e32 v141, 0x14000, v139
	ds_read_b128 v[154:157], v141
	ds_read_b128 v[158:161], v141 offset:1024
	ds_read_b128 v[162:165], v141 offset:2048
	ds_read_b128 v[166:169], v141 offset:3072
	s_add_u32 s38, s16, 0x100
	s_addc_u32 s39, s17, 0
	s_sub_i32 s16, s16, s4
	s_add_i32 s16, s16, 0x80080
	s_sub_i32 s74, s16, 0x80000
	s_cmp_eq_u32 s73, 28
	s_cselect_b32 s17, s18, s38
	s_mov_b32 m0, s67
	ds_read_b128 v[170:173], v140
	ds_read_b128 v[174:177], v140 offset:1024
	ds_read_b128 v[178:181], v140 offset:2048
	ds_read_b128 v[182:185], v140 offset:3072
	ds_read_b128 v[186:189], v140 offset:4096
	ds_read_b128 v[190:193], v140 offset:5120
	ds_read_b128 v[200:203], v140 offset:6144
	ds_read_b128 v[206:209], v140 offset:7168
	s_mov_b32 m0, s62
	s_nop 0
	buffer_load_dwordx4 v135, s[4:7], s74 offen lds
	s_mov_b32 m0, s67
	s_nop 0
	buffer_load_dwordx4 v0, s[4:7], s16 offen lds
	s_mov_b32 m0, s68
	s_nop 0
	buffer_load_dwordx4 v135, s[4:7], s16 offen lds
	s_waitcnt vmcnt(8)
	s_waitcnt lgkmcnt(0)
	s_setprio 1
	s_barrier
	v_mfma_f32_16x16x32_bf16 v[126:129], v[130:133], v[170:173], 0
	v_mfma_f32_16x16x32_bf16 v[122:125], v[146:149], v[170:173], 0
	v_mfma_f32_16x16x32_bf16 v[106:109], v[146:149], v[178:181], 0
	v_mfma_f32_16x16x32_bf16 v[110:113], v[130:133], v[178:181], 0
	v_mfma_f32_16x16x32_bf16 v[94:97], v[130:133], v[186:189], 0
	v_mfma_f32_16x16x32_bf16 v[90:93], v[146:149], v[186:189], 0
	v_mfma_f32_16x16x32_bf16 v[74:77], v[146:149], v[200:203], 0
	v_mfma_f32_16x16x32_bf16 v[78:81], v[130:133], v[200:203], 0
	v_mfma_f32_16x16x32_bf16 v[126:129], v[142:145], v[174:177], v[126:129]
	v_mfma_f32_16x16x32_bf16 v[122:125], v[150:153], v[174:177], v[122:125]
	v_mfma_f32_16x16x32_bf16 v[106:109], v[150:153], v[182:185], v[106:109]
	v_mfma_f32_16x16x32_bf16 v[110:113], v[142:145], v[182:185], v[110:113]
	v_mfma_f32_16x16x32_bf16 v[94:97], v[142:145], v[190:193], v[94:97]
	v_mfma_f32_16x16x32_bf16 v[90:93], v[150:153], v[190:193], v[90:93]
	v_mfma_f32_16x16x32_bf16 v[74:77], v[150:153], v[206:209], v[74:77]
	v_mfma_f32_16x16x32_bf16 v[78:81], v[142:145], v[206:209], v[78:81]
	v_mfma_f32_16x16x32_bf16 v[118:121], v[154:157], v[170:173], 0
	v_mfma_f32_16x16x32_bf16 v[114:117], v[162:165], v[170:173], 0
	v_mfma_f32_16x16x32_bf16 v[98:101], v[162:165], v[178:181], 0
	v_mfma_f32_16x16x32_bf16 v[102:105], v[154:157], v[178:181], 0
	v_mfma_f32_16x16x32_bf16 v[86:89], v[154:157], v[186:189], 0
	v_mfma_f32_16x16x32_bf16 v[82:85], v[162:165], v[186:189], 0
	v_mfma_f32_16x16x32_bf16 v[66:69], v[162:165], v[200:203], 0
	v_mfma_f32_16x16x32_bf16 v[70:73], v[154:157], v[200:203], 0
	v_mfma_f32_16x16x32_bf16 v[118:121], v[158:161], v[174:177], v[118:121]
	v_mfma_f32_16x16x32_bf16 v[114:117], v[166:169], v[174:177], v[114:117]
	v_mfma_f32_16x16x32_bf16 v[98:101], v[166:169], v[182:185], v[98:101]
	v_mfma_f32_16x16x32_bf16 v[102:105], v[158:161], v[182:185], v[102:105]
	v_mfma_f32_16x16x32_bf16 v[86:89], v[158:161], v[190:193], v[86:89]
	v_mfma_f32_16x16x32_bf16 v[82:85], v[166:169], v[190:193], v[82:85]
	v_mfma_f32_16x16x32_bf16 v[66:69], v[166:169], v[206:209], v[66:69]
	v_mfma_f32_16x16x32_bf16 v[70:73], v[158:161], v[206:209], v[70:73]
	s_barrier
	s_setprio 0
	s_cselect_b32 s16, s15, s19
	s_mov_b32 m0, s35
	s_mov_b32 s42, s6
	s_mov_b32 s43, s7
	s_sub_i32 s16, s16, s40
	ds_read_b128 v[170:173], v140 offset:16384
	ds_read_b128 v[174:177], v140 offset:17408
	ds_read_b128 v[178:181], v140 offset:18432
	ds_read_b128 v[182:185], v140 offset:19456
	ds_read_b128 v[186:189], v140 offset:20480
	ds_read_b128 v[190:193], v140 offset:21504
	ds_read_b128 v[200:203], v140 offset:22528
	ds_read_b128 v[206:209], v140 offset:23552
	buffer_load_dwordx4 v134, s[40:43], s16 offen lds
	s_mov_b32 m0, s44
	s_add_i32 s74, s16, 0x80000
	buffer_load_dwordx4 v136, s[40:43], s16 offen lds
	s_mov_b32 m0, s45
	s_sub_i32 s17, s17, s4
	buffer_load_dwordx4 v134, s[40:43], s74 offen lds
	s_mov_b32 m0, s46
	s_nop 0
	buffer_load_dwordx4 v136, s[40:43], s74 offen lds
	s_mov_b32 m0, s34
	s_nop 0
	buffer_load_dwordx4 v0, s[4:7], s17 offen lds
	s_waitcnt vmcnt(7)
	s_waitcnt lgkmcnt(0)
	s_setprio 1
	s_barrier
; #define PG8_STAGE(bufoff, gbase, voff) do { const int so_ = (int)(unsigned)((const char*)(gbase) - base_##voff); _Pragma("unroll") for (int _i = 0; _i < 2; ++_i) \
;         __builtin_amdgcn_raw_ptr_buffer_load_lds(rs_##voff, (PG8_LAS unsigned*)(lds + (bufoff) + ldsw + _i * 8192), 16, (int)(voff)[_i], so_, 0, 0); } while (0)
; #define PG8_LDA(dst, b, h) do { _Pragma("unroll") for (int m = 0; m < 4; ++m) _Pragma("unroll") for (int k = 0; k < 2; ++k) dst[m][k] = *(const PG8_LAS bf16x8*)(lds + PG8_SA(b, h) + aoff + m * 2048 + k * 1024); } while (0)
; #define PG8_LDB(dst, b, h) do { _Pragma("unroll") for (int n = 0; n < 2; ++n) _Pragma("unroll") for (int k = 0; k < 2; ++k) dst[n][k] = *(const PG8_LAS bf16x8*)(lds + PG8_SB(b, h) + boff + n * 2048 + k * 1024); } while (0)
; #define PG8_MMA(ai, bj, At, Bt) do { __builtin_amdgcn_s_setprio(1); _Pragma("unroll") for (int m = 0; m < 4; ++m) _Pragma("unroll") for (int n = 0; n < 2; ++n) _Pragma("unroll") for (int k = 0; k < 2; ++k) \
;         acc[ai][bj][m][n] = __builtin_amdgcn_mfma_f32_16x16x32_bf16(Bt[n][k], At[m][k], acc[ai][bj][m][n], 0, 0, 0); __builtin_amdgcn_s_setprio(0); } while (0)
; #define PG8_WAIT_V(n) asm volatile("s_waitcnt vmcnt(" #n ")" ::: "memory")
; #define PG8_WAIT_L(n) asm volatile("s_waitcnt lgkmcnt(" #n ")" ::: "memory")
; #define PG8_BAR __builtin_amdgcn_s_barrier()
; #define PG8_SCHED __builtin_amdgcn_sched_barrier(0)
; template <class Epi, class Sched, bool ALIGN_EPI = false, bool SP2 = false>
; __device__ __forceinline__ void gemm_phase(PG8_LAS unsigned char* lds, const Gemm g, const Sched& S, const Epi& E, int tid_in) {
;     ...
;             PG8_WAIT_V(8); PG8_WAIT_L(0); PG8_BAR; PG8_MMA(1, 0, At, B0); PG8_MMA(1, 1, At, B1); PG8_BAR; PG8_SCHED;
;             PG8_LDB(B0, 1, 0); PG8_LDB(B1, 1, 1); PG8_SCHED; PG8_LDA(At, 1, 0); PG8_STAGE(PG8_SA(0, 1), a2 + hstepA, voffA);
;             PG8_WAIT_V(8); PG8_WAIT_L(0); PG8_BAR; PG8_MMA(0, 0, At, B0); PG8_MMA(0, 1, At, B1); PG8_BAR; PG8_SCHED;
	v_mfma_f32_16x16x32_bf16 v[62:65], v[130:133], v[170:173], 0
	v_mfma_f32_16x16x32_bf16 v[58:61], v[146:149], v[170:173], 0
	v_mfma_f32_16x16x32_bf16 v[42:45], v[146:149], v[178:181], 0
	v_mfma_f32_16x16x32_bf16 v[46:49], v[130:133], v[178:181], 0
	v_mfma_f32_16x16x32_bf16 v[30:33], v[130:133], v[186:189], 0
	v_mfma_f32_16x16x32_bf16 v[26:29], v[146:149], v[186:189], 0
	v_mfma_f32_16x16x32_bf16 v[10:13], v[146:149], v[200:203], 0
	v_mfma_f32_16x16x32_bf16 v[14:17], v[130:133], v[200:203], 0
	v_mfma_f32_16x16x32_bf16 v[62:65], v[142:145], v[174:177], v[62:65]
	v_mfma_f32_16x16x32_bf16 v[58:61], v[150:153], v[174:177], v[58:61]
	v_mfma_f32_16x16x32_bf16 v[42:45], v[150:153], v[182:185], v[42:45]
	v_mfma_f32_16x16x32_bf16 v[46:49], v[142:145], v[182:185], v[46:49]
	v_mfma_f32_16x16x32_bf16 v[30:33], v[142:145], v[190:193], v[30:33]
	v_mfma_f32_16x16x32_bf16 v[26:29], v[150:153], v[190:193], v[26:29]
	v_mfma_f32_16x16x32_bf16 v[10:13], v[150:153], v[206:209], v[10:13]
	v_mfma_f32_16x16x32_bf16 v[14:17], v[142:145], v[206:209], v[14:17]
	v_mfma_f32_16x16x32_bf16 v[54:57], v[154:157], v[170:173], 0
	v_mfma_f32_16x16x32_bf16 v[50:53], v[162:165], v[170:173], 0
	v_mfma_f32_16x16x32_bf16 v[34:37], v[162:165], v[178:181], 0
	v_mfma_f32_16x16x32_bf16 v[38:41], v[154:157], v[178:181], 0
	v_mfma_f32_16x16x32_bf16 v[22:25], v[154:157], v[186:189], 0
	v_mfma_f32_16x16x32_bf16 v[18:21], v[162:165], v[186:189], 0
	v_mfma_f32_16x16x32_bf16 v[2:5], v[162:165], v[200:203], 0
	v_mfma_f32_16x16x32_bf16 v[6:9], v[154:157], v[200:203], 0
	v_mfma_f32_16x16x32_bf16 v[54:57], v[158:161], v[174:177], v[54:57]
	v_mfma_f32_16x16x32_bf16 v[50:53], v[166:169], v[174:177], v[50:53]
	v_mfma_f32_16x16x32_bf16 v[34:37], v[166:169], v[182:185], v[34:37]
	v_mfma_f32_16x16x32_bf16 v[38:41], v[158:161], v[182:185], v[38:41]
	v_mfma_f32_16x16x32_bf16 v[22:25], v[158:161], v[190:193], v[22:25]
	v_mfma_f32_16x16x32_bf16 v[18:21], v[166:169], v[190:193], v[18:21]
	v_mfma_f32_16x16x32_bf16 v[2:5], v[166:169], v[206:209], v[2:5]
	v_mfma_f32_16x16x32_bf16 v[6:9], v[158:161], v[206:209], v[6:9]
	s_barrier
	s_setprio 0
	v_add_u32_e32 v141, 0x18000, v139
	ds_read_b128 v[130:133], v141
	ds_read_b128 v[142:145], v141 offset:1024
	ds_read_b128 v[146:149], v141 offset:2048
	ds_read_b128 v[150:153], v141 offset:3072
	v_add_u32_e32 v141, 0x1c000, v139
	ds_read_b128 v[154:157], v141
	ds_read_b128 v[158:161], v141 offset:1024
	ds_read_b128 v[162:165], v141 offset:2048
	ds_read_b128 v[166:169], v141 offset:3072
	s_add_i32 s74, s17, 0x80000
	s_mov_b32 m0, s48
	ds_read_b128 v[170:173], v140 offset:32768
	ds_read_b128 v[174:177], v140 offset:33792
	ds_read_b128 v[178:181], v140 offset:34816
	ds_read_b128 v[182:185], v140 offset:35840
	ds_read_b128 v[186:189], v140 offset:36864
	ds_read_b128 v[190:193], v140 offset:37888
	ds_read_b128 v[200:203], v140 offset:38912
	ds_read_b128 v[206:209], v140 offset:39936
	s_mov_b32 m0, s47
	s_nop 0
	buffer_load_dwordx4 v135, s[4:7], s17 offen lds
	s_mov_b32 m0, s48
	s_nop 0
	buffer_load_dwordx4 v0, s[4:7], s74 offen lds
	s_mov_b32 m0, s49
	s_nop 0
	buffer_load_dwordx4 v135, s[4:7], s74 offen lds
	s_waitcnt vmcnt(8)
	s_waitcnt lgkmcnt(0)
	s_setprio 1
	s_barrier
	v_mfma_f32_16x16x32_bf16 v[126:129], v[130:133], v[170:173], v[126:129]
	v_mfma_f32_16x16x32_bf16 v[122:125], v[146:149], v[170:173], v[122:125]
	v_mfma_f32_16x16x32_bf16 v[106:109], v[146:149], v[178:181], v[106:109]
	v_mfma_f32_16x16x32_bf16 v[110:113], v[130:133], v[178:181], v[110:113]
	v_mfma_f32_16x16x32_bf16 v[94:97], v[130:133], v[186:189], v[94:97]
	v_mfma_f32_16x16x32_bf16 v[90:93], v[146:149], v[186:189], v[90:93]
	v_mfma_f32_16x16x32_bf16 v[74:77], v[146:149], v[200:203], v[74:77]
	v_mfma_f32_16x16x32_bf16 v[78:81], v[130:133], v[200:203], v[78:81]
	v_mfma_f32_16x16x32_bf16 v[126:129], v[142:145], v[174:177], v[126:129]
	v_mfma_f32_16x16x32_bf16 v[122:125], v[150:153], v[174:177], v[122:125]
	v_mfma_f32_16x16x32_bf16 v[106:109], v[150:153], v[182:185], v[106:109]
	v_mfma_f32_16x16x32_bf16 v[110:113], v[142:145], v[182:185], v[110:113]
	v_mfma_f32_16x16x32_bf16 v[94:97], v[142:145], v[190:193], v[94:97]
	v_mfma_f32_16x16x32_bf16 v[90:93], v[150:153], v[190:193], v[90:93]
	v_mfma_f32_16x16x32_bf16 v[74:77], v[150:153], v[206:209], v[74:77]
	v_mfma_f32_16x16x32_bf16 v[78:81], v[142:145], v[206:209], v[78:81]
	v_mfma_f32_16x16x32_bf16 v[118:121], v[154:157], v[170:173], v[118:121]
	v_mfma_f32_16x16x32_bf16 v[114:117], v[162:165], v[170:173], v[114:117]
	v_mfma_f32_16x16x32_bf16 v[98:101], v[162:165], v[178:181], v[98:101]
	v_mfma_f32_16x16x32_bf16 v[102:105], v[154:157], v[178:181], v[102:105]
	v_mfma_f32_16x16x32_bf16 v[86:89], v[154:157], v[186:189], v[86:89]
	v_mfma_f32_16x16x32_bf16 v[82:85], v[162:165], v[186:189], v[82:85]
	v_mfma_f32_16x16x32_bf16 v[66:69], v[162:165], v[200:203], v[66:69]
	v_mfma_f32_16x16x32_bf16 v[70:73], v[154:157], v[200:203], v[70:73]
	v_mfma_f32_16x16x32_bf16 v[118:121], v[158:161], v[174:177], v[118:121]
	v_mfma_f32_16x16x32_bf16 v[114:117], v[166:169], v[174:177], v[114:117]
	v_mfma_f32_16x16x32_bf16 v[98:101], v[166:169], v[182:185], v[98:101]
	v_mfma_f32_16x16x32_bf16 v[102:105], v[158:161], v[182:185], v[102:105]
	v_mfma_f32_16x16x32_bf16 v[86:89], v[158:161], v[190:193], v[86:89]
	v_mfma_f32_16x16x32_bf16 v[82:85], v[166:169], v[190:193], v[82:85]
	v_mfma_f32_16x16x32_bf16 v[66:69], v[166:169], v[206:209], v[66:69]
	v_mfma_f32_16x16x32_bf16 v[70:73], v[158:161], v[206:209], v[70:73]
	s_barrier
; #define PG8_STAGE(bufoff, gbase, voff) do { const int so_ = (int)(unsigned)((const char*)(gbase) - base_##voff); _Pragma("unroll") for (int _i = 0; _i < 2; ++_i) \
;         __builtin_amdgcn_raw_ptr_buffer_load_lds(rs_##voff, (PG8_LAS unsigned*)(lds + (bufoff) + ldsw + _i * 8192), 16, (int)(voff)[_i], so_, 0, 0); } while (0)
; #define PG8_LDA(dst, b, h) do { _Pragma("unroll") for (int m = 0; m < 4; ++m) _Pragma("unroll") for (int k = 0; k < 2; ++k) dst[m][k] = *(const PG8_LAS bf16x8*)(lds + PG8_SA(b, h) + aoff + m * 2048 + k * 1024); } while (0)
; #define PG8_LDB(dst, b, h) do { _Pragma("unroll") for (int n = 0; n < 2; ++n) _Pragma("unroll") for (int k = 0; k < 2; ++k) dst[n][k] = *(const PG8_LAS bf16x8*)(lds + PG8_SB(b, h) + boff + n * 2048 + k * 1024); } while (0)
; #define PG8_MMA(ai, bj, At, Bt) do { __builtin_amdgcn_s_setprio(1); _Pragma("unroll") for (int m = 0; m < 4; ++m) _Pragma("unroll") for (int n = 0; n < 2; ++n) _Pragma("unroll") for (int k = 0; k < 2; ++k) \
;         acc[ai][bj][m][n] = __builtin_amdgcn_mfma_f32_16x16x32_bf16(Bt[n][k], At[m][k], acc[ai][bj][m][n], 0, 0, 0); __builtin_amdgcn_s_setprio(0); } while (0)
; template <class Epi, class Sched, bool ALIGN_EPI = false, bool SP2 = false>
; __device__ __forceinline__ void gemm_phase(PG8_LAS unsigned char* lds, const Gemm g, const Sched& S, const Epi& E, int tid_in) {
;     ...
;             PG8_LDB(B0, 0, 0); PG8_LDB(B1, 0, 1); PG8_SCHED; PG8_LDA(At, 0, 0); PG8_STAGE(PG8_SA(1, 1), a1 + hstepA, voffA);
;             PG8_WAIT_V(8); PG8_WAIT_L(0); PG8_BAR; PG8_MMA(0, 0, At, B0); PG8_MMA(0, 1, At, B1); PG8_BAR; PG8_SCHED;
;             PG8_LDA(At, 0, 1); PG8_STAGE(PG8_SB(0, 0), b2, voffB); PG8_STAGE(PG8_SB(0, 1), b2 + hstepB, voffB); PG8_STAGE(PG8_SA(0, 0), a2, voffA);
;             PG8_WAIT_V(8); PG8_WAIT_L(0); PG8_BAR; PG8_MMA(1, 0, At, B0); PG8_MMA(1, 1, At, B1); PG8_BAR; PG8_SCHED;
;             PG8_LDB(B0, 1, 0); PG8_LDB(B1, 1, 1); PG8_SCHED; PG8_LDA(At, 1, 0); PG8_STAGE(PG8_SA(0, 1), a2 + hstepA, voffA);
;             PG8_WAIT_V(8); PG8_WAIT_L(0); PG8_BAR; PG8_MMA(0, 0, At, B0); PG8_MMA(0, 1, At, B1); PG8_BAR; PG8_SCHED;
;             PG8_LDA(At, 1, 1); PG8_STAGE(PG8_SB(1, 0), b3, voffB); PG8_STAGE(PG8_SB(1, 1), b3 + hstepB, voffB); PG8_STAGE(PG8_SA(1, 0), a3, voffA);
;             PG8_WAIT_V(8); PG8_WAIT_L(0); PG8_BAR; PG8_MMA(1, 0, At, B0); PG8_MMA(1, 1, At, B1); PG8_BAR; PG8_SCHED;
	s_setprio 0
	s_mov_b32 m0, s53
	s_add_i32 s74, s16, 0x80
	ds_read_b128 v[170:173], v140 offset:49152
	ds_read_b128 v[174:177], v140 offset:50176
	ds_read_b128 v[178:181], v140 offset:51200
	ds_read_b128 v[182:185], v140 offset:52224
	ds_read_b128 v[186:189], v140 offset:53248
	ds_read_b128 v[190:193], v140 offset:54272
	ds_read_b128 v[200:203], v140 offset:55296
	ds_read_b128 v[206:209], v140 offset:56320
	buffer_load_dwordx4 v134, s[40:43], s74 offen lds
	s_mov_b32 m0, s60
	s_add_i32 s16, s16, 0x80080
	buffer_load_dwordx4 v136, s[40:43], s74 offen lds
	s_mov_b32 m0, s63
	s_addk_i32 s17, 0x80
	buffer_load_dwordx4 v134, s[40:43], s16 offen lds
	s_mov_b32 m0, s66
	s_nop 0
	buffer_load_dwordx4 v136, s[40:43], s16 offen lds
	s_mov_b32 m0, s61
	s_nop 0
	buffer_load_dwordx4 v0, s[4:7], s17 offen lds
	s_waitcnt vmcnt(7)
	s_waitcnt lgkmcnt(0)
	s_setprio 1
	s_barrier
	v_mfma_f32_16x16x32_bf16 v[62:65], v[130:133], v[170:173], v[62:65]
	v_mfma_f32_16x16x32_bf16 v[58:61], v[146:149], v[170:173], v[58:61]
	v_mfma_f32_16x16x32_bf16 v[42:45], v[146:149], v[178:181], v[42:45]
	v_mfma_f32_16x16x32_bf16 v[46:49], v[130:133], v[178:181], v[46:49]
	v_mfma_f32_16x16x32_bf16 v[30:33], v[130:133], v[186:189], v[30:33]
	v_mfma_f32_16x16x32_bf16 v[26:29], v[146:149], v[186:189], v[26:29]
	v_mfma_f32_16x16x32_bf16 v[10:13], v[146:149], v[200:203], v[10:13]
	v_mfma_f32_16x16x32_bf16 v[14:17], v[130:133], v[200:203], v[14:17]
	v_mfma_f32_16x16x32_bf16 v[62:65], v[142:145], v[174:177], v[62:65]
	v_mfma_f32_16x16x32_bf16 v[58:61], v[150:153], v[174:177], v[58:61]
	v_mfma_f32_16x16x32_bf16 v[42:45], v[150:153], v[182:185], v[42:45]
	v_mfma_f32_16x16x32_bf16 v[46:49], v[142:145], v[182:185], v[46:49]
	v_mfma_f32_16x16x32_bf16 v[30:33], v[142:145], v[190:193], v[30:33]
	v_mfma_f32_16x16x32_bf16 v[26:29], v[150:153], v[190:193], v[26:29]
	v_mfma_f32_16x16x32_bf16 v[10:13], v[150:153], v[206:209], v[10:13]
	v_mfma_f32_16x16x32_bf16 v[14:17], v[142:145], v[206:209], v[14:17]
	v_mfma_f32_16x16x32_bf16 v[54:57], v[154:157], v[170:173], v[54:57]
	v_mfma_f32_16x16x32_bf16 v[50:53], v[162:165], v[170:173], v[50:53]
	v_mfma_f32_16x16x32_bf16 v[34:37], v[162:165], v[178:181], v[34:37]
	v_mfma_f32_16x16x32_bf16 v[38:41], v[154:157], v[178:181], v[38:41]
	v_mfma_f32_16x16x32_bf16 v[22:25], v[154:157], v[186:189], v[22:25]
	v_mfma_f32_16x16x32_bf16 v[18:21], v[162:165], v[186:189], v[18:21]
	v_mfma_f32_16x16x32_bf16 v[2:5], v[162:165], v[200:203], v[2:5]
	v_mfma_f32_16x16x32_bf16 v[6:9], v[154:157], v[200:203], v[6:9]
	v_mfma_f32_16x16x32_bf16 v[54:57], v[158:161], v[174:177], v[54:57]
	v_mfma_f32_16x16x32_bf16 v[50:53], v[166:169], v[174:177], v[50:53]
	v_mfma_f32_16x16x32_bf16 v[34:37], v[166:169], v[182:185], v[34:37]
	v_mfma_f32_16x16x32_bf16 v[38:41], v[158:161], v[182:185], v[38:41]
	v_mfma_f32_16x16x32_bf16 v[22:25], v[158:161], v[190:193], v[22:25]
	v_mfma_f32_16x16x32_bf16 v[18:21], v[166:169], v[190:193], v[18:21]
	v_mfma_f32_16x16x32_bf16 v[2:5], v[166:169], v[206:209], v[2:5]
	v_mfma_f32_16x16x32_bf16 v[6:9], v[158:161], v[206:209], v[6:9]
	s_barrier
	s_setprio 0
	s_add_i32 s73, s73, 2
	s_add_u32 s19, s19, 0x100
	s_addc_u32 s21, s21, 0
	s_cmp_gt_u32 s73, 29
	s_mov_b64 s[16:17], s[38:39]
.LBB0_1514:
	v_add_u32_e32 v141, 0x10000, v139
	ds_read_b128 v[130:133], v141
	ds_read_b128 v[142:145], v141 offset:1024
	ds_read_b128 v[146:149], v141 offset:2048
	ds_read_b128 v[150:153], v141 offset:3072
	v_add_u32_e32 v141, 0x14000, v139
	ds_read_b128 v[154:157], v141
	ds_read_b128 v[158:161], v141 offset:1024
	ds_read_b128 v[162:165], v141 offset:2048
	ds_read_b128 v[166:169], v141 offset:3072
	s_add_u32 s38, s16, 0x100
	s_addc_u32 s39, s17, 0
	s_sub_i32 s16, s16, s4
	s_add_i32 s16, s16, 0x80080
	s_sub_i32 s74, s16, 0x80000
	s_cmp_eq_u32 s73, 28
	s_cselect_b32 s17, s18, s38
	s_mov_b32 m0, s67
	ds_read_b128 v[170:173], v140
	ds_read_b128 v[174:177], v140 offset:1024
	ds_read_b128 v[178:181], v140 offset:2048
	ds_read_b128 v[182:185], v140 offset:3072
	ds_read_b128 v[186:189], v140 offset:4096
	ds_read_b128 v[190:193], v140 offset:5120
	ds_read_b128 v[200:203], v140 offset:6144
	ds_read_b128 v[206:209], v140 offset:7168
	s_mov_b32 m0, s62
	s_nop 0
	buffer_load_dwordx4 v135, s[4:7], s74 offen lds
	s_mov_b32 m0, s67
	s_nop 0
	buffer_load_dwordx4 v0, s[4:7], s16 offen lds
	s_mov_b32 m0, s68
	s_nop 0
	buffer_load_dwordx4 v135, s[4:7], s16 offen lds
	s_waitcnt vmcnt(8)
	s_waitcnt lgkmcnt(0)
	s_setprio 1
	s_barrier
	v_mfma_f32_16x16x32_bf16 v[126:129], v[130:133], v[170:173], v[126:129]
	v_mfma_f32_16x16x32_bf16 v[122:125], v[146:149], v[170:173], v[122:125]
	v_mfma_f32_16x16x32_bf16 v[106:109], v[146:149], v[178:181], v[106:109]
	v_mfma_f32_16x16x32_bf16 v[110:113], v[130:133], v[178:181], v[110:113]
	v_mfma_f32_16x16x32_bf16 v[94:97], v[130:133], v[186:189], v[94:97]
	v_mfma_f32_16x16x32_bf16 v[90:93], v[146:149], v[186:189], v[90:93]
	v_mfma_f32_16x16x32_bf16 v[74:77], v[146:149], v[200:203], v[74:77]
	v_mfma_f32_16x16x32_bf16 v[78:81], v[130:133], v[200:203], v[78:81]
	v_mfma_f32_16x16x32_bf16 v[126:129], v[142:145], v[174:177], v[126:129]
	v_mfma_f32_16x16x32_bf16 v[122:125], v[150:153], v[174:177], v[122:125]
	v_mfma_f32_16x16x32_bf16 v[106:109], v[150:153], v[182:185], v[106:109]
	v_mfma_f32_16x16x32_bf16 v[110:113], v[142:145], v[182:185], v[110:113]
	v_mfma_f32_16x16x32_bf16 v[94:97], v[142:145], v[190:193], v[94:97]
	v_mfma_f32_16x16x32_bf16 v[90:93], v[150:153], v[190:193], v[90:93]
	v_mfma_f32_16x16x32_bf16 v[74:77], v[150:153], v[206:209], v[74:77]
	v_mfma_f32_16x16x32_bf16 v[78:81], v[142:145], v[206:209], v[78:81]
	v_mfma_f32_16x16x32_bf16 v[118:121], v[154:157], v[170:173], v[118:121]
	v_mfma_f32_16x16x32_bf16 v[114:117], v[162:165], v[170:173], v[114:117]
	v_mfma_f32_16x16x32_bf16 v[98:101], v[162:165], v[178:181], v[98:101]
	v_mfma_f32_16x16x32_bf16 v[102:105], v[154:157], v[178:181], v[102:105]
	v_mfma_f32_16x16x32_bf16 v[86:89], v[154:157], v[186:189], v[86:89]
	v_mfma_f32_16x16x32_bf16 v[82:85], v[162:165], v[186:189], v[82:85]
	v_mfma_f32_16x16x32_bf16 v[66:69], v[162:165], v[200:203], v[66:69]
	v_mfma_f32_16x16x32_bf16 v[70:73], v[154:157], v[200:203], v[70:73]
	v_mfma_f32_16x16x32_bf16 v[118:121], v[158:161], v[174:177], v[118:121]
	v_mfma_f32_16x16x32_bf16 v[114:117], v[166:169], v[174:177], v[114:117]
	v_mfma_f32_16x16x32_bf16 v[98:101], v[166:169], v[182:185], v[98:101]
	v_mfma_f32_16x16x32_bf16 v[102:105], v[158:161], v[182:185], v[102:105]
	v_mfma_f32_16x16x32_bf16 v[86:89], v[158:161], v[190:193], v[86:89]
	v_mfma_f32_16x16x32_bf16 v[82:85], v[166:169], v[190:193], v[82:85]
	v_mfma_f32_16x16x32_bf16 v[66:69], v[166:169], v[206:209], v[66:69]
	v_mfma_f32_16x16x32_bf16 v[70:73], v[158:161], v[206:209], v[70:73]
	s_barrier
; #define PG8_STAGE(bufoff, gbase, voff) do { const int so_ = (int)(unsigned)((const char*)(gbase) - base_##voff); _Pragma("unroll") for (int _i = 0; _i < 2; ++_i) \
;         __builtin_amdgcn_raw_ptr_buffer_load_lds(rs_##voff, (PG8_LAS unsigned*)(lds + (bufoff) + ldsw + _i * 8192), 16, (int)(voff)[_i], so_, 0, 0); } while (0)
; #define PG8_LDA(dst, b, h) do { _Pragma("unroll") for (int m = 0; m < 4; ++m) _Pragma("unroll") for (int k = 0; k < 2; ++k) dst[m][k] = *(const PG8_LAS bf16x8*)(lds + PG8_SA(b, h) + aoff + m * 2048 + k * 1024); } while (0)
; #define PG8_LDB(dst, b, h) do { _Pragma("unroll") for (int n = 0; n < 2; ++n) _Pragma("unroll") for (int k = 0; k < 2; ++k) dst[n][k] = *(const PG8_LAS bf16x8*)(lds + PG8_SB(b, h) + boff + n * 2048 + k * 1024); } while (0)
; #define PG8_MMA(ai, bj, At, Bt) do { __builtin_amdgcn_s_setprio(1); _Pragma("unroll") for (int m = 0; m < 4; ++m) _Pragma("unroll") for (int n = 0; n < 2; ++n) _Pragma("unroll") for (int k = 0; k < 2; ++k) \
;         acc[ai][bj][m][n] = __builtin_amdgcn_mfma_f32_16x16x32_bf16(Bt[n][k], At[m][k], acc[ai][bj][m][n], 0, 0, 0); __builtin_amdgcn_s_setprio(0); } while (0)
; #define PG8_WAIT_V(n) asm volatile("s_waitcnt vmcnt(" #n ")" ::: "memory")
; #define PG8_WAIT_L(n) asm volatile("s_waitcnt lgkmcnt(" #n ")" ::: "memory")
; #define PG8_BAR __builtin_amdgcn_s_barrier()
; #define PG8_SCHED __builtin_amdgcn_sched_barrier(0)
; template <class Epi, class Sched, bool ALIGN_EPI = false, bool SP2 = false>
; __device__ __forceinline__ void gemm_phase(PG8_LAS unsigned char* lds, const Gemm g, const Sched& S, const Epi& E, int tid_in) {
;     ...
;             PG8_WAIT_V(8); PG8_WAIT_L(0); PG8_BAR; PG8_MMA(0, 0, At, B0); PG8_MMA(0, 1, At, B1); PG8_BAR; PG8_SCHED;
;             PG8_LDA(At, 0, 1); PG8_STAGE(PG8_SB(0, 0), b2, voffB); PG8_STAGE(PG8_SB(0, 1), b2 + hstepB, voffB); PG8_STAGE(PG8_SA(0, 0), a2, voffA);
;             PG8_WAIT_V(8); PG8_WAIT_L(0); PG8_BAR; PG8_MMA(1, 0, At, B0); PG8_MMA(1, 1, At, B1); PG8_BAR; PG8_SCHED;
;             PG8_LDB(B0, 1, 0); PG8_LDB(B1, 1, 1); PG8_SCHED; PG8_LDA(At, 1, 0); PG8_STAGE(PG8_SA(0, 1), a2 + hstepA, voffA);
;             PG8_WAIT_V(8); PG8_WAIT_L(0); PG8_BAR; PG8_MMA(0, 0, At, B0); PG8_MMA(0, 1, At, B1); PG8_BAR; PG8_SCHED;
	s_setprio 0
	s_cselect_b32 s16, s15, s19
	s_mov_b32 m0, s35
	s_mov_b32 s42, s6
	s_mov_b32 s43, s7
	s_sub_i32 s16, s16, s40
	ds_read_b128 v[170:173], v140 offset:16384
	ds_read_b128 v[174:177], v140 offset:17408
	ds_read_b128 v[178:181], v140 offset:18432
	ds_read_b128 v[182:185], v140 offset:19456
	ds_read_b128 v[186:189], v140 offset:20480
	ds_read_b128 v[190:193], v140 offset:21504
	ds_read_b128 v[200:203], v140 offset:22528
	ds_read_b128 v[206:209], v140 offset:23552
	buffer_load_dwordx4 v134, s[40:43], s16 offen lds
	s_mov_b32 m0, s44
	s_add_i32 s74, s16, 0x80000
	buffer_load_dwordx4 v136, s[40:43], s16 offen lds
	s_mov_b32 m0, s45
	s_sub_i32 s17, s17, s4
	buffer_load_dwordx4 v134, s[40:43], s74 offen lds
	s_mov_b32 m0, s46
	s_nop 0
	buffer_load_dwordx4 v136, s[40:43], s74 offen lds
	s_mov_b32 m0, s34
	s_nop 0
	buffer_load_dwordx4 v0, s[4:7], s17 offen lds
	s_waitcnt vmcnt(7)
	s_waitcnt lgkmcnt(0)
	s_setprio 1
	s_barrier
	v_mfma_f32_16x16x32_bf16 v[62:65], v[130:133], v[170:173], v[62:65]
	v_mfma_f32_16x16x32_bf16 v[58:61], v[146:149], v[170:173], v[58:61]
	v_mfma_f32_16x16x32_bf16 v[42:45], v[146:149], v[178:181], v[42:45]
	v_mfma_f32_16x16x32_bf16 v[46:49], v[130:133], v[178:181], v[46:49]
	v_mfma_f32_16x16x32_bf16 v[30:33], v[130:133], v[186:189], v[30:33]
	v_mfma_f32_16x16x32_bf16 v[26:29], v[146:149], v[186:189], v[26:29]
	v_mfma_f32_16x16x32_bf16 v[10:13], v[146:149], v[200:203], v[10:13]
	v_mfma_f32_16x16x32_bf16 v[14:17], v[130:133], v[200:203], v[14:17]
	v_mfma_f32_16x16x32_bf16 v[62:65], v[142:145], v[174:177], v[62:65]
	v_mfma_f32_16x16x32_bf16 v[58:61], v[150:153], v[174:177], v[58:61]
	v_mfma_f32_16x16x32_bf16 v[42:45], v[150:153], v[182:185], v[42:45]
	v_mfma_f32_16x16x32_bf16 v[46:49], v[142:145], v[182:185], v[46:49]
	v_mfma_f32_16x16x32_bf16 v[30:33], v[142:145], v[190:193], v[30:33]
	v_mfma_f32_16x16x32_bf16 v[26:29], v[150:153], v[190:193], v[26:29]
	v_mfma_f32_16x16x32_bf16 v[10:13], v[150:153], v[206:209], v[10:13]
	v_mfma_f32_16x16x32_bf16 v[14:17], v[142:145], v[206:209], v[14:17]
	v_mfma_f32_16x16x32_bf16 v[54:57], v[154:157], v[170:173], v[54:57]
	v_mfma_f32_16x16x32_bf16 v[50:53], v[162:165], v[170:173], v[50:53]
	v_mfma_f32_16x16x32_bf16 v[34:37], v[162:165], v[178:181], v[34:37]
	v_mfma_f32_16x16x32_bf16 v[38:41], v[154:157], v[178:181], v[38:41]
	v_mfma_f32_16x16x32_bf16 v[22:25], v[154:157], v[186:189], v[22:25]
	v_mfma_f32_16x16x32_bf16 v[18:21], v[162:165], v[186:189], v[18:21]
	v_mfma_f32_16x16x32_bf16 v[2:5], v[162:165], v[200:203], v[2:5]
	v_mfma_f32_16x16x32_bf16 v[6:9], v[154:157], v[200:203], v[6:9]
	v_mfma_f32_16x16x32_bf16 v[54:57], v[158:161], v[174:177], v[54:57]
	v_mfma_f32_16x16x32_bf16 v[50:53], v[166:169], v[174:177], v[50:53]
	v_mfma_f32_16x16x32_bf16 v[34:37], v[166:169], v[182:185], v[34:37]
	v_mfma_f32_16x16x32_bf16 v[38:41], v[158:161], v[182:185], v[38:41]
	v_mfma_f32_16x16x32_bf16 v[22:25], v[158:161], v[190:193], v[22:25]
	v_mfma_f32_16x16x32_bf16 v[18:21], v[166:169], v[190:193], v[18:21]
	v_mfma_f32_16x16x32_bf16 v[2:5], v[166:169], v[206:209], v[2:5]
	v_mfma_f32_16x16x32_bf16 v[6:9], v[158:161], v[206:209], v[6:9]
	s_barrier
	s_setprio 0
	v_add_u32_e32 v141, 0x18000, v139
	ds_read_b128 v[130:133], v141
	ds_read_b128 v[142:145], v141 offset:1024
	ds_read_b128 v[146:149], v141 offset:2048
	ds_read_b128 v[150:153], v141 offset:3072
	v_add_u32_e32 v141, 0x1c000, v139
	ds_read_b128 v[154:157], v141
	ds_read_b128 v[158:161], v141 offset:1024
	ds_read_b128 v[162:165], v141 offset:2048
	ds_read_b128 v[166:169], v141 offset:3072
	s_add_i32 s74, s17, 0x80000
	s_mov_b32 m0, s48
	ds_read_b128 v[170:173], v140 offset:32768
	ds_read_b128 v[174:177], v140 offset:33792
	ds_read_b128 v[178:181], v140 offset:34816
	ds_read_b128 v[182:185], v140 offset:35840
	ds_read_b128 v[186:189], v140 offset:36864
	ds_read_b128 v[190:193], v140 offset:37888
	ds_read_b128 v[200:203], v140 offset:38912
	ds_read_b128 v[206:209], v140 offset:39936
	s_mov_b32 m0, s47
	s_nop 0
	buffer_load_dwordx4 v135, s[4:7], s17 offen lds
	s_mov_b32 m0, s48
	s_nop 0
	buffer_load_dwordx4 v0, s[4:7], s74 offen lds
	s_mov_b32 m0, s49
	s_nop 0
	buffer_load_dwordx4 v135, s[4:7], s74 offen lds
	s_waitcnt vmcnt(8)
	s_waitcnt lgkmcnt(0)
	s_setprio 1
	s_barrier
; #define PG8_STAGE(bufoff, gbase, voff) do { const int so_ = (int)(unsigned)((const char*)(gbase) - base_##voff); _Pragma("unroll") for (int _i = 0; _i < 2; ++_i) \
;         __builtin_amdgcn_raw_ptr_buffer_load_lds(rs_##voff, (PG8_LAS unsigned*)(lds + (bufoff) + ldsw + _i * 8192), 16, (int)(voff)[_i], so_, 0, 0); } while (0)
; #define PG8_WAIT_V(n) asm volatile("s_waitcnt vmcnt(" #n ")" ::: "memory")
; template <class Epi, class Sched, bool ALIGN_EPI = false, bool SP2 = false>
; __device__ __forceinline__ void gemm_phase(PG8_LAS unsigned char* lds, const Gemm g, const Sched& S, const Epi& E, int tid_in) {
;     ...
;             PG8_WAIT_V(8); PG8_WAIT_L(0); PG8_BAR; PG8_MMA(0, 0, At, B0); PG8_MMA(0, 1, At, B1); PG8_BAR; PG8_SCHED;
;             PG8_LDA(At, 1, 1); PG8_STAGE(PG8_SB(1, 0), b3, voffB); PG8_STAGE(PG8_SB(1, 1), b3 + hstepB, voffB); PG8_STAGE(PG8_SA(1, 0), a3, voffA);
;             PG8_WAIT_V(8); PG8_WAIT_L(0); PG8_BAR; PG8_MMA(1, 0, At, B0); PG8_MMA(1, 1, At, B1); PG8_BAR; PG8_SCHED;
;             } else {
;             PG8_LDB(B0, 0, 0); PG8_SCHED; PG8_LDA(At, 0, 0); PG8_STAGE(PG8_SA(1, 1), a1 + hstepA, voffA);
;             PG8_WAIT_L(8); PG8_BAR; PG8_WAIT_L(0); PG8_MMA(0, 0, At, B0); PG8_BAR; PG8_SCHED;
;             PG8_LDB(B1, 0, 1); PG8_STAGE(PG8_SB(0, 0), b2, voffB);
;             PG8_BAR; PG8_WAIT_L(0); PG8_MMA(0, 1, At, B1); PG8_BAR;
;             PG8_LDA(At, 0, 1); PG8_STAGE(PG8_SA(0, 0), a2, voffA);
;             PG8_BAR; PG8_WAIT_L(0); PG8_MMA(1, 0, At, B0); PG8_BAR; PG8_SCHED;
;             PG8_STAGE(PG8_SB(0, 1), b2 + hstepB, voffB);
;             PG8_WAIT_V(6); PG8_BAR; PG8_MMA(1, 1, At, B1); PG8_BAR;
;             PG8_LDB(B0, 1, 0); PG8_SCHED; PG8_LDA(At, 1, 0); PG8_STAGE(PG8_SA(0, 1), a2 + hstepA, voffA);
;             PG8_WAIT_L(8); PG8_BAR; PG8_WAIT_L(0); PG8_MMA(0, 0, At, B0); PG8_BAR; PG8_SCHED;
;             PG8_LDB(B1, 1, 1); PG8_STAGE(PG8_SB(1, 0), b3, voffB);
;             PG8_BAR; PG8_WAIT_L(0); PG8_MMA(0, 1, At, B1); PG8_BAR;
;             PG8_LDA(At, 1, 1); PG8_STAGE(PG8_SA(1, 0), a3, voffA);
;             PG8_BAR; PG8_WAIT_L(0); PG8_MMA(1, 0, At, B0); PG8_BAR; PG8_SCHED;
;             PG8_STAGE(PG8_SB(1, 1), b3 + hstepB, voffB);
;             PG8_WAIT_V(6); PG8_BAR; PG8_MMA(1, 1, At, B1); PG8_BAR;
;             }
;         }
;         if constexpr (ALIGN_EPI) { if (wr == 0) PG8_BAR; }
	v_mfma_f32_16x16x32_bf16 v[126:129], v[130:133], v[170:173], v[126:129]
	v_mfma_f32_16x16x32_bf16 v[122:125], v[146:149], v[170:173], v[122:125]
	v_mfma_f32_16x16x32_bf16 v[106:109], v[146:149], v[178:181], v[106:109]
	v_mfma_f32_16x16x32_bf16 v[110:113], v[130:133], v[178:181], v[110:113]
	v_mfma_f32_16x16x32_bf16 v[94:97], v[130:133], v[186:189], v[94:97]
	v_mfma_f32_16x16x32_bf16 v[90:93], v[146:149], v[186:189], v[90:93]
	v_mfma_f32_16x16x32_bf16 v[74:77], v[146:149], v[200:203], v[74:77]
	v_mfma_f32_16x16x32_bf16 v[78:81], v[130:133], v[200:203], v[78:81]
	v_mfma_f32_16x16x32_bf16 v[126:129], v[142:145], v[174:177], v[126:129]
	v_mfma_f32_16x16x32_bf16 v[122:125], v[150:153], v[174:177], v[122:125]
	v_mfma_f32_16x16x32_bf16 v[106:109], v[150:153], v[182:185], v[106:109]
	v_mfma_f32_16x16x32_bf16 v[110:113], v[142:145], v[182:185], v[110:113]
	v_mfma_f32_16x16x32_bf16 v[94:97], v[142:145], v[190:193], v[94:97]
	v_mfma_f32_16x16x32_bf16 v[90:93], v[150:153], v[190:193], v[90:93]
	v_mfma_f32_16x16x32_bf16 v[74:77], v[150:153], v[206:209], v[74:77]
	v_mfma_f32_16x16x32_bf16 v[78:81], v[142:145], v[206:209], v[78:81]
	v_mfma_f32_16x16x32_bf16 v[118:121], v[154:157], v[170:173], v[118:121]
	v_mfma_f32_16x16x32_bf16 v[114:117], v[162:165], v[170:173], v[114:117]
	v_mfma_f32_16x16x32_bf16 v[98:101], v[162:165], v[178:181], v[98:101]
	v_mfma_f32_16x16x32_bf16 v[102:105], v[154:157], v[178:181], v[102:105]
	v_mfma_f32_16x16x32_bf16 v[86:89], v[154:157], v[186:189], v[86:89]
	v_mfma_f32_16x16x32_bf16 v[82:85], v[162:165], v[186:189], v[82:85]
	v_mfma_f32_16x16x32_bf16 v[66:69], v[162:165], v[200:203], v[66:69]
	v_mfma_f32_16x16x32_bf16 v[70:73], v[154:157], v[200:203], v[70:73]
	v_mfma_f32_16x16x32_bf16 v[118:121], v[158:161], v[174:177], v[118:121]
	v_mfma_f32_16x16x32_bf16 v[114:117], v[166:169], v[174:177], v[114:117]
	v_mfma_f32_16x16x32_bf16 v[98:101], v[166:169], v[182:185], v[98:101]
	v_mfma_f32_16x16x32_bf16 v[102:105], v[158:161], v[182:185], v[102:105]
	v_mfma_f32_16x16x32_bf16 v[86:89], v[158:161], v[190:193], v[86:89]
	v_mfma_f32_16x16x32_bf16 v[82:85], v[166:169], v[190:193], v[82:85]
	v_mfma_f32_16x16x32_bf16 v[66:69], v[166:169], v[206:209], v[66:69]
	v_mfma_f32_16x16x32_bf16 v[70:73], v[158:161], v[206:209], v[70:73]
	s_barrier
	s_setprio 0
	s_mov_b32 m0, s53
	s_add_i32 s74, s16, 0x80
	ds_read_b128 v[170:173], v140 offset:49152
	ds_read_b128 v[174:177], v140 offset:50176
	ds_read_b128 v[178:181], v140 offset:51200
	ds_read_b128 v[182:185], v140 offset:52224
	ds_read_b128 v[186:189], v140 offset:53248
	ds_read_b128 v[190:193], v140 offset:54272
	ds_read_b128 v[200:203], v140 offset:55296
	ds_read_b128 v[206:209], v140 offset:56320
	buffer_load_dwordx4 v134, s[40:43], s74 offen lds
	s_mov_b32 m0, s60
	s_add_i32 s16, s16, 0x80080
	buffer_load_dwordx4 v136, s[40:43], s74 offen lds
	s_mov_b32 m0, s63
	s_addk_i32 s17, 0x80
	buffer_load_dwordx4 v134, s[40:43], s16 offen lds
	s_mov_b32 m0, s66
	s_nop 0
	buffer_load_dwordx4 v136, s[40:43], s16 offen lds
	s_mov_b32 m0, s61
	s_nop 0
	buffer_load_dwordx4 v0, s[4:7], s17 offen lds
	s_waitcnt vmcnt(7)
	s_waitcnt lgkmcnt(0)
	s_setprio 1
	s_barrier
	v_mfma_f32_16x16x32_bf16 v[62:65], v[130:133], v[170:173], v[62:65]
	v_mfma_f32_16x16x32_bf16 v[58:61], v[146:149], v[170:173], v[58:61]
	v_mfma_f32_16x16x32_bf16 v[42:45], v[146:149], v[178:181], v[42:45]
	v_mfma_f32_16x16x32_bf16 v[46:49], v[130:133], v[178:181], v[46:49]
	v_mfma_f32_16x16x32_bf16 v[30:33], v[130:133], v[186:189], v[30:33]
	v_mfma_f32_16x16x32_bf16 v[26:29], v[146:149], v[186:189], v[26:29]
	v_mfma_f32_16x16x32_bf16 v[10:13], v[146:149], v[200:203], v[10:13]
	v_mfma_f32_16x16x32_bf16 v[14:17], v[130:133], v[200:203], v[14:17]
	v_mfma_f32_16x16x32_bf16 v[62:65], v[142:145], v[174:177], v[62:65]
	v_mfma_f32_16x16x32_bf16 v[58:61], v[150:153], v[174:177], v[58:61]
	v_mfma_f32_16x16x32_bf16 v[42:45], v[150:153], v[182:185], v[42:45]
	v_mfma_f32_16x16x32_bf16 v[46:49], v[142:145], v[182:185], v[46:49]
	v_mfma_f32_16x16x32_bf16 v[30:33], v[142:145], v[190:193], v[30:33]
	v_mfma_f32_16x16x32_bf16 v[26:29], v[150:153], v[190:193], v[26:29]
	v_mfma_f32_16x16x32_bf16 v[10:13], v[150:153], v[206:209], v[10:13]
	v_mfma_f32_16x16x32_bf16 v[14:17], v[142:145], v[206:209], v[14:17]
	v_mfma_f32_16x16x32_bf16 v[54:57], v[154:157], v[170:173], v[54:57]
	v_mfma_f32_16x16x32_bf16 v[50:53], v[162:165], v[170:173], v[50:53]
	v_mfma_f32_16x16x32_bf16 v[34:37], v[162:165], v[178:181], v[34:37]
	v_mfma_f32_16x16x32_bf16 v[38:41], v[154:157], v[178:181], v[38:41]
	v_mfma_f32_16x16x32_bf16 v[22:25], v[154:157], v[186:189], v[22:25]
	v_mfma_f32_16x16x32_bf16 v[18:21], v[162:165], v[186:189], v[18:21]
	v_mfma_f32_16x16x32_bf16 v[2:5], v[162:165], v[200:203], v[2:5]
	v_mfma_f32_16x16x32_bf16 v[6:9], v[154:157], v[200:203], v[6:9]
	v_mfma_f32_16x16x32_bf16 v[54:57], v[158:161], v[174:177], v[54:57]
	v_mfma_f32_16x16x32_bf16 v[50:53], v[166:169], v[174:177], v[50:53]
	v_mfma_f32_16x16x32_bf16 v[34:37], v[166:169], v[182:185], v[34:37]
	v_mfma_f32_16x16x32_bf16 v[38:41], v[158:161], v[182:185], v[38:41]
	v_mfma_f32_16x16x32_bf16 v[22:25], v[158:161], v[190:193], v[22:25]
	v_mfma_f32_16x16x32_bf16 v[18:21], v[166:169], v[190:193], v[18:21]
	v_mfma_f32_16x16x32_bf16 v[2:5], v[166:169], v[206:209], v[2:5]
	v_mfma_f32_16x16x32_bf16 v[6:9], v[158:161], v[206:209], v[6:9]
	s_barrier
	s_setprio 0
	s_add_i32 s73, s73, 2
	s_add_u32 s19, s19, 0x100
	s_addc_u32 s21, s21, 0
	s_cmp_gt_u32 s73, 29
	s_mov_b64 s[16:17], s[38:39]
	s_cbranch_scc0 .LBB0_1514
	s_and_b64 vcc, exec, s[12:13]
	s_cbranch_vccz .LBB0_1517
	s_barrier

; #define PG8_STAGE(bufoff, gbase, voff) do { const int so_ = (int)(unsigned)((const char*)(gbase) - base_##voff); _Pragma("unroll") for (int _i = 0; _i < 2; ++_i) \
;         __builtin_amdgcn_raw_ptr_buffer_load_lds(rs_##voff, (PG8_LAS unsigned*)(lds + (bufoff) + ldsw + _i * 8192), 16, (int)(voff)[_i], so_, 0, 0); } while (0)
; #define PG8_LDA(dst, b, h) do { _Pragma("unroll") for (int m = 0; m < 4; ++m) _Pragma("unroll") for (int k = 0; k < 2; ++k) dst[m][k] = *(const PG8_LAS bf16x8*)(lds + PG8_SA(b, h) + aoff + m * 2048 + k * 1024); } while (0)
; #define PG8_LDB(dst, b, h) do { _Pragma("unroll") for (int n = 0; n < 2; ++n) _Pragma("unroll") for (int k = 0; k < 2; ++k) dst[n][k] = *(const PG8_LAS bf16x8*)(lds + PG8_SB(b, h) + boff + n * 2048 + k * 1024); } while (0)
; #define PG8_MMA(ai, bj, At, Bt) do { __builtin_amdgcn_s_setprio(1); _Pragma("unroll") for (int m = 0; m < 4; ++m) _Pragma("unroll") for (int n = 0; n < 2; ++n) _Pragma("unroll") for (int k = 0; k < 2; ++k) \
;         acc[ai][bj][m][n] = __builtin_amdgcn_mfma_f32_16x16x32_bf16(Bt[n][k], At[m][k], acc[ai][bj][m][n], 0, 0, 0); __builtin_amdgcn_s_setprio(0); } while (0)
; #define PG8_WAIT_V(n) asm volatile("s_waitcnt vmcnt(" #n ")" ::: "memory")
; #define PG8_WAIT_L(n) asm volatile("s_waitcnt lgkmcnt(" #n ")" ::: "memory")
; #define PG8_BAR __builtin_amdgcn_s_barrier()
; #define PG8_SCHED __builtin_amdgcn_sched_barrier(0)
; template <class Epi, class Sched, bool ALIGN_EPI = false, bool SP2 = false>
; __device__ __forceinline__ void gemm_phase(PG8_LAS unsigned char* lds, const Gemm g, const Sched& S, const Epi& E, int tid_in) {
;     ...
;             PG8_LDB(B0, 0, 0); PG8_LDB(B1, 0, 1); PG8_SCHED; PG8_LDA(At, 0, 0); PG8_STAGE(PG8_SA(1, 1), a1 + hstepA, voffA);
;             PG8_WAIT_V(8); PG8_WAIT_L(0); PG8_BAR; PG8_MMA(0, 0, At, B0); PG8_MMA(0, 1, At, B1); PG8_BAR; PG8_SCHED;
;             PG8_LDA(At, 0, 1); PG8_STAGE(PG8_SB(0, 0), b2, voffB); PG8_STAGE(PG8_SB(0, 1), b2 + hstepB, voffB); PG8_STAGE(PG8_SA(0, 0), a2, voffA);
;             PG8_WAIT_V(8); PG8_WAIT_L(0); PG8_BAR; PG8_MMA(1, 0, At, B0); PG8_MMA(1, 1, At, B1); PG8_BAR; PG8_SCHED;
.LBB0_1584:
	v_add_u32_e32 v133, 0x10000, v131
	ds_read_b128 v[134:137], v133
	ds_read_b128 v[138:141], v133 offset:1024
	ds_read_b128 v[142:145], v133 offset:2048
	ds_read_b128 v[146:149], v133 offset:3072
	v_add_u32_e32 v133, 0x14000, v131
	ds_read_b128 v[150:153], v133
	ds_read_b128 v[154:157], v133 offset:1024
	ds_read_b128 v[158:161], v133 offset:2048
	ds_read_b128 v[166:169], v133 offset:3072
	s_add_i32 s43, s38, s22
	s_add_i32 s42, s14, s22
	s_add_i32 s76, s12, s22
	s_addk_i32 s43, 0xff80
	s_sub_i32 s78, s43, 0x160000
	s_cmpk_eq_i32 s39, 0x54
	s_cselect_b32 s77, s16, s42
	s_mov_b32 m0, s68
	ds_read_b128 v[170:173], v132
	ds_read_b128 v[174:177], v132 offset:1024
	ds_read_b128 v[178:181], v132 offset:2048
	ds_read_b128 v[182:185], v132 offset:3072
	ds_read_b128 v[186:189], v132 offset:4096
	ds_read_b128 v[190:193], v132 offset:5120
	ds_read_b128 v[200:203], v132 offset:6144
	ds_read_b128 v[206:209], v132 offset:7168
	s_mov_b32 m0, s63
	s_nop 0
	buffer_load_dwordx4 v130, s[4:7], s78 offen lds
	s_mov_b32 m0, s68
	s_nop 0
	buffer_load_dwordx4 v0, s[4:7], s43 offen lds
	s_mov_b32 m0, s69
	s_nop 0
	buffer_load_dwordx4 v130, s[4:7], s43 offen lds
	s_waitcnt vmcnt(8)
	s_waitcnt lgkmcnt(0)
	s_setprio 1
	s_barrier
	v_mfma_f32_16x16x32_bf16 v[22:25], v[134:137], v[170:173], v[22:25]
	v_mfma_f32_16x16x32_bf16 v[14:17], v[142:145], v[170:173], v[14:17]
	v_mfma_f32_16x16x32_bf16 v[54:57], v[142:145], v[178:181], v[54:57]
	v_mfma_f32_16x16x32_bf16 v[74:77], v[134:137], v[178:181], v[74:77]
	v_mfma_f32_16x16x32_bf16 v[106:109], v[134:137], v[186:189], v[106:109]
	v_mfma_f32_16x16x32_bf16 v[102:105], v[142:145], v[186:189], v[102:105]
	v_mfma_f32_16x16x32_bf16 v[118:121], v[142:145], v[200:203], v[118:121]
	v_mfma_f32_16x16x32_bf16 v[122:125], v[134:137], v[200:203], v[122:125]
	v_mfma_f32_16x16x32_bf16 v[22:25], v[138:141], v[174:177], v[22:25]
	v_mfma_f32_16x16x32_bf16 v[14:17], v[146:149], v[174:177], v[14:17]
	v_mfma_f32_16x16x32_bf16 v[54:57], v[146:149], v[182:185], v[54:57]
	v_mfma_f32_16x16x32_bf16 v[74:77], v[138:141], v[182:185], v[74:77]
	v_mfma_f32_16x16x32_bf16 v[106:109], v[138:141], v[190:193], v[106:109]
	v_mfma_f32_16x16x32_bf16 v[102:105], v[146:149], v[190:193], v[102:105]
	v_mfma_f32_16x16x32_bf16 v[118:121], v[146:149], v[206:209], v[118:121]
	v_mfma_f32_16x16x32_bf16 v[122:125], v[138:141], v[206:209], v[122:125]
	v_mfma_f32_16x16x32_bf16 v[6:9], v[150:153], v[170:173], v[6:9]
	v_mfma_f32_16x16x32_bf16 v[18:21], v[158:161], v[170:173], v[18:21]
	v_mfma_f32_16x16x32_bf16 v[78:81], v[158:161], v[178:181], v[78:81]
	v_mfma_f32_16x16x32_bf16 v[50:53], v[150:153], v[178:181], v[50:53]
	v_mfma_f32_16x16x32_bf16 v[98:101], v[150:153], v[186:189], v[98:101]
	v_mfma_f32_16x16x32_bf16 v[110:113], v[158:161], v[186:189], v[110:113]
	v_mfma_f32_16x16x32_bf16 v[126:129], v[158:161], v[200:203], v[126:129]
	v_mfma_f32_16x16x32_bf16 v[114:117], v[150:153], v[200:203], v[114:117]
	v_mfma_f32_16x16x32_bf16 v[6:9], v[154:157], v[174:177], v[6:9]
	v_mfma_f32_16x16x32_bf16 v[18:21], v[166:169], v[174:177], v[18:21]
	v_mfma_f32_16x16x32_bf16 v[78:81], v[166:169], v[182:185], v[78:81]
	v_mfma_f32_16x16x32_bf16 v[50:53], v[154:157], v[182:185], v[50:53]
	v_mfma_f32_16x16x32_bf16 v[98:101], v[154:157], v[190:193], v[98:101]
	v_mfma_f32_16x16x32_bf16 v[110:113], v[166:169], v[190:193], v[110:113]
	v_mfma_f32_16x16x32_bf16 v[126:129], v[166:169], v[206:209], v[126:129]
	v_mfma_f32_16x16x32_bf16 v[114:117], v[154:157], v[206:209], v[114:117]
	s_barrier
	s_setprio 0
	s_cselect_b32 s76, s20, s76
	s_mov_b32 m0, s26
	s_mov_b32 s42, s6
	s_mov_b32 s43, s7
	s_sub_i32 s76, s76, s40
	ds_read_b128 v[170:173], v132 offset:16384
	ds_read_b128 v[174:177], v132 offset:17408
	ds_read_b128 v[178:181], v132 offset:18432
	ds_read_b128 v[182:185], v132 offset:19456
	ds_read_b128 v[186:189], v132 offset:20480
	ds_read_b128 v[190:193], v132 offset:21504
	ds_read_b128 v[200:203], v132 offset:22528
	ds_read_b128 v[206:209], v132 offset:23552
	buffer_load_dwordx4 v0, s[40:43], s76 offen lds
	s_mov_b32 m0, s44
	s_add_i32 s78, s76, 0x160000
	buffer_load_dwordx4 v130, s[40:43], s76 offen lds
	s_mov_b32 m0, s45
	s_sub_i32 s77, s77, s4
	buffer_load_dwordx4 v0, s[40:43], s78 offen lds
	s_mov_b32 m0, s46
	s_nop 0
	buffer_load_dwordx4 v130, s[40:43], s78 offen lds
	s_mov_b32 m0, s19
	s_nop 0
	buffer_load_dwordx4 v0, s[4:7], s77 offen lds
	s_waitcnt vmcnt(7)
	s_waitcnt lgkmcnt(0)
	s_setprio 1
	s_barrier
	v_mfma_f32_16x16x32_bf16 v[62:65], v[134:137], v[170:173], v[62:65]
	v_mfma_f32_16x16x32_bf16 v[46:49], v[142:145], v[170:173], v[46:49]
	v_mfma_f32_16x16x32_bf16 v[70:73], v[142:145], v[178:181], v[70:73]
	v_mfma_f32_16x16x32_bf16 v[82:85], v[134:137], v[178:181], v[82:85]
	v_mfma_f32_16x16x32_bf16 v[94:97], v[134:137], v[186:189], v[94:97]
	v_mfma_f32_16x16x32_bf16 v[90:93], v[142:145], v[186:189], v[90:93]
	v_mfma_f32_16x16x32_bf16 v[26:29], v[142:145], v[200:203], v[26:29]
	v_mfma_f32_16x16x32_bf16 v[38:41], v[134:137], v[200:203], v[38:41]
	v_mfma_f32_16x16x32_bf16 v[62:65], v[138:141], v[174:177], v[62:65]
	v_mfma_f32_16x16x32_bf16 v[46:49], v[146:149], v[174:177], v[46:49]
	v_mfma_f32_16x16x32_bf16 v[70:73], v[146:149], v[182:185], v[70:73]
	v_mfma_f32_16x16x32_bf16 v[82:85], v[138:141], v[182:185], v[82:85]
	v_mfma_f32_16x16x32_bf16 v[94:97], v[138:141], v[190:193], v[94:97]
	v_mfma_f32_16x16x32_bf16 v[90:93], v[146:149], v[190:193], v[90:93]
	v_mfma_f32_16x16x32_bf16 v[26:29], v[146:149], v[206:209], v[26:29]
	v_mfma_f32_16x16x32_bf16 v[38:41], v[138:141], v[206:209], v[38:41]
	v_mfma_f32_16x16x32_bf16 v[42:45], v[150:153], v[170:173], v[42:45]
	v_mfma_f32_16x16x32_bf16 v[30:33], v[158:161], v[170:173], v[30:33]
	v_mfma_f32_16x16x32_bf16 v[86:89], v[158:161], v[178:181], v[86:89]
	v_mfma_f32_16x16x32_bf16 v[66:69], v[150:153], v[178:181], v[66:69]
	v_mfma_f32_16x16x32_bf16 v[58:61], v[150:153], v[186:189], v[58:61]
	v_mfma_f32_16x16x32_bf16 v[34:37], v[158:161], v[186:189], v[34:37]
	v_mfma_f32_16x16x32_bf16 v[2:5], v[158:161], v[200:203], v[2:5]
	v_mfma_f32_16x16x32_bf16 v[10:13], v[150:153], v[200:203], v[10:13]
	v_mfma_f32_16x16x32_bf16 v[42:45], v[154:157], v[174:177], v[42:45]
	v_mfma_f32_16x16x32_bf16 v[30:33], v[166:169], v[174:177], v[30:33]
	v_mfma_f32_16x16x32_bf16 v[86:89], v[166:169], v[182:185], v[86:89]
	v_mfma_f32_16x16x32_bf16 v[66:69], v[154:157], v[182:185], v[66:69]
	v_mfma_f32_16x16x32_bf16 v[58:61], v[154:157], v[190:193], v[58:61]
	v_mfma_f32_16x16x32_bf16 v[34:37], v[166:169], v[190:193], v[34:37]
	v_mfma_f32_16x16x32_bf16 v[2:5], v[166:169], v[206:209], v[2:5]
	v_mfma_f32_16x16x32_bf16 v[10:13], v[154:157], v[206:209], v[10:13]
	s_barrier
; #define PG8_STAGE(bufoff, gbase, voff) do { const int so_ = (int)(unsigned)((const char*)(gbase) - base_##voff); _Pragma("unroll") for (int _i = 0; _i < 2; ++_i) \
;         __builtin_amdgcn_raw_ptr_buffer_load_lds(rs_##voff, (PG8_LAS unsigned*)(lds + (bufoff) + ldsw + _i * 8192), 16, (int)(voff)[_i], so_, 0, 0); } while (0)
; #define PG8_LDA(dst, b, h) do { _Pragma("unroll") for (int m = 0; m < 4; ++m) _Pragma("unroll") for (int k = 0; k < 2; ++k) dst[m][k] = *(const PG8_LAS bf16x8*)(lds + PG8_SA(b, h) + aoff + m * 2048 + k * 1024); } while (0)
; #define PG8_LDB(dst, b, h) do { _Pragma("unroll") for (int n = 0; n < 2; ++n) _Pragma("unroll") for (int k = 0; k < 2; ++k) dst[n][k] = *(const PG8_LAS bf16x8*)(lds + PG8_SB(b, h) + boff + n * 2048 + k * 1024); } while (0)
; #define PG8_MMA(ai, bj, At, Bt) do { __builtin_amdgcn_s_setprio(1); _Pragma("unroll") for (int m = 0; m < 4; ++m) _Pragma("unroll") for (int n = 0; n < 2; ++n) _Pragma("unroll") for (int k = 0; k < 2; ++k) \
;         acc[ai][bj][m][n] = __builtin_amdgcn_mfma_f32_16x16x32_bf16(Bt[n][k], At[m][k], acc[ai][bj][m][n], 0, 0, 0); __builtin_amdgcn_s_setprio(0); } while (0)
; #define PG8_WAIT_V(n) asm volatile("s_waitcnt vmcnt(" #n ")" ::: "memory")
; #define PG8_WAIT_L(n) asm volatile("s_waitcnt lgkmcnt(" #n ")" ::: "memory")
; #define PG8_BAR __builtin_amdgcn_s_barrier()
; #define PG8_SCHED __builtin_amdgcn_sched_barrier(0)
; template <class Epi, class Sched, bool ALIGN_EPI = false, bool SP2 = false>
; __device__ __forceinline__ void gemm_phase(PG8_LAS unsigned char* lds, const Gemm g, const Sched& S, const Epi& E, int tid_in) {
;     ...
;             PG8_WAIT_V(8); PG8_WAIT_L(0); PG8_BAR; PG8_MMA(1, 0, At, B0); PG8_MMA(1, 1, At, B1); PG8_BAR; PG8_SCHED;
;             PG8_LDB(B0, 1, 0); PG8_LDB(B1, 1, 1); PG8_SCHED; PG8_LDA(At, 1, 0); PG8_STAGE(PG8_SA(0, 1), a2 + hstepA, voffA);
;             PG8_WAIT_V(8); PG8_WAIT_L(0); PG8_BAR; PG8_MMA(0, 0, At, B0); PG8_MMA(0, 1, At, B1); PG8_BAR; PG8_SCHED;
;             PG8_LDA(At, 1, 1); PG8_STAGE(PG8_SB(1, 0), b3, voffB); PG8_STAGE(PG8_SB(1, 1), b3 + hstepB, voffB); PG8_STAGE(PG8_SA(1, 0), a3, voffA);
	s_setprio 0
	v_add_u32_e32 v133, 0x18000, v131
	ds_read_b128 v[134:137], v133
	ds_read_b128 v[138:141], v133 offset:1024
	ds_read_b128 v[142:145], v133 offset:2048
	ds_read_b128 v[146:149], v133 offset:3072
	v_add_u32_e32 v133, 0x1c000, v131
	ds_read_b128 v[150:153], v133
	ds_read_b128 v[154:157], v133 offset:1024
	ds_read_b128 v[158:161], v133 offset:2048
	ds_read_b128 v[166:169], v133 offset:3072
	s_add_i32 s78, s77, 0x160000
	s_mov_b32 m0, s48
	ds_read_b128 v[170:173], v132 offset:32768
	ds_read_b128 v[174:177], v132 offset:33792
	ds_read_b128 v[178:181], v132 offset:34816
	ds_read_b128 v[182:185], v132 offset:35840
	ds_read_b128 v[186:189], v132 offset:36864
	ds_read_b128 v[190:193], v132 offset:37888
	ds_read_b128 v[200:203], v132 offset:38912
	ds_read_b128 v[206:209], v132 offset:39936
	s_mov_b32 m0, s47
	s_nop 0
	buffer_load_dwordx4 v130, s[4:7], s77 offen lds
	s_mov_b32 m0, s48
	s_nop 0
	buffer_load_dwordx4 v0, s[4:7], s78 offen lds
	s_mov_b32 m0, s49
	s_nop 0
	buffer_load_dwordx4 v130, s[4:7], s78 offen lds
	s_waitcnt vmcnt(8)
	s_waitcnt lgkmcnt(0)
	s_setprio 1
	s_barrier
	v_mfma_f32_16x16x32_bf16 v[22:25], v[134:137], v[170:173], v[22:25]
	v_mfma_f32_16x16x32_bf16 v[14:17], v[142:145], v[170:173], v[14:17]
	v_mfma_f32_16x16x32_bf16 v[54:57], v[142:145], v[178:181], v[54:57]
	v_mfma_f32_16x16x32_bf16 v[74:77], v[134:137], v[178:181], v[74:77]
	v_mfma_f32_16x16x32_bf16 v[106:109], v[134:137], v[186:189], v[106:109]
	v_mfma_f32_16x16x32_bf16 v[102:105], v[142:145], v[186:189], v[102:105]
	v_mfma_f32_16x16x32_bf16 v[118:121], v[142:145], v[200:203], v[118:121]
	v_mfma_f32_16x16x32_bf16 v[122:125], v[134:137], v[200:203], v[122:125]
	v_mfma_f32_16x16x32_bf16 v[22:25], v[138:141], v[174:177], v[22:25]
	v_mfma_f32_16x16x32_bf16 v[14:17], v[146:149], v[174:177], v[14:17]
	v_mfma_f32_16x16x32_bf16 v[54:57], v[146:149], v[182:185], v[54:57]
	v_mfma_f32_16x16x32_bf16 v[74:77], v[138:141], v[182:185], v[74:77]
	v_mfma_f32_16x16x32_bf16 v[106:109], v[138:141], v[190:193], v[106:109]
	v_mfma_f32_16x16x32_bf16 v[102:105], v[146:149], v[190:193], v[102:105]
	v_mfma_f32_16x16x32_bf16 v[118:121], v[146:149], v[206:209], v[118:121]
	v_mfma_f32_16x16x32_bf16 v[122:125], v[138:141], v[206:209], v[122:125]
	v_mfma_f32_16x16x32_bf16 v[6:9], v[150:153], v[170:173], v[6:9]
	v_mfma_f32_16x16x32_bf16 v[18:21], v[158:161], v[170:173], v[18:21]
	v_mfma_f32_16x16x32_bf16 v[78:81], v[158:161], v[178:181], v[78:81]
	v_mfma_f32_16x16x32_bf16 v[50:53], v[150:153], v[178:181], v[50:53]
	v_mfma_f32_16x16x32_bf16 v[98:101], v[150:153], v[186:189], v[98:101]
	v_mfma_f32_16x16x32_bf16 v[110:113], v[158:161], v[186:189], v[110:113]
	v_mfma_f32_16x16x32_bf16 v[126:129], v[158:161], v[200:203], v[126:129]
	v_mfma_f32_16x16x32_bf16 v[114:117], v[150:153], v[200:203], v[114:117]
	v_mfma_f32_16x16x32_bf16 v[6:9], v[154:157], v[174:177], v[6:9]
	v_mfma_f32_16x16x32_bf16 v[18:21], v[166:169], v[174:177], v[18:21]
	v_mfma_f32_16x16x32_bf16 v[78:81], v[166:169], v[182:185], v[78:81]
	v_mfma_f32_16x16x32_bf16 v[50:53], v[154:157], v[182:185], v[50:53]
	v_mfma_f32_16x16x32_bf16 v[98:101], v[154:157], v[190:193], v[98:101]
	v_mfma_f32_16x16x32_bf16 v[110:113], v[166:169], v[190:193], v[110:113]
	v_mfma_f32_16x16x32_bf16 v[126:129], v[166:169], v[206:209], v[126:129]
	v_mfma_f32_16x16x32_bf16 v[114:117], v[154:157], v[206:209], v[114:117]
	s_barrier
	s_setprio 0
	s_mov_b32 m0, s60
	s_add_i32 s78, s76, 0x80
	ds_read_b128 v[170:173], v132 offset:49152
	ds_read_b128 v[174:177], v132 offset:50176
	ds_read_b128 v[178:181], v132 offset:51200
	ds_read_b128 v[182:185], v132 offset:52224
	ds_read_b128 v[186:189], v132 offset:53248
	ds_read_b128 v[190:193], v132 offset:54272
	ds_read_b128 v[200:203], v132 offset:55296
	ds_read_b128 v[206:209], v132 offset:56320
	buffer_load_dwordx4 v0, s[40:43], s78 offen lds
	s_mov_b32 m0, s61
	s_add_i32 s76, s76, 0x160080
	buffer_load_dwordx4 v130, s[40:43], s78 offen lds
	s_mov_b32 m0, s66
	s_addk_i32 s77, 0x80
	buffer_load_dwordx4 v0, s[40:43], s76 offen lds
	s_mov_b32 m0, s67
	s_nop 0
	buffer_load_dwordx4 v130, s[40:43], s76 offen lds
	s_mov_b32 m0, s62
	s_nop 0
	buffer_load_dwordx4 v0, s[4:7], s77 offen lds
	s_waitcnt vmcnt(7)
	s_waitcnt lgkmcnt(0)
	s_setprio 1
	s_barrier
;     static __device__ __forceinline__ bool last_of_chain(const Unit& u) { return (u.pn >> 3) == 2; }
; template <class Epi, class Sched, bool ALIGN_EPI = false, bool SP2 = false>
; __device__ __forceinline__ void gemm_phase(PG8_LAS unsigned char* lds, const Gemm g, const Sched& S, const Epi& E, int tid_in) {
;     ...
;             PG8_WAIT_V(8); PG8_WAIT_L(0); PG8_BAR; PG8_MMA(1, 0, At, B0); PG8_MMA(1, 1, At, B1); PG8_BAR; PG8_SCHED;
;             } else {
;             PG8_LDB(B0, 0, 0); PG8_SCHED; PG8_LDA(At, 0, 0); PG8_STAGE(PG8_SA(1, 1), a1 + hstepA, voffA);
;             PG8_WAIT_L(8); PG8_BAR; PG8_WAIT_L(0); PG8_MMA(0, 0, At, B0); PG8_BAR; PG8_SCHED;
;             PG8_LDB(B1, 0, 1); PG8_STAGE(PG8_SB(0, 0), b2, voffB);
;             PG8_BAR; PG8_WAIT_L(0); PG8_MMA(0, 1, At, B1); PG8_BAR;
;             PG8_LDA(At, 0, 1); PG8_STAGE(PG8_SA(0, 0), a2, voffA);
;             PG8_BAR; PG8_WAIT_L(0); PG8_MMA(1, 0, At, B0); PG8_BAR; PG8_SCHED;
;             PG8_STAGE(PG8_SB(0, 1), b2 + hstepB, voffB);
;             PG8_WAIT_V(6); PG8_BAR; PG8_MMA(1, 1, At, B1); PG8_BAR;
;             PG8_LDB(B0, 1, 0); PG8_SCHED; PG8_LDA(At, 1, 0); PG8_STAGE(PG8_SA(0, 1), a2 + hstepA, voffA);
;             PG8_WAIT_L(8); PG8_BAR; PG8_WAIT_L(0); PG8_MMA(0, 0, At, B0); PG8_BAR; PG8_SCHED;
;             PG8_LDB(B1, 1, 1); PG8_STAGE(PG8_SB(1, 0), b3, voffB);
;             PG8_BAR; PG8_WAIT_L(0); PG8_MMA(0, 1, At, B1); PG8_BAR;
;             PG8_LDA(At, 1, 1); PG8_STAGE(PG8_SA(1, 0), a3, voffA);
;             PG8_BAR; PG8_WAIT_L(0); PG8_MMA(1, 0, At, B0); PG8_BAR; PG8_SCHED;
;             PG8_STAGE(PG8_SB(1, 1), b3 + hstepB, voffB);
;             PG8_WAIT_V(6); PG8_BAR; PG8_MMA(1, 1, At, B1); PG8_BAR;
;             }
;         }
;         if constexpr (ALIGN_EPI) { if (wr == 0) PG8_BAR; }
;         if constexpr (!Epi::AFTER_DRAIN) { E(acc, cur, wr, wc, fr, fq); S.done(cur); }
;         if (!has_next) break;
;         bool zero_acc = true; if constexpr (Epi::CHAIN) zero_acc = Epi::last_of_chain(cur);
;         if (zero_acc) {
; #pragma unroll
;         for (int a = 0; a < 2; ++a)
; #pragma unroll
;             for (int b = 0; b < 2; ++b)
; #pragma unroll
;                 for (int m = 0; m < 4; ++m)
; #pragma unroll
;                     for (int n = 0; n < 2; ++n) acc[a][b][m][n] = (f32x4){0.f, 0.f, 0.f, 0.f};
;         }
;         cur = nxt; cA = nA; cB = nB; ++ui;
	v_mfma_f32_16x16x32_bf16 v[62:65], v[134:137], v[170:173], v[62:65]
	v_mfma_f32_16x16x32_bf16 v[46:49], v[142:145], v[170:173], v[46:49]
	v_mfma_f32_16x16x32_bf16 v[70:73], v[142:145], v[178:181], v[70:73]
	v_mfma_f32_16x16x32_bf16 v[82:85], v[134:137], v[178:181], v[82:85]
	v_mfma_f32_16x16x32_bf16 v[94:97], v[134:137], v[186:189], v[94:97]
	v_mfma_f32_16x16x32_bf16 v[90:93], v[142:145], v[186:189], v[90:93]
	v_mfma_f32_16x16x32_bf16 v[26:29], v[142:145], v[200:203], v[26:29]
	v_mfma_f32_16x16x32_bf16 v[38:41], v[134:137], v[200:203], v[38:41]
	v_mfma_f32_16x16x32_bf16 v[62:65], v[138:141], v[174:177], v[62:65]
	v_mfma_f32_16x16x32_bf16 v[46:49], v[146:149], v[174:177], v[46:49]
	v_mfma_f32_16x16x32_bf16 v[70:73], v[146:149], v[182:185], v[70:73]
	v_mfma_f32_16x16x32_bf16 v[82:85], v[138:141], v[182:185], v[82:85]
	v_mfma_f32_16x16x32_bf16 v[94:97], v[138:141], v[190:193], v[94:97]
	v_mfma_f32_16x16x32_bf16 v[90:93], v[146:149], v[190:193], v[90:93]
	v_mfma_f32_16x16x32_bf16 v[26:29], v[146:149], v[206:209], v[26:29]
	v_mfma_f32_16x16x32_bf16 v[38:41], v[138:141], v[206:209], v[38:41]
	v_mfma_f32_16x16x32_bf16 v[42:45], v[150:153], v[170:173], v[42:45]
	v_mfma_f32_16x16x32_bf16 v[30:33], v[158:161], v[170:173], v[30:33]
	v_mfma_f32_16x16x32_bf16 v[86:89], v[158:161], v[178:181], v[86:89]
	v_mfma_f32_16x16x32_bf16 v[66:69], v[150:153], v[178:181], v[66:69]
	v_mfma_f32_16x16x32_bf16 v[58:61], v[150:153], v[186:189], v[58:61]
	v_mfma_f32_16x16x32_bf16 v[34:37], v[158:161], v[186:189], v[34:37]
	v_mfma_f32_16x16x32_bf16 v[2:5], v[158:161], v[200:203], v[2:5]
	v_mfma_f32_16x16x32_bf16 v[10:13], v[150:153], v[200:203], v[10:13]
	v_mfma_f32_16x16x32_bf16 v[42:45], v[154:157], v[174:177], v[42:45]
	v_mfma_f32_16x16x32_bf16 v[30:33], v[166:169], v[174:177], v[30:33]
	v_mfma_f32_16x16x32_bf16 v[86:89], v[166:169], v[182:185], v[86:89]
	v_mfma_f32_16x16x32_bf16 v[66:69], v[154:157], v[182:185], v[66:69]
	v_mfma_f32_16x16x32_bf16 v[58:61], v[154:157], v[190:193], v[58:61]
	v_mfma_f32_16x16x32_bf16 v[34:37], v[166:169], v[190:193], v[34:37]
	v_mfma_f32_16x16x32_bf16 v[2:5], v[166:169], v[206:209], v[2:5]
	v_mfma_f32_16x16x32_bf16 v[10:13], v[154:157], v[206:209], v[10:13]
	s_barrier
	s_setprio 0
	s_add_i32 s39, s39, 2
	s_add_u32 s22, s22, 0x100
	s_addc_u32 s23, s23, 0
	s_cmpk_gt_u32 s39, 0x55
	s_cbranch_scc0 .LBB0_1584
	s_and_b64 vcc, exec, s[36:37]
	s_cbranch_vccnz .LBB0_1572
	v_mov_b32_e32 v2, 0
	s_mov_b32 s10, s73
	s_mov_b32 s25, s74
	s_mov_b64 s[12:13], s[20:21]
	s_mov_b64 s[14:15], s[16:17]
	s_mov_b32 s72, s75
	v_mov_b32_e32 v3, v2
	v_mov_b32_e32 v4, v2
	v_mov_b32_e32 v5, v2
	v_mov_b32_e32 v10, v2
	v_mov_b32_e32 v11, v2
	v_mov_b32_e32 v12, v2
	v_mov_b32_e32 v13, v2
	v_mov_b32_e32 v34, v2
	v_mov_b32_e32 v35, v2
	v_mov_b32_e32 v36, v2
	v_mov_b32_e32 v37, v2
	v_mov_b32_e32 v58, v2
	v_mov_b32_e32 v59, v2
	v_mov_b32_e32 v60, v2
	v_mov_b32_e32 v61, v2
	v_mov_b32_e32 v86, v2
	v_mov_b32_e32 v87, v2
	v_mov_b32_e32 v88, v2
	v_mov_b32_e32 v89, v2
	v_mov_b32_e32 v66, v2
	v_mov_b32_e32 v67, v2
	v_mov_b32_e32 v68, v2
	v_mov_b32_e32 v69, v2
	v_mov_b32_e32 v30, v2
	v_mov_b32_e32 v31, v2
	v_mov_b32_e32 v32, v2
	v_mov_b32_e32 v33, v2
	v_mov_b32_e32 v42, v2
	v_mov_b32_e32 v43, v2
	v_mov_b32_e32 v44, v2
	v_mov_b32_e32 v45, v2
	v_mov_b32_e32 v26, v2
	v_mov_b32_e32 v27, v2
	v_mov_b32_e32 v28, v2
	v_mov_b32_e32 v29, v2
	v_mov_b32_e32 v38, v2
	v_mov_b32_e32 v39, v2
	v_mov_b32_e32 v40, v2
	v_mov_b32_e32 v41, v2
	v_mov_b32_e32 v90, v2
	v_mov_b32_e32 v91, v2
	v_mov_b32_e32 v92, v2
	v_mov_b32_e32 v93, v2
	v_mov_b32_e32 v94, v2
	v_mov_b32_e32 v95, v2
	v_mov_b32_e32 v96, v2
	v_mov_b32_e32 v97, v2
	v_mov_b32_e32 v70, v2
	v_mov_b32_e32 v71, v2
	v_mov_b32_e32 v72, v2
	v_mov_b32_e32 v73, v2
	v_mov_b32_e32 v82, v2
	v_mov_b32_e32 v83, v2
	v_mov_b32_e32 v84, v2
	v_mov_b32_e32 v85, v2
	v_mov_b32_e32 v46, v2
	v_mov_b32_e32 v47, v2
	v_mov_b32_e32 v48, v2
	v_mov_b32_e32 v49, v2
	v_mov_b32_e32 v62, v2
	v_mov_b32_e32 v63, v2
	v_mov_b32_e32 v64, v2
	v_mov_b32_e32 v65, v2
	v_mov_b32_e32 v126, v2
	v_mov_b32_e32 v127, v2
	v_mov_b32_e32 v128, v2
	v_mov_b32_e32 v129, v2
	v_mov_b32_e32 v114, v2
	v_mov_b32_e32 v115, v2
	v_mov_b32_e32 v116, v2
	v_mov_b32_e32 v117, v2
	v_mov_b32_e32 v110, v2
	v_mov_b32_e32 v111, v2
	v_mov_b32_e32 v112, v2
	v_mov_b32_e32 v113, v2
	v_mov_b32_e32 v98, v2
	v_mov_b32_e32 v99, v2
	v_mov_b32_e32 v100, v2
	v_mov_b32_e32 v101, v2
	v_mov_b32_e32 v78, v2
	v_mov_b32_e32 v79, v2
	v_mov_b32_e32 v80, v2
	v_mov_b32_e32 v81, v2
	v_mov_b32_e32 v50, v2
	v_mov_b32_e32 v51, v2
	v_mov_b32_e32 v52, v2
	v_mov_b32_e32 v53, v2
	v_mov_b32_e32 v18, v2
	v_mov_b32_e32 v19, v2
	v_mov_b32_e32 v20, v2
	v_mov_b32_e32 v21, v2
	v_mov_b32_e32 v6, v2
	v_mov_b32_e32 v7, v2
	v_mov_b32_e32 v8, v2
	v_mov_b32_e32 v9, v2
	v_mov_b32_e32 v118, v2
	v_mov_b32_e32 v119, v2
	v_mov_b32_e32 v120, v2
	v_mov_b32_e32 v121, v2
	v_mov_b32_e32 v122, v2
	v_mov_b32_e32 v123, v2
	v_mov_b32_e32 v124, v2
	v_mov_b32_e32 v125, v2
	v_mov_b32_e32 v102, v2
	v_mov_b32_e32 v103, v2
	v_mov_b32_e32 v104, v2
	v_mov_b32_e32 v105, v2
	v_mov_b32_e32 v106, v2
	v_mov_b32_e32 v107, v2
	v_mov_b32_e32 v108, v2
	v_mov_b32_e32 v109, v2
	v_mov_b32_e32 v54, v2
	v_mov_b32_e32 v55, v2
	v_mov_b32_e32 v56, v2
	v_mov_b32_e32 v57, v2
	v_mov_b32_e32 v74, v2
	v_mov_b32_e32 v75, v2
	v_mov_b32_e32 v76, v2
	v_mov_b32_e32 v77, v2
	v_mov_b32_e32 v14, v2
	v_mov_b32_e32 v15, v2
	v_mov_b32_e32 v16, v2
	v_mov_b32_e32 v17, v2
	v_mov_b32_e32 v22, v2
	v_mov_b32_e32 v23, v2
	v_mov_b32_e32 v24, v2
	v_mov_b32_e32 v25, v2
	s_branch .LBB0_1572
